# v40 + all s_setprio removed from the 8 GEMM K-loops (MFMA burst no longer starves the partner wave's address VALU)
# speedup vs baseline: 1.0311x; 1.0049x over previous
.LBB0_228:
	s_ashr_i32 s39, s38, 31
	s_lshl_b64 s[40:41], s[38:39], 19
	v_readlane_b32 s42, v238, 7
	v_readlane_b32 s43, v238, 8
	s_add_u32 s40, s42, s40
	s_addc_u32 s41, s43, s41
	s_and_b64 s[42:43], s[2:3], exec
	s_cselect_b32 s5, s41, s1
	s_cselect_b32 s7, s40, s0
	s_ashr_i32 s37, s36, 31
	s_lshl_b64 s[42:43], s[36:37], 19
	s_add_u32 s42, s64, s42
	s_addc_u32 s43, s65, s43
	s_and_b64 s[44:45], s[2:3], exec
	s_cselect_b32 s33, s43, s9
	s_cselect_b32 s37, s42, s8
	s_add_u32 s0, s0, 0x40080
	s_addc_u32 s1, s1, 0
	s_add_u32 s39, s8, 0x100
	s_addc_u32 s46, s9, 0
	s_mov_b32 s47, -2
	ds_read_b128 v[144:147], v170
	ds_read_b128 v[148:151], v170 offset:1024
	ds_read_b128 v[152:155], v170 offset:2048
	ds_read_b128 v[156:159], v170 offset:3072
	ds_read_b128 v[162:165], v171
	ds_read_b128 v[174:177], v171 offset:1024
	ds_read_b128 v[178:181], v171 offset:2048
	ds_read_b128 v[182:185], v171 offset:3072
	s_add_u32 s8, s0, 0xfffc0080
	s_addc_u32 s9, s1, -1
	s_cmp_eq_u32 s47, 12
	s_cselect_b32 s45, s5, s9
	s_cselect_b32 s44, s7, s8
	s_cselect_b32 s9, s33, s46
	s_cselect_b32 s8, s37, s39
	v_lshl_add_u64 v[218:219], s[0:1], 0, v[136:137]
	s_add_i32 m0, s67, 0xc000
	ds_read_b128 v[186:189], v172
	ds_read_b128 v[190:193], v172 offset:1024
	ds_read_b128 v[194:197], v172 offset:2048
	ds_read_b128 v[198:201], v172 offset:3072
	ds_read_b128 v[202:205], v172 offset:4096
	ds_read_b128 v[206:209], v172 offset:5120
	ds_read_b128 v[210:213], v172 offset:6144
	ds_read_b128 v[214:217], v172 offset:7168
	global_load_lds_dwordx4 v[218:219], off
	v_lshl_add_u64 v[218:219], s[0:1], 0, v[138:139]
	s_add_i32 m0, s67, 0xe000
	s_nop 0
	global_load_lds_dwordx4 v[218:219], off
	s_waitcnt vmcnt(8)
	s_waitcnt lgkmcnt(0)
	s_barrier
	s_waitcnt lgkmcnt(0)
	v_mfma_f32_16x16x32_bf16 v[124:127], v[144:147], v[186:189], 0
	v_mfma_f32_16x16x32_bf16 v[120:123], v[152:155], v[186:189], 0
	v_mfma_f32_16x16x32_bf16 v[108:111], v[144:147], v[194:197], 0
	v_mfma_f32_16x16x32_bf16 v[104:107], v[152:155], v[194:197], 0
	v_mfma_f32_16x16x32_bf16 v[92:95], v[144:147], v[202:205], 0
	v_mfma_f32_16x16x32_bf16 v[88:91], v[152:155], v[202:205], 0
	v_mfma_f32_16x16x32_bf16 v[76:79], v[144:147], v[210:213], 0
	v_mfma_f32_16x16x32_bf16 v[72:75], v[152:155], v[210:213], 0
	v_mfma_f32_16x16x32_bf16 v[124:127], v[148:151], v[190:193], v[124:127]
	v_mfma_f32_16x16x32_bf16 v[120:123], v[156:159], v[190:193], v[120:123]
	v_mfma_f32_16x16x32_bf16 v[108:111], v[148:151], v[198:201], v[108:111]
	v_mfma_f32_16x16x32_bf16 v[104:107], v[156:159], v[198:201], v[104:107]
	v_mfma_f32_16x16x32_bf16 v[92:95], v[148:151], v[206:209], v[92:95]
	v_mfma_f32_16x16x32_bf16 v[88:91], v[156:159], v[206:209], v[88:91]
	v_mfma_f32_16x16x32_bf16 v[76:79], v[148:151], v[214:217], v[76:79]
	v_mfma_f32_16x16x32_bf16 v[72:75], v[156:159], v[214:217], v[72:75]
	v_mfma_f32_16x16x32_bf16 v[116:119], v[162:165], v[186:189], 0
	v_mfma_f32_16x16x32_bf16 v[112:115], v[178:181], v[186:189], 0
	v_mfma_f32_16x16x32_bf16 v[100:103], v[162:165], v[194:197], 0
	v_mfma_f32_16x16x32_bf16 v[96:99], v[178:181], v[194:197], 0
	v_mfma_f32_16x16x32_bf16 v[84:87], v[162:165], v[202:205], 0
	v_mfma_f32_16x16x32_bf16 v[80:83], v[178:181], v[202:205], 0
	v_mfma_f32_16x16x32_bf16 v[68:71], v[162:165], v[210:213], 0
	v_mfma_f32_16x16x32_bf16 v[64:67], v[178:181], v[210:213], 0
	v_mfma_f32_16x16x32_bf16 v[116:119], v[174:177], v[190:193], v[116:119]
	v_mfma_f32_16x16x32_bf16 v[112:115], v[182:185], v[190:193], v[112:115]
	v_mfma_f32_16x16x32_bf16 v[100:103], v[174:177], v[198:201], v[100:103]
	v_mfma_f32_16x16x32_bf16 v[96:99], v[182:185], v[198:201], v[96:99]
	v_mfma_f32_16x16x32_bf16 v[84:87], v[174:177], v[206:209], v[84:87]
	v_mfma_f32_16x16x32_bf16 v[80:83], v[182:185], v[206:209], v[80:83]
	v_mfma_f32_16x16x32_bf16 v[68:71], v[174:177], v[214:217], v[68:71]
	v_mfma_f32_16x16x32_bf16 v[64:67], v[182:185], v[214:217], v[64:67]
	s_barrier
	s_add_i32 s52, s79, s66
	v_lshl_add_u64 v[218:219], s[8:9], 0, v[130:131]
	s_mov_b32 m0, s52
	ds_read_b128 v[186:189], v172 offset:16384
	ds_read_b128 v[190:193], v172 offset:17408
	ds_read_b128 v[194:197], v172 offset:18432
	ds_read_b128 v[198:201], v172 offset:19456
	ds_read_b128 v[202:205], v172 offset:20480
	ds_read_b128 v[206:209], v172 offset:21504
	ds_read_b128 v[210:213], v172 offset:22528
	ds_read_b128 v[214:217], v172 offset:23552
	global_load_lds_dwordx4 v[218:219], off
	s_add_i32 m0, s52, 0x2000
	s_add_u32 s52, s8, 0x40000
	v_lshl_add_u64 v[220:221], s[8:9], 0, v[134:135]
	s_addc_u32 s53, s9, 0
	s_add_i32 s56, s85, s66
	global_load_lds_dwordx4 v[220:221], off
	v_lshl_add_u64 v[222:223], s[52:53], 0, v[130:131]
	s_mov_b32 m0, s56
	v_lshl_add_u64 v[224:225], s[44:45], 0, v[132:133]
	global_load_lds_dwordx4 v[222:223], off
	v_lshl_add_u64 v[222:223], s[52:53], 0, v[134:135]
	s_add_i32 m0, s56, 0x2000
	s_nop 0
	global_load_lds_dwordx4 v[222:223], off
	v_lshl_add_u64 v[222:223], s[44:45], 0, v[128:129]
	s_mov_b32 m0, s67
	s_nop 0
	global_load_lds_dwordx4 v[222:223], off
	s_mov_b32 m0, s72
	s_nop 0
	global_load_lds_dwordx4 v[224:225], off
	s_waitcnt vmcnt(8)
	s_waitcnt lgkmcnt(0)
	s_barrier
	s_waitcnt lgkmcnt(0)
	v_mfma_f32_16x16x32_bf16 v[60:63], v[144:147], v[186:189], 0
	v_mfma_f32_16x16x32_bf16 v[56:59], v[152:155], v[186:189], 0
	v_mfma_f32_16x16x32_bf16 v[44:47], v[144:147], v[194:197], 0
	v_mfma_f32_16x16x32_bf16 v[40:43], v[152:155], v[194:197], 0
	v_mfma_f32_16x16x32_bf16 v[28:31], v[144:147], v[202:205], 0
	v_mfma_f32_16x16x32_bf16 v[24:27], v[152:155], v[202:205], 0
	v_mfma_f32_16x16x32_bf16 v[12:15], v[144:147], v[210:213], 0
	v_mfma_f32_16x16x32_bf16 v[8:11], v[152:155], v[210:213], 0
	v_mfma_f32_16x16x32_bf16 v[60:63], v[148:151], v[190:193], v[60:63]
	v_mfma_f32_16x16x32_bf16 v[56:59], v[156:159], v[190:193], v[56:59]
	v_mfma_f32_16x16x32_bf16 v[44:47], v[148:151], v[198:201], v[44:47]
	v_mfma_f32_16x16x32_bf16 v[40:43], v[156:159], v[198:201], v[40:43]
	v_mfma_f32_16x16x32_bf16 v[28:31], v[148:151], v[206:209], v[28:31]
	v_mfma_f32_16x16x32_bf16 v[24:27], v[156:159], v[206:209], v[24:27]
	v_mfma_f32_16x16x32_bf16 v[12:15], v[148:151], v[214:217], v[12:15]
	v_mfma_f32_16x16x32_bf16 v[8:11], v[156:159], v[214:217], v[8:11]
	v_mfma_f32_16x16x32_bf16 v[52:55], v[162:165], v[186:189], 0
	v_mfma_f32_16x16x32_bf16 v[48:51], v[178:181], v[186:189], 0
	v_mfma_f32_16x16x32_bf16 v[36:39], v[162:165], v[194:197], 0
	v_mfma_f32_16x16x32_bf16 v[32:35], v[178:181], v[194:197], 0
	v_mfma_f32_16x16x32_bf16 v[20:23], v[162:165], v[202:205], 0
	v_mfma_f32_16x16x32_bf16 v[16:19], v[178:181], v[202:205], 0
	v_mfma_f32_16x16x32_bf16 v[4:7], v[162:165], v[210:213], 0
	v_mfma_f32_16x16x32_bf16 v[0:3], v[178:181], v[210:213], 0
	v_mfma_f32_16x16x32_bf16 v[52:55], v[174:177], v[190:193], v[52:55]
	v_mfma_f32_16x16x32_bf16 v[48:51], v[182:185], v[190:193], v[48:51]
	v_mfma_f32_16x16x32_bf16 v[36:39], v[174:177], v[198:201], v[36:39]
	v_mfma_f32_16x16x32_bf16 v[32:35], v[182:185], v[198:201], v[32:35]
	v_mfma_f32_16x16x32_bf16 v[20:23], v[174:177], v[206:209], v[20:23]
	v_mfma_f32_16x16x32_bf16 v[16:19], v[182:185], v[206:209], v[16:19]
	v_mfma_f32_16x16x32_bf16 v[4:7], v[174:177], v[214:217], v[4:7]
	v_mfma_f32_16x16x32_bf16 v[0:3], v[182:185], v[214:217], v[0:3]
	s_barrier
	s_add_i32 s52, 0, 0x18000
	s_add_i32 s53, 0, 0x1c000
	v_add_u32_e32 v156, s52, v168
	v_add_u32_e32 v173, s53, v168
	ds_read_b128 v[144:147], v156
	ds_read_b128 v[148:151], v156 offset:1024
	ds_read_b128 v[152:155], v156 offset:2048
	ds_read_b128 v[156:159], v156 offset:3072
	ds_read_b128 v[162:165], v173
	ds_read_b128 v[174:177], v173 offset:1024
	ds_read_b128 v[178:181], v173 offset:2048
	ds_read_b128 v[182:185], v173 offset:3072
	s_add_u32 s44, s44, 0x40000
	s_addc_u32 s45, s45, 0
	s_mov_b32 m0, s73
	v_lshl_add_u64 v[226:227], s[44:45], 0, v[128:129]
	ds_read_b128 v[186:189], v172 offset:32768
	ds_read_b128 v[190:193], v172 offset:33792
	ds_read_b128 v[194:197], v172 offset:34816
	ds_read_b128 v[198:201], v172 offset:35840
	ds_read_b128 v[202:205], v172 offset:36864
	ds_read_b128 v[206:209], v172 offset:37888
	ds_read_b128 v[210:213], v172 offset:38912
	ds_read_b128 v[214:217], v172 offset:39936
	global_load_lds_dwordx4 v[226:227], off
	v_lshl_add_u64 v[226:227], s[44:45], 0, v[132:133]
	s_mov_b32 m0, s74
	s_nop 0
	global_load_lds_dwordx4 v[226:227], off
	s_waitcnt vmcnt(8)
	s_waitcnt lgkmcnt(0)
	s_barrier
	s_waitcnt lgkmcnt(0)
	v_mfma_f32_16x16x32_bf16 v[124:127], v[144:147], v[186:189], v[124:127]
	v_mfma_f32_16x16x32_bf16 v[120:123], v[152:155], v[186:189], v[120:123]
	v_mfma_f32_16x16x32_bf16 v[108:111], v[144:147], v[194:197], v[108:111]
	v_mfma_f32_16x16x32_bf16 v[104:107], v[152:155], v[194:197], v[104:107]
	v_mfma_f32_16x16x32_bf16 v[92:95], v[144:147], v[202:205], v[92:95]
	v_mfma_f32_16x16x32_bf16 v[88:91], v[152:155], v[202:205], v[88:91]
	v_mfma_f32_16x16x32_bf16 v[76:79], v[144:147], v[210:213], v[76:79]
	v_mfma_f32_16x16x32_bf16 v[72:75], v[152:155], v[210:213], v[72:75]
	v_mfma_f32_16x16x32_bf16 v[124:127], v[148:151], v[190:193], v[124:127]
	v_mfma_f32_16x16x32_bf16 v[120:123], v[156:159], v[190:193], v[120:123]
	v_mfma_f32_16x16x32_bf16 v[108:111], v[148:151], v[198:201], v[108:111]
	v_mfma_f32_16x16x32_bf16 v[104:107], v[156:159], v[198:201], v[104:107]
	v_mfma_f32_16x16x32_bf16 v[92:95], v[148:151], v[206:209], v[92:95]
	v_mfma_f32_16x16x32_bf16 v[88:91], v[156:159], v[206:209], v[88:91]
	v_mfma_f32_16x16x32_bf16 v[76:79], v[148:151], v[214:217], v[76:79]
	v_mfma_f32_16x16x32_bf16 v[72:75], v[156:159], v[214:217], v[72:75]
	v_mfma_f32_16x16x32_bf16 v[116:119], v[162:165], v[186:189], v[116:119]
	v_mfma_f32_16x16x32_bf16 v[112:115], v[178:181], v[186:189], v[112:115]
	v_mfma_f32_16x16x32_bf16 v[100:103], v[162:165], v[194:197], v[100:103]
	v_mfma_f32_16x16x32_bf16 v[96:99], v[178:181], v[194:197], v[96:99]
	v_mfma_f32_16x16x32_bf16 v[84:87], v[162:165], v[202:205], v[84:87]
	v_mfma_f32_16x16x32_bf16 v[80:83], v[178:181], v[202:205], v[80:83]
	v_mfma_f32_16x16x32_bf16 v[68:71], v[162:165], v[210:213], v[68:71]
	v_mfma_f32_16x16x32_bf16 v[64:67], v[178:181], v[210:213], v[64:67]
	v_mfma_f32_16x16x32_bf16 v[116:119], v[174:177], v[190:193], v[116:119]
	v_mfma_f32_16x16x32_bf16 v[112:115], v[182:185], v[190:193], v[112:115]
	v_mfma_f32_16x16x32_bf16 v[100:103], v[174:177], v[198:201], v[100:103]
	v_mfma_f32_16x16x32_bf16 v[96:99], v[182:185], v[198:201], v[96:99]
	v_mfma_f32_16x16x32_bf16 v[84:87], v[174:177], v[206:209], v[84:87]
	v_mfma_f32_16x16x32_bf16 v[80:83], v[182:185], v[206:209], v[80:83]
	v_mfma_f32_16x16x32_bf16 v[68:71], v[174:177], v[214:217], v[68:71]
	v_mfma_f32_16x16x32_bf16 v[64:67], v[182:185], v[214:217], v[64:67]
	s_barrier
	s_add_i32 s44, s52, s66
	v_lshl_add_u64 v[218:219], v[218:219], 0, s[30:31]
	s_mov_b32 m0, s44
	ds_read_b128 v[186:189], v172 offset:49152
	ds_read_b128 v[190:193], v172 offset:50176
	ds_read_b128 v[194:197], v172 offset:51200
	ds_read_b128 v[198:201], v172 offset:52224
	ds_read_b128 v[202:205], v172 offset:53248
	ds_read_b128 v[206:209], v172 offset:54272
	ds_read_b128 v[210:213], v172 offset:55296
	ds_read_b128 v[214:217], v172 offset:56320
	global_load_lds_dwordx4 v[218:219], off
	s_add_i32 m0, s44, 0x2000
	s_add_u32 s8, s8, 0x40080
	v_lshl_add_u64 v[218:219], v[220:221], 0, s[30:31]
	s_addc_u32 s9, s9, 0
	s_add_i32 s44, s53, s66
	global_load_lds_dwordx4 v[218:219], off
	v_lshl_add_u64 v[218:219], s[8:9], 0, v[130:131]
	s_mov_b32 m0, s44
	s_nop 0
	global_load_lds_dwordx4 v[218:219], off
	v_lshl_add_u64 v[218:219], s[8:9], 0, v[134:135]
	s_add_i32 m0, s44, 0x2000
	s_nop 0
	global_load_lds_dwordx4 v[218:219], off
	v_lshl_add_u64 v[218:219], v[222:223], 0, s[30:31]
	s_mov_b32 m0, s77
	s_nop 0
	global_load_lds_dwordx4 v[218:219], off
	v_lshl_add_u64 v[218:219], v[224:225], 0, s[30:31]
	s_mov_b32 m0, s78
	s_nop 0
	global_load_lds_dwordx4 v[218:219], off
	s_waitcnt vmcnt(8)
	s_waitcnt lgkmcnt(0)
	s_barrier
	s_waitcnt lgkmcnt(0)
	v_mfma_f32_16x16x32_bf16 v[60:63], v[144:147], v[186:189], v[60:63]
	v_mfma_f32_16x16x32_bf16 v[56:59], v[152:155], v[186:189], v[56:59]
	v_mfma_f32_16x16x32_bf16 v[44:47], v[144:147], v[194:197], v[44:47]
	v_mfma_f32_16x16x32_bf16 v[40:43], v[152:155], v[194:197], v[40:43]
	v_mfma_f32_16x16x32_bf16 v[28:31], v[144:147], v[202:205], v[28:31]
	v_mfma_f32_16x16x32_bf16 v[24:27], v[152:155], v[202:205], v[24:27]
	v_mfma_f32_16x16x32_bf16 v[12:15], v[144:147], v[210:213], v[12:15]
	v_mfma_f32_16x16x32_bf16 v[8:11], v[152:155], v[210:213], v[8:11]
	v_mfma_f32_16x16x32_bf16 v[60:63], v[148:151], v[190:193], v[60:63]
	v_mfma_f32_16x16x32_bf16 v[56:59], v[156:159], v[190:193], v[56:59]
	v_mfma_f32_16x16x32_bf16 v[44:47], v[148:151], v[198:201], v[44:47]
	v_mfma_f32_16x16x32_bf16 v[40:43], v[156:159], v[198:201], v[40:43]
	v_mfma_f32_16x16x32_bf16 v[28:31], v[148:151], v[206:209], v[28:31]
	v_mfma_f32_16x16x32_bf16 v[24:27], v[156:159], v[206:209], v[24:27]
	v_mfma_f32_16x16x32_bf16 v[12:15], v[148:151], v[214:217], v[12:15]
	v_mfma_f32_16x16x32_bf16 v[8:11], v[156:159], v[214:217], v[8:11]
	v_mfma_f32_16x16x32_bf16 v[52:55], v[162:165], v[186:189], v[52:55]
	v_mfma_f32_16x16x32_bf16 v[48:51], v[178:181], v[186:189], v[48:51]
	v_mfma_f32_16x16x32_bf16 v[36:39], v[162:165], v[194:197], v[36:39]
	v_mfma_f32_16x16x32_bf16 v[32:35], v[178:181], v[194:197], v[32:35]
	v_mfma_f32_16x16x32_bf16 v[20:23], v[162:165], v[202:205], v[20:23]
	v_mfma_f32_16x16x32_bf16 v[16:19], v[178:181], v[202:205], v[16:19]
	v_mfma_f32_16x16x32_bf16 v[4:7], v[162:165], v[210:213], v[4:7]
	v_mfma_f32_16x16x32_bf16 v[0:3], v[178:181], v[210:213], v[0:3]
	v_mfma_f32_16x16x32_bf16 v[52:55], v[174:177], v[190:193], v[52:55]
	v_mfma_f32_16x16x32_bf16 v[48:51], v[182:185], v[190:193], v[48:51]
	v_mfma_f32_16x16x32_bf16 v[36:39], v[174:177], v[198:201], v[36:39]
	v_mfma_f32_16x16x32_bf16 v[32:35], v[182:185], v[198:201], v[32:35]
	v_mfma_f32_16x16x32_bf16 v[20:23], v[174:177], v[206:209], v[20:23]
	v_mfma_f32_16x16x32_bf16 v[16:19], v[182:185], v[206:209], v[16:19]
	v_mfma_f32_16x16x32_bf16 v[4:7], v[174:177], v[214:217], v[4:7]
	v_mfma_f32_16x16x32_bf16 v[0:3], v[182:185], v[214:217], v[0:3]
	s_barrier
	s_add_i32 s47, s47, 2
	s_add_u32 s0, s0, 0x100
	s_addc_u32 s1, s1, 0
	s_add_u32 s39, s39, 0x100
	s_addc_u32 s46, s46, 0
	s_cmp_gt_u32 s47, 13
	s_cbranch_scc0 .LBB0_229
	s_branch .Lpeel_exit_1
.LBB0_229:
	ds_read_b128 v[144:147], v170
	ds_read_b128 v[148:151], v170 offset:1024
	ds_read_b128 v[152:155], v170 offset:2048
	ds_read_b128 v[156:159], v170 offset:3072
	ds_read_b128 v[162:165], v171
	ds_read_b128 v[174:177], v171 offset:1024
	ds_read_b128 v[178:181], v171 offset:2048
	ds_read_b128 v[182:185], v171 offset:3072
	s_add_u32 s8, s0, 0xfffc0080
	s_addc_u32 s9, s1, -1
	s_cmp_eq_u32 s47, 12
	s_cselect_b32 s45, s5, s9
	s_cselect_b32 s44, s7, s8
	s_cselect_b32 s9, s33, s46
	s_cselect_b32 s8, s37, s39
	v_lshl_add_u64 v[218:219], s[0:1], 0, v[136:137]
	s_add_i32 m0, s67, 0xc000
	ds_read_b128 v[186:189], v172
	ds_read_b128 v[190:193], v172 offset:1024
	ds_read_b128 v[194:197], v172 offset:2048
	ds_read_b128 v[198:201], v172 offset:3072
	ds_read_b128 v[202:205], v172 offset:4096
	ds_read_b128 v[206:209], v172 offset:5120
	ds_read_b128 v[210:213], v172 offset:6144
	ds_read_b128 v[214:217], v172 offset:7168
	global_load_lds_dwordx4 v[218:219], off
	v_lshl_add_u64 v[218:219], s[0:1], 0, v[138:139]
	s_add_i32 m0, s67, 0xe000
	s_nop 0
	global_load_lds_dwordx4 v[218:219], off
	s_waitcnt vmcnt(8)
	s_waitcnt lgkmcnt(0)
	s_barrier
	s_waitcnt lgkmcnt(0)
	v_mfma_f32_16x16x32_bf16 v[124:127], v[144:147], v[186:189], v[124:127]
	v_mfma_f32_16x16x32_bf16 v[120:123], v[152:155], v[186:189], v[120:123]
	v_mfma_f32_16x16x32_bf16 v[108:111], v[144:147], v[194:197], v[108:111]
	v_mfma_f32_16x16x32_bf16 v[104:107], v[152:155], v[194:197], v[104:107]
	v_mfma_f32_16x16x32_bf16 v[92:95], v[144:147], v[202:205], v[92:95]
	v_mfma_f32_16x16x32_bf16 v[88:91], v[152:155], v[202:205], v[88:91]
	v_mfma_f32_16x16x32_bf16 v[76:79], v[144:147], v[210:213], v[76:79]
	v_mfma_f32_16x16x32_bf16 v[72:75], v[152:155], v[210:213], v[72:75]
	v_mfma_f32_16x16x32_bf16 v[124:127], v[148:151], v[190:193], v[124:127]
	v_mfma_f32_16x16x32_bf16 v[120:123], v[156:159], v[190:193], v[120:123]
	v_mfma_f32_16x16x32_bf16 v[108:111], v[148:151], v[198:201], v[108:111]
	v_mfma_f32_16x16x32_bf16 v[104:107], v[156:159], v[198:201], v[104:107]
	v_mfma_f32_16x16x32_bf16 v[92:95], v[148:151], v[206:209], v[92:95]
	v_mfma_f32_16x16x32_bf16 v[88:91], v[156:159], v[206:209], v[88:91]
	v_mfma_f32_16x16x32_bf16 v[76:79], v[148:151], v[214:217], v[76:79]
	v_mfma_f32_16x16x32_bf16 v[72:75], v[156:159], v[214:217], v[72:75]
	v_mfma_f32_16x16x32_bf16 v[116:119], v[162:165], v[186:189], v[116:119]
	v_mfma_f32_16x16x32_bf16 v[112:115], v[178:181], v[186:189], v[112:115]
	v_mfma_f32_16x16x32_bf16 v[100:103], v[162:165], v[194:197], v[100:103]
	v_mfma_f32_16x16x32_bf16 v[96:99], v[178:181], v[194:197], v[96:99]
	v_mfma_f32_16x16x32_bf16 v[84:87], v[162:165], v[202:205], v[84:87]
	v_mfma_f32_16x16x32_bf16 v[80:83], v[178:181], v[202:205], v[80:83]
	v_mfma_f32_16x16x32_bf16 v[68:71], v[162:165], v[210:213], v[68:71]
	v_mfma_f32_16x16x32_bf16 v[64:67], v[178:181], v[210:213], v[64:67]
	v_mfma_f32_16x16x32_bf16 v[116:119], v[174:177], v[190:193], v[116:119]
	v_mfma_f32_16x16x32_bf16 v[112:115], v[182:185], v[190:193], v[112:115]
	v_mfma_f32_16x16x32_bf16 v[100:103], v[174:177], v[198:201], v[100:103]
	v_mfma_f32_16x16x32_bf16 v[96:99], v[182:185], v[198:201], v[96:99]
	v_mfma_f32_16x16x32_bf16 v[84:87], v[174:177], v[206:209], v[84:87]
	v_mfma_f32_16x16x32_bf16 v[80:83], v[182:185], v[206:209], v[80:83]
	v_mfma_f32_16x16x32_bf16 v[68:71], v[174:177], v[214:217], v[68:71]
	v_mfma_f32_16x16x32_bf16 v[64:67], v[182:185], v[214:217], v[64:67]
	s_barrier
	s_add_i32 s52, s79, s66
	v_lshl_add_u64 v[218:219], s[8:9], 0, v[130:131]
	s_mov_b32 m0, s52
	ds_read_b128 v[186:189], v172 offset:16384
	ds_read_b128 v[190:193], v172 offset:17408
	ds_read_b128 v[194:197], v172 offset:18432
	ds_read_b128 v[198:201], v172 offset:19456
	ds_read_b128 v[202:205], v172 offset:20480
	ds_read_b128 v[206:209], v172 offset:21504
	ds_read_b128 v[210:213], v172 offset:22528
	ds_read_b128 v[214:217], v172 offset:23552
	global_load_lds_dwordx4 v[218:219], off
	s_add_i32 m0, s52, 0x2000
	s_add_u32 s52, s8, 0x40000
	v_lshl_add_u64 v[220:221], s[8:9], 0, v[134:135]
	s_addc_u32 s53, s9, 0
	s_add_i32 s56, s85, s66
	global_load_lds_dwordx4 v[220:221], off
	v_lshl_add_u64 v[222:223], s[52:53], 0, v[130:131]
	s_mov_b32 m0, s56
	v_lshl_add_u64 v[224:225], s[44:45], 0, v[132:133]
	global_load_lds_dwordx4 v[222:223], off
	v_lshl_add_u64 v[222:223], s[52:53], 0, v[134:135]
	s_add_i32 m0, s56, 0x2000
	s_nop 0
	global_load_lds_dwordx4 v[222:223], off
	v_lshl_add_u64 v[222:223], s[44:45], 0, v[128:129]
	s_mov_b32 m0, s67
	s_nop 0
	global_load_lds_dwordx4 v[222:223], off
	s_mov_b32 m0, s72
	s_nop 0
	global_load_lds_dwordx4 v[224:225], off
	s_waitcnt vmcnt(8)
	s_waitcnt lgkmcnt(0)
	s_barrier
	s_waitcnt lgkmcnt(0)
	v_mfma_f32_16x16x32_bf16 v[60:63], v[144:147], v[186:189], v[60:63]
	v_mfma_f32_16x16x32_bf16 v[56:59], v[152:155], v[186:189], v[56:59]
	v_mfma_f32_16x16x32_bf16 v[44:47], v[144:147], v[194:197], v[44:47]
	v_mfma_f32_16x16x32_bf16 v[40:43], v[152:155], v[194:197], v[40:43]
	v_mfma_f32_16x16x32_bf16 v[28:31], v[144:147], v[202:205], v[28:31]
	v_mfma_f32_16x16x32_bf16 v[24:27], v[152:155], v[202:205], v[24:27]
	v_mfma_f32_16x16x32_bf16 v[12:15], v[144:147], v[210:213], v[12:15]
	v_mfma_f32_16x16x32_bf16 v[8:11], v[152:155], v[210:213], v[8:11]
	v_mfma_f32_16x16x32_bf16 v[60:63], v[148:151], v[190:193], v[60:63]
	v_mfma_f32_16x16x32_bf16 v[56:59], v[156:159], v[190:193], v[56:59]
	v_mfma_f32_16x16x32_bf16 v[44:47], v[148:151], v[198:201], v[44:47]
	v_mfma_f32_16x16x32_bf16 v[40:43], v[156:159], v[198:201], v[40:43]
	v_mfma_f32_16x16x32_bf16 v[28:31], v[148:151], v[206:209], v[28:31]
	v_mfma_f32_16x16x32_bf16 v[24:27], v[156:159], v[206:209], v[24:27]
	v_mfma_f32_16x16x32_bf16 v[12:15], v[148:151], v[214:217], v[12:15]
	v_mfma_f32_16x16x32_bf16 v[8:11], v[156:159], v[214:217], v[8:11]
	v_mfma_f32_16x16x32_bf16 v[52:55], v[162:165], v[186:189], v[52:55]
	v_mfma_f32_16x16x32_bf16 v[48:51], v[178:181], v[186:189], v[48:51]
	v_mfma_f32_16x16x32_bf16 v[36:39], v[162:165], v[194:197], v[36:39]
	v_mfma_f32_16x16x32_bf16 v[32:35], v[178:181], v[194:197], v[32:35]
	v_mfma_f32_16x16x32_bf16 v[20:23], v[162:165], v[202:205], v[20:23]
	v_mfma_f32_16x16x32_bf16 v[16:19], v[178:181], v[202:205], v[16:19]
	v_mfma_f32_16x16x32_bf16 v[4:7], v[162:165], v[210:213], v[4:7]
	v_mfma_f32_16x16x32_bf16 v[0:3], v[178:181], v[210:213], v[0:3]
	v_mfma_f32_16x16x32_bf16 v[52:55], v[174:177], v[190:193], v[52:55]
	v_mfma_f32_16x16x32_bf16 v[48:51], v[182:185], v[190:193], v[48:51]
	v_mfma_f32_16x16x32_bf16 v[36:39], v[174:177], v[198:201], v[36:39]
	v_mfma_f32_16x16x32_bf16 v[32:35], v[182:185], v[198:201], v[32:35]
	v_mfma_f32_16x16x32_bf16 v[20:23], v[174:177], v[206:209], v[20:23]
	v_mfma_f32_16x16x32_bf16 v[16:19], v[182:185], v[206:209], v[16:19]
	v_mfma_f32_16x16x32_bf16 v[4:7], v[174:177], v[214:217], v[4:7]
	v_mfma_f32_16x16x32_bf16 v[0:3], v[182:185], v[214:217], v[0:3]
	s_barrier
	s_add_i32 s52, 0, 0x18000
	s_add_i32 s53, 0, 0x1c000
	v_add_u32_e32 v156, s52, v168
	v_add_u32_e32 v173, s53, v168
	ds_read_b128 v[144:147], v156
	ds_read_b128 v[148:151], v156 offset:1024
	ds_read_b128 v[152:155], v156 offset:2048
	ds_read_b128 v[156:159], v156 offset:3072
	ds_read_b128 v[162:165], v173
	ds_read_b128 v[174:177], v173 offset:1024
	ds_read_b128 v[178:181], v173 offset:2048
	ds_read_b128 v[182:185], v173 offset:3072
	s_add_u32 s44, s44, 0x40000
	s_addc_u32 s45, s45, 0
	s_mov_b32 m0, s73
	v_lshl_add_u64 v[226:227], s[44:45], 0, v[128:129]
	ds_read_b128 v[186:189], v172 offset:32768
	ds_read_b128 v[190:193], v172 offset:33792
	ds_read_b128 v[194:197], v172 offset:34816
	ds_read_b128 v[198:201], v172 offset:35840
	ds_read_b128 v[202:205], v172 offset:36864
	ds_read_b128 v[206:209], v172 offset:37888
	ds_read_b128 v[210:213], v172 offset:38912
	ds_read_b128 v[214:217], v172 offset:39936
	global_load_lds_dwordx4 v[226:227], off
	v_lshl_add_u64 v[226:227], s[44:45], 0, v[132:133]
	s_mov_b32 m0, s74
	s_nop 0
	global_load_lds_dwordx4 v[226:227], off
	s_waitcnt vmcnt(8)
	s_waitcnt lgkmcnt(0)
	s_barrier
	s_waitcnt lgkmcnt(0)
	v_mfma_f32_16x16x32_bf16 v[124:127], v[144:147], v[186:189], v[124:127]
	v_mfma_f32_16x16x32_bf16 v[120:123], v[152:155], v[186:189], v[120:123]
	v_mfma_f32_16x16x32_bf16 v[108:111], v[144:147], v[194:197], v[108:111]
	v_mfma_f32_16x16x32_bf16 v[104:107], v[152:155], v[194:197], v[104:107]
	v_mfma_f32_16x16x32_bf16 v[92:95], v[144:147], v[202:205], v[92:95]
	v_mfma_f32_16x16x32_bf16 v[88:91], v[152:155], v[202:205], v[88:91]
	v_mfma_f32_16x16x32_bf16 v[76:79], v[144:147], v[210:213], v[76:79]
	v_mfma_f32_16x16x32_bf16 v[72:75], v[152:155], v[210:213], v[72:75]
	v_mfma_f32_16x16x32_bf16 v[124:127], v[148:151], v[190:193], v[124:127]
	v_mfma_f32_16x16x32_bf16 v[120:123], v[156:159], v[190:193], v[120:123]
	v_mfma_f32_16x16x32_bf16 v[108:111], v[148:151], v[198:201], v[108:111]
	v_mfma_f32_16x16x32_bf16 v[104:107], v[156:159], v[198:201], v[104:107]
	v_mfma_f32_16x16x32_bf16 v[92:95], v[148:151], v[206:209], v[92:95]
	v_mfma_f32_16x16x32_bf16 v[88:91], v[156:159], v[206:209], v[88:91]
	v_mfma_f32_16x16x32_bf16 v[76:79], v[148:151], v[214:217], v[76:79]
	v_mfma_f32_16x16x32_bf16 v[72:75], v[156:159], v[214:217], v[72:75]
	v_mfma_f32_16x16x32_bf16 v[116:119], v[162:165], v[186:189], v[116:119]
	v_mfma_f32_16x16x32_bf16 v[112:115], v[178:181], v[186:189], v[112:115]
	v_mfma_f32_16x16x32_bf16 v[100:103], v[162:165], v[194:197], v[100:103]
	v_mfma_f32_16x16x32_bf16 v[96:99], v[178:181], v[194:197], v[96:99]
	v_mfma_f32_16x16x32_bf16 v[84:87], v[162:165], v[202:205], v[84:87]
	v_mfma_f32_16x16x32_bf16 v[80:83], v[178:181], v[202:205], v[80:83]
	v_mfma_f32_16x16x32_bf16 v[68:71], v[162:165], v[210:213], v[68:71]
	v_mfma_f32_16x16x32_bf16 v[64:67], v[178:181], v[210:213], v[64:67]
	v_mfma_f32_16x16x32_bf16 v[116:119], v[174:177], v[190:193], v[116:119]
	v_mfma_f32_16x16x32_bf16 v[112:115], v[182:185], v[190:193], v[112:115]
	v_mfma_f32_16x16x32_bf16 v[100:103], v[174:177], v[198:201], v[100:103]
	v_mfma_f32_16x16x32_bf16 v[96:99], v[182:185], v[198:201], v[96:99]
	v_mfma_f32_16x16x32_bf16 v[84:87], v[174:177], v[206:209], v[84:87]
	v_mfma_f32_16x16x32_bf16 v[80:83], v[182:185], v[206:209], v[80:83]
	v_mfma_f32_16x16x32_bf16 v[68:71], v[174:177], v[214:217], v[68:71]
	v_mfma_f32_16x16x32_bf16 v[64:67], v[182:185], v[214:217], v[64:67]
	s_barrier
	s_add_i32 s44, s52, s66
	v_lshl_add_u64 v[218:219], v[218:219], 0, s[30:31]
	s_mov_b32 m0, s44
	ds_read_b128 v[186:189], v172 offset:49152
	ds_read_b128 v[190:193], v172 offset:50176
	ds_read_b128 v[194:197], v172 offset:51200
	ds_read_b128 v[198:201], v172 offset:52224
	ds_read_b128 v[202:205], v172 offset:53248
	ds_read_b128 v[206:209], v172 offset:54272
	ds_read_b128 v[210:213], v172 offset:55296
	ds_read_b128 v[214:217], v172 offset:56320
	global_load_lds_dwordx4 v[218:219], off
	s_add_i32 m0, s44, 0x2000
	s_add_u32 s8, s8, 0x40080
	v_lshl_add_u64 v[218:219], v[220:221], 0, s[30:31]
	s_addc_u32 s9, s9, 0
	s_add_i32 s44, s53, s66
	global_load_lds_dwordx4 v[218:219], off
	v_lshl_add_u64 v[218:219], s[8:9], 0, v[130:131]
	s_mov_b32 m0, s44
	s_nop 0
	global_load_lds_dwordx4 v[218:219], off
	v_lshl_add_u64 v[218:219], s[8:9], 0, v[134:135]
	s_add_i32 m0, s44, 0x2000
	s_nop 0
	global_load_lds_dwordx4 v[218:219], off
	v_lshl_add_u64 v[218:219], v[222:223], 0, s[30:31]
	s_mov_b32 m0, s77
	s_nop 0
	global_load_lds_dwordx4 v[218:219], off
	v_lshl_add_u64 v[218:219], v[224:225], 0, s[30:31]
	s_mov_b32 m0, s78
	s_nop 0
	global_load_lds_dwordx4 v[218:219], off
	s_waitcnt vmcnt(8)
	s_waitcnt lgkmcnt(0)
	s_barrier
	s_waitcnt lgkmcnt(0)
	v_mfma_f32_16x16x32_bf16 v[60:63], v[144:147], v[186:189], v[60:63]
	v_mfma_f32_16x16x32_bf16 v[56:59], v[152:155], v[186:189], v[56:59]
	v_mfma_f32_16x16x32_bf16 v[44:47], v[144:147], v[194:197], v[44:47]
	v_mfma_f32_16x16x32_bf16 v[40:43], v[152:155], v[194:197], v[40:43]
	v_mfma_f32_16x16x32_bf16 v[28:31], v[144:147], v[202:205], v[28:31]
	v_mfma_f32_16x16x32_bf16 v[24:27], v[152:155], v[202:205], v[24:27]
	v_mfma_f32_16x16x32_bf16 v[12:15], v[144:147], v[210:213], v[12:15]
	v_mfma_f32_16x16x32_bf16 v[8:11], v[152:155], v[210:213], v[8:11]
	v_mfma_f32_16x16x32_bf16 v[60:63], v[148:151], v[190:193], v[60:63]
	v_mfma_f32_16x16x32_bf16 v[56:59], v[156:159], v[190:193], v[56:59]
	v_mfma_f32_16x16x32_bf16 v[44:47], v[148:151], v[198:201], v[44:47]
	v_mfma_f32_16x16x32_bf16 v[40:43], v[156:159], v[198:201], v[40:43]
	v_mfma_f32_16x16x32_bf16 v[28:31], v[148:151], v[206:209], v[28:31]
	v_mfma_f32_16x16x32_bf16 v[24:27], v[156:159], v[206:209], v[24:27]
	v_mfma_f32_16x16x32_bf16 v[12:15], v[148:151], v[214:217], v[12:15]
	v_mfma_f32_16x16x32_bf16 v[8:11], v[156:159], v[214:217], v[8:11]
	v_mfma_f32_16x16x32_bf16 v[52:55], v[162:165], v[186:189], v[52:55]
	v_mfma_f32_16x16x32_bf16 v[48:51], v[178:181], v[186:189], v[48:51]
	v_mfma_f32_16x16x32_bf16 v[36:39], v[162:165], v[194:197], v[36:39]
	v_mfma_f32_16x16x32_bf16 v[32:35], v[178:181], v[194:197], v[32:35]
	v_mfma_f32_16x16x32_bf16 v[20:23], v[162:165], v[202:205], v[20:23]
	v_mfma_f32_16x16x32_bf16 v[16:19], v[178:181], v[202:205], v[16:19]
	v_mfma_f32_16x16x32_bf16 v[4:7], v[162:165], v[210:213], v[4:7]
	v_mfma_f32_16x16x32_bf16 v[0:3], v[178:181], v[210:213], v[0:3]
	v_mfma_f32_16x16x32_bf16 v[52:55], v[174:177], v[190:193], v[52:55]
	v_mfma_f32_16x16x32_bf16 v[48:51], v[182:185], v[190:193], v[48:51]
	v_mfma_f32_16x16x32_bf16 v[36:39], v[174:177], v[198:201], v[36:39]
	v_mfma_f32_16x16x32_bf16 v[32:35], v[182:185], v[198:201], v[32:35]
	v_mfma_f32_16x16x32_bf16 v[20:23], v[174:177], v[206:209], v[20:23]
	v_mfma_f32_16x16x32_bf16 v[16:19], v[182:185], v[206:209], v[16:19]
	v_mfma_f32_16x16x32_bf16 v[4:7], v[174:177], v[214:217], v[4:7]
	v_mfma_f32_16x16x32_bf16 v[0:3], v[182:185], v[214:217], v[0:3]
	s_barrier
	s_add_i32 s47, s47, 2
	s_add_u32 s0, s0, 0x100
	s_addc_u32 s1, s1, 0
	s_add_u32 s39, s39, 0x100
	s_addc_u32 s46, s46, 0
	s_cmp_gt_u32 s47, 13
	s_cbranch_scc0 .LBB0_229

.LBB0_550:
	s_add_u32 s59, s16, 0x100
	s_addc_u32 s60, s17, 0
	s_mov_b32 s61, -2
	s_waitcnt lgkmcnt(0)
	ds_read_b128 v[128:131], v188
	ds_read_b128 v[132:135], v188 offset:1024
	ds_read_b128 v[136:139], v188 offset:2048
	ds_read_b128 v[140:143], v188 offset:3072
	ds_read_b128 v[144:147], v189
	ds_read_b128 v[148:151], v189 offset:1024
	ds_read_b128 v[152:155], v189 offset:2048
	ds_read_b128 v[156:159], v189 offset:3072
	s_add_u32 s16, s0, 0x100
	s_addc_u32 s17, s1, 0
	s_cmp_eq_u32 s61, 16
	s_cselect_b32 s35, s7, s17
	s_cselect_b32 s34, s6, s16
	s_cselect_b32 s29, s15, s60
	s_cselect_b32 s28, s14, s59
	v_lshl_add_u64 v[220:221], s[0:1], 0, v[170:171]
	s_add_i32 m0, s39, 0xc000
	ds_read_b128 v[178:181], v190
	ds_read_b128 v[192:195], v190 offset:1024
	ds_read_b128 v[196:199], v190 offset:2048
	ds_read_b128 v[200:203], v190 offset:3072
	ds_read_b128 v[204:207], v190 offset:4096
	ds_read_b128 v[208:211], v190 offset:5120
	ds_read_b128 v[212:215], v190 offset:6144
	ds_read_b128 v[216:219], v190 offset:7168
	global_load_lds_dwordx4 v[220:221], off
	v_lshl_add_u64 v[220:221], s[0:1], 0, v[172:173]
	s_add_i32 m0, s39, 0xe000
	s_nop 0
	global_load_lds_dwordx4 v[220:221], off
	s_waitcnt vmcnt(8)
	s_waitcnt lgkmcnt(0)
	s_barrier
	s_waitcnt lgkmcnt(0)
	v_mfma_f32_16x16x32_bf16 v[124:127], v[128:131], v[178:181], 0
	v_mfma_f32_16x16x32_bf16 v[120:123], v[136:139], v[178:181], 0
	v_mfma_f32_16x16x32_bf16 v[108:111], v[128:131], v[196:199], 0
	v_mfma_f32_16x16x32_bf16 v[104:107], v[136:139], v[196:199], 0
	v_mfma_f32_16x16x32_bf16 v[92:95], v[128:131], v[204:207], 0
	v_mfma_f32_16x16x32_bf16 v[88:91], v[136:139], v[204:207], 0
	v_mfma_f32_16x16x32_bf16 v[76:79], v[128:131], v[212:215], 0
	v_mfma_f32_16x16x32_bf16 v[72:75], v[136:139], v[212:215], 0
	v_mfma_f32_16x16x32_bf16 v[124:127], v[132:135], v[192:195], v[124:127]
	v_mfma_f32_16x16x32_bf16 v[120:123], v[140:143], v[192:195], v[120:123]
	v_mfma_f32_16x16x32_bf16 v[108:111], v[132:135], v[200:203], v[108:111]
	v_mfma_f32_16x16x32_bf16 v[104:107], v[140:143], v[200:203], v[104:107]
	v_mfma_f32_16x16x32_bf16 v[92:95], v[132:135], v[208:211], v[92:95]
	v_mfma_f32_16x16x32_bf16 v[88:91], v[140:143], v[208:211], v[88:91]
	v_mfma_f32_16x16x32_bf16 v[76:79], v[132:135], v[216:219], v[76:79]
	v_mfma_f32_16x16x32_bf16 v[72:75], v[140:143], v[216:219], v[72:75]
	v_mfma_f32_16x16x32_bf16 v[116:119], v[144:147], v[178:181], 0
	v_mfma_f32_16x16x32_bf16 v[112:115], v[152:155], v[178:181], 0
	v_mfma_f32_16x16x32_bf16 v[100:103], v[144:147], v[196:199], 0
	v_mfma_f32_16x16x32_bf16 v[96:99], v[152:155], v[196:199], 0
	v_mfma_f32_16x16x32_bf16 v[84:87], v[144:147], v[204:207], 0
	v_mfma_f32_16x16x32_bf16 v[80:83], v[152:155], v[204:207], 0
	v_mfma_f32_16x16x32_bf16 v[68:71], v[144:147], v[212:215], 0
	v_mfma_f32_16x16x32_bf16 v[64:67], v[152:155], v[212:215], 0
	v_mfma_f32_16x16x32_bf16 v[116:119], v[148:151], v[192:195], v[116:119]
	v_mfma_f32_16x16x32_bf16 v[112:115], v[156:159], v[192:195], v[112:115]
	v_mfma_f32_16x16x32_bf16 v[100:103], v[148:151], v[200:203], v[100:103]
	v_mfma_f32_16x16x32_bf16 v[96:99], v[156:159], v[200:203], v[96:99]
	v_mfma_f32_16x16x32_bf16 v[84:87], v[148:151], v[208:211], v[84:87]
	v_mfma_f32_16x16x32_bf16 v[80:83], v[156:159], v[208:211], v[80:83]
	v_mfma_f32_16x16x32_bf16 v[68:71], v[148:151], v[216:219], v[68:71]
	v_mfma_f32_16x16x32_bf16 v[64:67], v[156:159], v[216:219], v[64:67]
	s_barrier
	s_add_i32 s0, s50, s38
	v_lshl_add_u64 v[220:221], s[28:29], 0, v[164:165]
	s_mov_b32 m0, s0
	ds_read_b128 v[178:181], v190 offset:16384
	ds_read_b128 v[192:195], v190 offset:17408
	ds_read_b128 v[196:199], v190 offset:18432
	ds_read_b128 v[200:203], v190 offset:19456
	ds_read_b128 v[204:207], v190 offset:20480
	ds_read_b128 v[208:211], v190 offset:21504
	ds_read_b128 v[212:215], v190 offset:22528
	ds_read_b128 v[216:219], v190 offset:23552
	global_load_lds_dwordx4 v[220:221], off
	s_add_i32 m0, s0, 0x2000
	s_add_u32 s0, s28, 0x50000
	v_lshl_add_u64 v[222:223], s[28:29], 0, v[168:169]
	s_addc_u32 s1, s29, 0
	s_add_i32 s62, s51, s38
	global_load_lds_dwordx4 v[222:223], off
	v_lshl_add_u64 v[224:225], s[0:1], 0, v[164:165]
	s_mov_b32 m0, s62
	v_lshl_add_u64 v[226:227], s[34:35], 0, v[166:167]
	global_load_lds_dwordx4 v[224:225], off
	v_lshl_add_u64 v[224:225], s[0:1], 0, v[168:169]
	s_add_i32 m0, s62, 0x2000
	s_nop 0
	global_load_lds_dwordx4 v[224:225], off
	v_lshl_add_u64 v[224:225], s[34:35], 0, v[162:163]
	s_mov_b32 m0, s39
	s_nop 0
	global_load_lds_dwordx4 v[224:225], off
	s_mov_b32 m0, s40
	s_nop 0
	global_load_lds_dwordx4 v[226:227], off
	s_waitcnt vmcnt(8)
	s_waitcnt lgkmcnt(0)
	s_barrier
	s_waitcnt lgkmcnt(0)
	v_mfma_f32_16x16x32_bf16 v[60:63], v[128:131], v[178:181], 0
	v_mfma_f32_16x16x32_bf16 v[56:59], v[136:139], v[178:181], 0
	v_mfma_f32_16x16x32_bf16 v[44:47], v[128:131], v[196:199], 0
	v_mfma_f32_16x16x32_bf16 v[40:43], v[136:139], v[196:199], 0
	v_mfma_f32_16x16x32_bf16 v[28:31], v[128:131], v[204:207], 0
	v_mfma_f32_16x16x32_bf16 v[24:27], v[136:139], v[204:207], 0
	v_mfma_f32_16x16x32_bf16 v[12:15], v[128:131], v[212:215], 0
	v_mfma_f32_16x16x32_bf16 v[8:11], v[136:139], v[212:215], 0
	v_mfma_f32_16x16x32_bf16 v[60:63], v[132:135], v[192:195], v[60:63]
	v_mfma_f32_16x16x32_bf16 v[56:59], v[140:143], v[192:195], v[56:59]
	v_mfma_f32_16x16x32_bf16 v[44:47], v[132:135], v[200:203], v[44:47]
	v_mfma_f32_16x16x32_bf16 v[40:43], v[140:143], v[200:203], v[40:43]
	v_mfma_f32_16x16x32_bf16 v[28:31], v[132:135], v[208:211], v[28:31]
	v_mfma_f32_16x16x32_bf16 v[24:27], v[140:143], v[208:211], v[24:27]
	v_mfma_f32_16x16x32_bf16 v[12:15], v[132:135], v[216:219], v[12:15]
	v_mfma_f32_16x16x32_bf16 v[8:11], v[140:143], v[216:219], v[8:11]
	v_mfma_f32_16x16x32_bf16 v[52:55], v[144:147], v[178:181], 0
	v_mfma_f32_16x16x32_bf16 v[48:51], v[152:155], v[178:181], 0
	v_mfma_f32_16x16x32_bf16 v[36:39], v[144:147], v[196:199], 0
	v_mfma_f32_16x16x32_bf16 v[32:35], v[152:155], v[196:199], 0
	v_mfma_f32_16x16x32_bf16 v[20:23], v[144:147], v[204:207], 0
	v_mfma_f32_16x16x32_bf16 v[16:19], v[152:155], v[204:207], 0
	v_mfma_f32_16x16x32_bf16 v[4:7], v[144:147], v[212:215], 0
	v_mfma_f32_16x16x32_bf16 v[0:3], v[152:155], v[212:215], 0
	v_mfma_f32_16x16x32_bf16 v[52:55], v[148:151], v[192:195], v[52:55]
	v_mfma_f32_16x16x32_bf16 v[48:51], v[156:159], v[192:195], v[48:51]
	v_mfma_f32_16x16x32_bf16 v[36:39], v[148:151], v[200:203], v[36:39]
	v_mfma_f32_16x16x32_bf16 v[32:35], v[156:159], v[200:203], v[32:35]
	v_mfma_f32_16x16x32_bf16 v[20:23], v[148:151], v[208:211], v[20:23]
	v_mfma_f32_16x16x32_bf16 v[16:19], v[156:159], v[208:211], v[16:19]
	v_mfma_f32_16x16x32_bf16 v[4:7], v[148:151], v[216:219], v[4:7]
	v_mfma_f32_16x16x32_bf16 v[0:3], v[156:159], v[216:219], v[0:3]
	s_barrier
	s_add_i32 s62, 0, 0x18000
	s_add_i32 s63, 0, 0x1c000
	v_add_u32_e32 v140, s62, v183
	v_add_u32_e32 v156, s63, v183
	ds_read_b128 v[128:131], v140
	ds_read_b128 v[132:135], v140 offset:1024
	ds_read_b128 v[136:139], v140 offset:2048
	ds_read_b128 v[140:143], v140 offset:3072
	ds_read_b128 v[144:147], v156
	ds_read_b128 v[148:151], v156 offset:1024
	ds_read_b128 v[152:155], v156 offset:2048
	ds_read_b128 v[156:159], v156 offset:3072
	s_add_u32 s0, s34, 0x50000
	s_addc_u32 s1, s35, 0
	s_mov_b32 m0, s41
	v_lshl_add_u64 v[228:229], s[0:1], 0, v[162:163]
	ds_read_b128 v[178:181], v190 offset:32768
	ds_read_b128 v[192:195], v190 offset:33792
	ds_read_b128 v[196:199], v190 offset:34816
	ds_read_b128 v[200:203], v190 offset:35840
	ds_read_b128 v[204:207], v190 offset:36864
	ds_read_b128 v[208:211], v190 offset:37888
	ds_read_b128 v[212:215], v190 offset:38912
	ds_read_b128 v[216:219], v190 offset:39936
	global_load_lds_dwordx4 v[228:229], off
	v_lshl_add_u64 v[228:229], s[0:1], 0, v[166:167]
	s_mov_b32 m0, s42
	s_nop 0
	global_load_lds_dwordx4 v[228:229], off
	s_waitcnt vmcnt(8)
	s_waitcnt lgkmcnt(0)
	s_barrier
	s_waitcnt lgkmcnt(0)
	v_mfma_f32_16x16x32_bf16 v[124:127], v[128:131], v[178:181], v[124:127]
	v_mfma_f32_16x16x32_bf16 v[120:123], v[136:139], v[178:181], v[120:123]
	v_mfma_f32_16x16x32_bf16 v[108:111], v[128:131], v[196:199], v[108:111]
	v_mfma_f32_16x16x32_bf16 v[104:107], v[136:139], v[196:199], v[104:107]
	v_mfma_f32_16x16x32_bf16 v[92:95], v[128:131], v[204:207], v[92:95]
	v_mfma_f32_16x16x32_bf16 v[88:91], v[136:139], v[204:207], v[88:91]
	v_mfma_f32_16x16x32_bf16 v[76:79], v[128:131], v[212:215], v[76:79]
	v_mfma_f32_16x16x32_bf16 v[72:75], v[136:139], v[212:215], v[72:75]
	v_mfma_f32_16x16x32_bf16 v[124:127], v[132:135], v[192:195], v[124:127]
	v_mfma_f32_16x16x32_bf16 v[120:123], v[140:143], v[192:195], v[120:123]
	v_mfma_f32_16x16x32_bf16 v[108:111], v[132:135], v[200:203], v[108:111]
	v_mfma_f32_16x16x32_bf16 v[104:107], v[140:143], v[200:203], v[104:107]
	v_mfma_f32_16x16x32_bf16 v[92:95], v[132:135], v[208:211], v[92:95]
	v_mfma_f32_16x16x32_bf16 v[88:91], v[140:143], v[208:211], v[88:91]
	v_mfma_f32_16x16x32_bf16 v[76:79], v[132:135], v[216:219], v[76:79]
	v_mfma_f32_16x16x32_bf16 v[72:75], v[140:143], v[216:219], v[72:75]
	v_mfma_f32_16x16x32_bf16 v[116:119], v[144:147], v[178:181], v[116:119]
	v_mfma_f32_16x16x32_bf16 v[112:115], v[152:155], v[178:181], v[112:115]
	v_mfma_f32_16x16x32_bf16 v[100:103], v[144:147], v[196:199], v[100:103]
	v_mfma_f32_16x16x32_bf16 v[96:99], v[152:155], v[196:199], v[96:99]
	v_mfma_f32_16x16x32_bf16 v[84:87], v[144:147], v[204:207], v[84:87]
	v_mfma_f32_16x16x32_bf16 v[80:83], v[152:155], v[204:207], v[80:83]
	v_mfma_f32_16x16x32_bf16 v[68:71], v[144:147], v[212:215], v[68:71]
	v_mfma_f32_16x16x32_bf16 v[64:67], v[152:155], v[212:215], v[64:67]
	v_mfma_f32_16x16x32_bf16 v[116:119], v[148:151], v[192:195], v[116:119]
	v_mfma_f32_16x16x32_bf16 v[112:115], v[156:159], v[192:195], v[112:115]
	v_mfma_f32_16x16x32_bf16 v[100:103], v[148:151], v[200:203], v[100:103]
	v_mfma_f32_16x16x32_bf16 v[96:99], v[156:159], v[200:203], v[96:99]
	v_mfma_f32_16x16x32_bf16 v[84:87], v[148:151], v[208:211], v[84:87]
	v_mfma_f32_16x16x32_bf16 v[80:83], v[156:159], v[208:211], v[80:83]
	v_mfma_f32_16x16x32_bf16 v[68:71], v[148:151], v[216:219], v[68:71]
	v_mfma_f32_16x16x32_bf16 v[64:67], v[156:159], v[216:219], v[64:67]
	s_barrier
	s_add_i32 s0, s62, s38
	v_lshl_add_u64 v[220:221], v[220:221], 0, s[10:11]
	s_mov_b32 m0, s0
	ds_read_b128 v[178:181], v190 offset:49152
	ds_read_b128 v[192:195], v190 offset:50176
	ds_read_b128 v[196:199], v190 offset:51200
	ds_read_b128 v[200:203], v190 offset:52224
	ds_read_b128 v[204:207], v190 offset:53248
	ds_read_b128 v[208:211], v190 offset:54272
	ds_read_b128 v[212:215], v190 offset:55296
	ds_read_b128 v[216:219], v190 offset:56320
	global_load_lds_dwordx4 v[220:221], off
	s_add_i32 m0, s0, 0x2000
	s_add_u32 s0, s28, 0x50080
	v_lshl_add_u64 v[220:221], v[222:223], 0, s[10:11]
	s_addc_u32 s1, s29, 0
	s_add_i32 s28, s63, s38
	global_load_lds_dwordx4 v[220:221], off
	v_lshl_add_u64 v[220:221], s[0:1], 0, v[164:165]
	s_mov_b32 m0, s28
	s_nop 0
	global_load_lds_dwordx4 v[220:221], off
	v_lshl_add_u64 v[220:221], s[0:1], 0, v[168:169]
	s_add_i32 m0, s28, 0x2000
	s_nop 0
	global_load_lds_dwordx4 v[220:221], off
	v_lshl_add_u64 v[220:221], v[224:225], 0, s[10:11]
	s_mov_b32 m0, s45
	s_nop 0
	global_load_lds_dwordx4 v[220:221], off
	v_lshl_add_u64 v[220:221], v[226:227], 0, s[10:11]
	s_mov_b32 m0, s46
	s_nop 0
	global_load_lds_dwordx4 v[220:221], off
	s_waitcnt vmcnt(8)
	s_waitcnt lgkmcnt(0)
	s_barrier
	s_waitcnt lgkmcnt(0)
	v_mfma_f32_16x16x32_bf16 v[60:63], v[128:131], v[178:181], v[60:63]
	v_mfma_f32_16x16x32_bf16 v[56:59], v[136:139], v[178:181], v[56:59]
	v_mfma_f32_16x16x32_bf16 v[44:47], v[128:131], v[196:199], v[44:47]
	v_mfma_f32_16x16x32_bf16 v[40:43], v[136:139], v[196:199], v[40:43]
	v_mfma_f32_16x16x32_bf16 v[28:31], v[128:131], v[204:207], v[28:31]
	v_mfma_f32_16x16x32_bf16 v[24:27], v[136:139], v[204:207], v[24:27]
	v_mfma_f32_16x16x32_bf16 v[12:15], v[128:131], v[212:215], v[12:15]
	v_mfma_f32_16x16x32_bf16 v[8:11], v[136:139], v[212:215], v[8:11]
	v_mfma_f32_16x16x32_bf16 v[60:63], v[132:135], v[192:195], v[60:63]
	v_mfma_f32_16x16x32_bf16 v[56:59], v[140:143], v[192:195], v[56:59]
	v_mfma_f32_16x16x32_bf16 v[44:47], v[132:135], v[200:203], v[44:47]
	v_mfma_f32_16x16x32_bf16 v[40:43], v[140:143], v[200:203], v[40:43]
	v_mfma_f32_16x16x32_bf16 v[28:31], v[132:135], v[208:211], v[28:31]
	v_mfma_f32_16x16x32_bf16 v[24:27], v[140:143], v[208:211], v[24:27]
	v_mfma_f32_16x16x32_bf16 v[12:15], v[132:135], v[216:219], v[12:15]
	v_mfma_f32_16x16x32_bf16 v[8:11], v[140:143], v[216:219], v[8:11]
	v_mfma_f32_16x16x32_bf16 v[52:55], v[144:147], v[178:181], v[52:55]
	v_mfma_f32_16x16x32_bf16 v[48:51], v[152:155], v[178:181], v[48:51]
	v_mfma_f32_16x16x32_bf16 v[36:39], v[144:147], v[196:199], v[36:39]
	v_mfma_f32_16x16x32_bf16 v[32:35], v[152:155], v[196:199], v[32:35]
	v_mfma_f32_16x16x32_bf16 v[20:23], v[144:147], v[204:207], v[20:23]
	v_mfma_f32_16x16x32_bf16 v[16:19], v[152:155], v[204:207], v[16:19]
	v_mfma_f32_16x16x32_bf16 v[4:7], v[144:147], v[212:215], v[4:7]
	v_mfma_f32_16x16x32_bf16 v[0:3], v[152:155], v[212:215], v[0:3]
	v_mfma_f32_16x16x32_bf16 v[52:55], v[148:151], v[192:195], v[52:55]
	v_mfma_f32_16x16x32_bf16 v[48:51], v[156:159], v[192:195], v[48:51]
	v_mfma_f32_16x16x32_bf16 v[36:39], v[148:151], v[200:203], v[36:39]
	v_mfma_f32_16x16x32_bf16 v[32:35], v[156:159], v[200:203], v[32:35]
	v_mfma_f32_16x16x32_bf16 v[20:23], v[148:151], v[208:211], v[20:23]
	v_mfma_f32_16x16x32_bf16 v[16:19], v[156:159], v[208:211], v[16:19]
	v_mfma_f32_16x16x32_bf16 v[4:7], v[148:151], v[216:219], v[4:7]
	v_mfma_f32_16x16x32_bf16 v[0:3], v[156:159], v[216:219], v[0:3]
	s_barrier
	s_add_i32 s61, s61, 2
	s_add_u32 s59, s59, 0x100
	s_addc_u32 s60, s60, 0
	s_cmp_gt_u32 s61, 17
	s_mov_b64 s[0:1], s[16:17]
	s_cbranch_scc0 .LBB0_551
	s_branch .Lpeel_exit_2
.LBB0_551:
	ds_read_b128 v[128:131], v188
	ds_read_b128 v[132:135], v188 offset:1024
	ds_read_b128 v[136:139], v188 offset:2048
	ds_read_b128 v[140:143], v188 offset:3072
	ds_read_b128 v[144:147], v189
	ds_read_b128 v[148:151], v189 offset:1024
	ds_read_b128 v[152:155], v189 offset:2048
	ds_read_b128 v[156:159], v189 offset:3072
	s_add_u32 s16, s0, 0x100
	s_addc_u32 s17, s1, 0
	s_cmp_eq_u32 s61, 16
	s_cselect_b32 s35, s7, s17
	s_cselect_b32 s34, s6, s16
	s_cselect_b32 s29, s15, s60
	s_cselect_b32 s28, s14, s59
	v_lshl_add_u64 v[220:221], s[0:1], 0, v[170:171]
	s_add_i32 m0, s39, 0xc000
	ds_read_b128 v[178:181], v190
	ds_read_b128 v[192:195], v190 offset:1024
	ds_read_b128 v[196:199], v190 offset:2048
	ds_read_b128 v[200:203], v190 offset:3072
	ds_read_b128 v[204:207], v190 offset:4096
	ds_read_b128 v[208:211], v190 offset:5120
	ds_read_b128 v[212:215], v190 offset:6144
	ds_read_b128 v[216:219], v190 offset:7168
	global_load_lds_dwordx4 v[220:221], off
	v_lshl_add_u64 v[220:221], s[0:1], 0, v[172:173]
	s_add_i32 m0, s39, 0xe000
	s_nop 0
	global_load_lds_dwordx4 v[220:221], off
	s_waitcnt vmcnt(8)
	s_waitcnt lgkmcnt(0)
	s_barrier
	s_waitcnt lgkmcnt(0)
	v_mfma_f32_16x16x32_bf16 v[124:127], v[128:131], v[178:181], v[124:127]
	v_mfma_f32_16x16x32_bf16 v[120:123], v[136:139], v[178:181], v[120:123]
	v_mfma_f32_16x16x32_bf16 v[108:111], v[128:131], v[196:199], v[108:111]
	v_mfma_f32_16x16x32_bf16 v[104:107], v[136:139], v[196:199], v[104:107]
	v_mfma_f32_16x16x32_bf16 v[92:95], v[128:131], v[204:207], v[92:95]
	v_mfma_f32_16x16x32_bf16 v[88:91], v[136:139], v[204:207], v[88:91]
	v_mfma_f32_16x16x32_bf16 v[76:79], v[128:131], v[212:215], v[76:79]
	v_mfma_f32_16x16x32_bf16 v[72:75], v[136:139], v[212:215], v[72:75]
	v_mfma_f32_16x16x32_bf16 v[124:127], v[132:135], v[192:195], v[124:127]
	v_mfma_f32_16x16x32_bf16 v[120:123], v[140:143], v[192:195], v[120:123]
	v_mfma_f32_16x16x32_bf16 v[108:111], v[132:135], v[200:203], v[108:111]
	v_mfma_f32_16x16x32_bf16 v[104:107], v[140:143], v[200:203], v[104:107]
	v_mfma_f32_16x16x32_bf16 v[92:95], v[132:135], v[208:211], v[92:95]
	v_mfma_f32_16x16x32_bf16 v[88:91], v[140:143], v[208:211], v[88:91]
	v_mfma_f32_16x16x32_bf16 v[76:79], v[132:135], v[216:219], v[76:79]
	v_mfma_f32_16x16x32_bf16 v[72:75], v[140:143], v[216:219], v[72:75]
	v_mfma_f32_16x16x32_bf16 v[116:119], v[144:147], v[178:181], v[116:119]
	v_mfma_f32_16x16x32_bf16 v[112:115], v[152:155], v[178:181], v[112:115]
	v_mfma_f32_16x16x32_bf16 v[100:103], v[144:147], v[196:199], v[100:103]
	v_mfma_f32_16x16x32_bf16 v[96:99], v[152:155], v[196:199], v[96:99]
	v_mfma_f32_16x16x32_bf16 v[84:87], v[144:147], v[204:207], v[84:87]
	v_mfma_f32_16x16x32_bf16 v[80:83], v[152:155], v[204:207], v[80:83]
	v_mfma_f32_16x16x32_bf16 v[68:71], v[144:147], v[212:215], v[68:71]
	v_mfma_f32_16x16x32_bf16 v[64:67], v[152:155], v[212:215], v[64:67]
	v_mfma_f32_16x16x32_bf16 v[116:119], v[148:151], v[192:195], v[116:119]
	v_mfma_f32_16x16x32_bf16 v[112:115], v[156:159], v[192:195], v[112:115]
	v_mfma_f32_16x16x32_bf16 v[100:103], v[148:151], v[200:203], v[100:103]
	v_mfma_f32_16x16x32_bf16 v[96:99], v[156:159], v[200:203], v[96:99]
	v_mfma_f32_16x16x32_bf16 v[84:87], v[148:151], v[208:211], v[84:87]
	v_mfma_f32_16x16x32_bf16 v[80:83], v[156:159], v[208:211], v[80:83]
	v_mfma_f32_16x16x32_bf16 v[68:71], v[148:151], v[216:219], v[68:71]
	v_mfma_f32_16x16x32_bf16 v[64:67], v[156:159], v[216:219], v[64:67]
	s_barrier
	s_add_i32 s0, s50, s38
	v_lshl_add_u64 v[220:221], s[28:29], 0, v[164:165]
	s_mov_b32 m0, s0
	ds_read_b128 v[178:181], v190 offset:16384
	ds_read_b128 v[192:195], v190 offset:17408
	ds_read_b128 v[196:199], v190 offset:18432
	ds_read_b128 v[200:203], v190 offset:19456
	ds_read_b128 v[204:207], v190 offset:20480
	ds_read_b128 v[208:211], v190 offset:21504
	ds_read_b128 v[212:215], v190 offset:22528
	ds_read_b128 v[216:219], v190 offset:23552
	global_load_lds_dwordx4 v[220:221], off
	s_add_i32 m0, s0, 0x2000
	s_add_u32 s0, s28, 0x50000
	v_lshl_add_u64 v[222:223], s[28:29], 0, v[168:169]
	s_addc_u32 s1, s29, 0
	s_add_i32 s62, s51, s38
	global_load_lds_dwordx4 v[222:223], off
	v_lshl_add_u64 v[224:225], s[0:1], 0, v[164:165]
	s_mov_b32 m0, s62
	v_lshl_add_u64 v[226:227], s[34:35], 0, v[166:167]
	global_load_lds_dwordx4 v[224:225], off
	v_lshl_add_u64 v[224:225], s[0:1], 0, v[168:169]
	s_add_i32 m0, s62, 0x2000
	s_nop 0
	global_load_lds_dwordx4 v[224:225], off
	v_lshl_add_u64 v[224:225], s[34:35], 0, v[162:163]
	s_mov_b32 m0, s39
	s_nop 0
	global_load_lds_dwordx4 v[224:225], off
	s_mov_b32 m0, s40
	s_nop 0
	global_load_lds_dwordx4 v[226:227], off
	s_waitcnt vmcnt(8)
	s_waitcnt lgkmcnt(0)
	s_barrier
	s_waitcnt lgkmcnt(0)
	v_mfma_f32_16x16x32_bf16 v[60:63], v[128:131], v[178:181], v[60:63]
	v_mfma_f32_16x16x32_bf16 v[56:59], v[136:139], v[178:181], v[56:59]
	v_mfma_f32_16x16x32_bf16 v[44:47], v[128:131], v[196:199], v[44:47]
	v_mfma_f32_16x16x32_bf16 v[40:43], v[136:139], v[196:199], v[40:43]
	v_mfma_f32_16x16x32_bf16 v[28:31], v[128:131], v[204:207], v[28:31]
	v_mfma_f32_16x16x32_bf16 v[24:27], v[136:139], v[204:207], v[24:27]
	v_mfma_f32_16x16x32_bf16 v[12:15], v[128:131], v[212:215], v[12:15]
	v_mfma_f32_16x16x32_bf16 v[8:11], v[136:139], v[212:215], v[8:11]
	v_mfma_f32_16x16x32_bf16 v[60:63], v[132:135], v[192:195], v[60:63]
	v_mfma_f32_16x16x32_bf16 v[56:59], v[140:143], v[192:195], v[56:59]
	v_mfma_f32_16x16x32_bf16 v[44:47], v[132:135], v[200:203], v[44:47]
	v_mfma_f32_16x16x32_bf16 v[40:43], v[140:143], v[200:203], v[40:43]
	v_mfma_f32_16x16x32_bf16 v[28:31], v[132:135], v[208:211], v[28:31]
	v_mfma_f32_16x16x32_bf16 v[24:27], v[140:143], v[208:211], v[24:27]
	v_mfma_f32_16x16x32_bf16 v[12:15], v[132:135], v[216:219], v[12:15]
	v_mfma_f32_16x16x32_bf16 v[8:11], v[140:143], v[216:219], v[8:11]
	v_mfma_f32_16x16x32_bf16 v[52:55], v[144:147], v[178:181], v[52:55]
	v_mfma_f32_16x16x32_bf16 v[48:51], v[152:155], v[178:181], v[48:51]
	v_mfma_f32_16x16x32_bf16 v[36:39], v[144:147], v[196:199], v[36:39]
	v_mfma_f32_16x16x32_bf16 v[32:35], v[152:155], v[196:199], v[32:35]
	v_mfma_f32_16x16x32_bf16 v[20:23], v[144:147], v[204:207], v[20:23]
	v_mfma_f32_16x16x32_bf16 v[16:19], v[152:155], v[204:207], v[16:19]
	v_mfma_f32_16x16x32_bf16 v[4:7], v[144:147], v[212:215], v[4:7]
	v_mfma_f32_16x16x32_bf16 v[0:3], v[152:155], v[212:215], v[0:3]
	v_mfma_f32_16x16x32_bf16 v[52:55], v[148:151], v[192:195], v[52:55]
	v_mfma_f32_16x16x32_bf16 v[48:51], v[156:159], v[192:195], v[48:51]
	v_mfma_f32_16x16x32_bf16 v[36:39], v[148:151], v[200:203], v[36:39]
	v_mfma_f32_16x16x32_bf16 v[32:35], v[156:159], v[200:203], v[32:35]
	v_mfma_f32_16x16x32_bf16 v[20:23], v[148:151], v[208:211], v[20:23]
	v_mfma_f32_16x16x32_bf16 v[16:19], v[156:159], v[208:211], v[16:19]
	v_mfma_f32_16x16x32_bf16 v[4:7], v[148:151], v[216:219], v[4:7]
	v_mfma_f32_16x16x32_bf16 v[0:3], v[156:159], v[216:219], v[0:3]
	s_barrier
	s_add_i32 s62, 0, 0x18000
	s_add_i32 s63, 0, 0x1c000
	v_add_u32_e32 v140, s62, v183
	v_add_u32_e32 v156, s63, v183
	ds_read_b128 v[128:131], v140
	ds_read_b128 v[132:135], v140 offset:1024
	ds_read_b128 v[136:139], v140 offset:2048
	ds_read_b128 v[140:143], v140 offset:3072
	ds_read_b128 v[144:147], v156
	ds_read_b128 v[148:151], v156 offset:1024
	ds_read_b128 v[152:155], v156 offset:2048
	ds_read_b128 v[156:159], v156 offset:3072
	s_add_u32 s0, s34, 0x50000
	s_addc_u32 s1, s35, 0
	s_mov_b32 m0, s41
	v_lshl_add_u64 v[228:229], s[0:1], 0, v[162:163]
	ds_read_b128 v[178:181], v190 offset:32768
	ds_read_b128 v[192:195], v190 offset:33792
	ds_read_b128 v[196:199], v190 offset:34816
	ds_read_b128 v[200:203], v190 offset:35840
	ds_read_b128 v[204:207], v190 offset:36864
	ds_read_b128 v[208:211], v190 offset:37888
	ds_read_b128 v[212:215], v190 offset:38912
	ds_read_b128 v[216:219], v190 offset:39936
	global_load_lds_dwordx4 v[228:229], off
	v_lshl_add_u64 v[228:229], s[0:1], 0, v[166:167]
	s_mov_b32 m0, s42
	s_nop 0
	global_load_lds_dwordx4 v[228:229], off
	s_waitcnt vmcnt(8)
	s_waitcnt lgkmcnt(0)
	s_barrier
	s_waitcnt lgkmcnt(0)
	v_mfma_f32_16x16x32_bf16 v[124:127], v[128:131], v[178:181], v[124:127]
	v_mfma_f32_16x16x32_bf16 v[120:123], v[136:139], v[178:181], v[120:123]
	v_mfma_f32_16x16x32_bf16 v[108:111], v[128:131], v[196:199], v[108:111]
	v_mfma_f32_16x16x32_bf16 v[104:107], v[136:139], v[196:199], v[104:107]
	v_mfma_f32_16x16x32_bf16 v[92:95], v[128:131], v[204:207], v[92:95]
	v_mfma_f32_16x16x32_bf16 v[88:91], v[136:139], v[204:207], v[88:91]
	v_mfma_f32_16x16x32_bf16 v[76:79], v[128:131], v[212:215], v[76:79]
	v_mfma_f32_16x16x32_bf16 v[72:75], v[136:139], v[212:215], v[72:75]
	v_mfma_f32_16x16x32_bf16 v[124:127], v[132:135], v[192:195], v[124:127]
	v_mfma_f32_16x16x32_bf16 v[120:123], v[140:143], v[192:195], v[120:123]
	v_mfma_f32_16x16x32_bf16 v[108:111], v[132:135], v[200:203], v[108:111]
	v_mfma_f32_16x16x32_bf16 v[104:107], v[140:143], v[200:203], v[104:107]
	v_mfma_f32_16x16x32_bf16 v[92:95], v[132:135], v[208:211], v[92:95]
	v_mfma_f32_16x16x32_bf16 v[88:91], v[140:143], v[208:211], v[88:91]
	v_mfma_f32_16x16x32_bf16 v[76:79], v[132:135], v[216:219], v[76:79]
	v_mfma_f32_16x16x32_bf16 v[72:75], v[140:143], v[216:219], v[72:75]
	v_mfma_f32_16x16x32_bf16 v[116:119], v[144:147], v[178:181], v[116:119]
	v_mfma_f32_16x16x32_bf16 v[112:115], v[152:155], v[178:181], v[112:115]
	v_mfma_f32_16x16x32_bf16 v[100:103], v[144:147], v[196:199], v[100:103]
	v_mfma_f32_16x16x32_bf16 v[96:99], v[152:155], v[196:199], v[96:99]
	v_mfma_f32_16x16x32_bf16 v[84:87], v[144:147], v[204:207], v[84:87]
	v_mfma_f32_16x16x32_bf16 v[80:83], v[152:155], v[204:207], v[80:83]
	v_mfma_f32_16x16x32_bf16 v[68:71], v[144:147], v[212:215], v[68:71]
	v_mfma_f32_16x16x32_bf16 v[64:67], v[152:155], v[212:215], v[64:67]
	v_mfma_f32_16x16x32_bf16 v[116:119], v[148:151], v[192:195], v[116:119]
	v_mfma_f32_16x16x32_bf16 v[112:115], v[156:159], v[192:195], v[112:115]
	v_mfma_f32_16x16x32_bf16 v[100:103], v[148:151], v[200:203], v[100:103]
	v_mfma_f32_16x16x32_bf16 v[96:99], v[156:159], v[200:203], v[96:99]
	v_mfma_f32_16x16x32_bf16 v[84:87], v[148:151], v[208:211], v[84:87]
	v_mfma_f32_16x16x32_bf16 v[80:83], v[156:159], v[208:211], v[80:83]
	v_mfma_f32_16x16x32_bf16 v[68:71], v[148:151], v[216:219], v[68:71]
	v_mfma_f32_16x16x32_bf16 v[64:67], v[156:159], v[216:219], v[64:67]
	s_barrier
	s_add_i32 s0, s62, s38
	v_lshl_add_u64 v[220:221], v[220:221], 0, s[10:11]
	s_mov_b32 m0, s0
	ds_read_b128 v[178:181], v190 offset:49152
	ds_read_b128 v[192:195], v190 offset:50176
	ds_read_b128 v[196:199], v190 offset:51200
	ds_read_b128 v[200:203], v190 offset:52224
	ds_read_b128 v[204:207], v190 offset:53248
	ds_read_b128 v[208:211], v190 offset:54272
	ds_read_b128 v[212:215], v190 offset:55296
	ds_read_b128 v[216:219], v190 offset:56320
	global_load_lds_dwordx4 v[220:221], off
	s_add_i32 m0, s0, 0x2000
	s_add_u32 s0, s28, 0x50080
	v_lshl_add_u64 v[220:221], v[222:223], 0, s[10:11]
	s_addc_u32 s1, s29, 0
	s_add_i32 s28, s63, s38
	global_load_lds_dwordx4 v[220:221], off
	v_lshl_add_u64 v[220:221], s[0:1], 0, v[164:165]
	s_mov_b32 m0, s28
	s_nop 0
	global_load_lds_dwordx4 v[220:221], off
	v_lshl_add_u64 v[220:221], s[0:1], 0, v[168:169]
	s_add_i32 m0, s28, 0x2000
	s_nop 0
	global_load_lds_dwordx4 v[220:221], off
	v_lshl_add_u64 v[220:221], v[224:225], 0, s[10:11]
	s_mov_b32 m0, s45
	s_nop 0
	global_load_lds_dwordx4 v[220:221], off
	v_lshl_add_u64 v[220:221], v[226:227], 0, s[10:11]
	s_mov_b32 m0, s46
	s_nop 0
	global_load_lds_dwordx4 v[220:221], off
	s_waitcnt vmcnt(8)
	s_waitcnt lgkmcnt(0)
	s_barrier
	s_waitcnt lgkmcnt(0)
	v_mfma_f32_16x16x32_bf16 v[60:63], v[128:131], v[178:181], v[60:63]
	v_mfma_f32_16x16x32_bf16 v[56:59], v[136:139], v[178:181], v[56:59]
	v_mfma_f32_16x16x32_bf16 v[44:47], v[128:131], v[196:199], v[44:47]
	v_mfma_f32_16x16x32_bf16 v[40:43], v[136:139], v[196:199], v[40:43]
	v_mfma_f32_16x16x32_bf16 v[28:31], v[128:131], v[204:207], v[28:31]
	v_mfma_f32_16x16x32_bf16 v[24:27], v[136:139], v[204:207], v[24:27]
	v_mfma_f32_16x16x32_bf16 v[12:15], v[128:131], v[212:215], v[12:15]
	v_mfma_f32_16x16x32_bf16 v[8:11], v[136:139], v[212:215], v[8:11]
	v_mfma_f32_16x16x32_bf16 v[60:63], v[132:135], v[192:195], v[60:63]
	v_mfma_f32_16x16x32_bf16 v[56:59], v[140:143], v[192:195], v[56:59]
	v_mfma_f32_16x16x32_bf16 v[44:47], v[132:135], v[200:203], v[44:47]
	v_mfma_f32_16x16x32_bf16 v[40:43], v[140:143], v[200:203], v[40:43]
	v_mfma_f32_16x16x32_bf16 v[28:31], v[132:135], v[208:211], v[28:31]
	v_mfma_f32_16x16x32_bf16 v[24:27], v[140:143], v[208:211], v[24:27]
	v_mfma_f32_16x16x32_bf16 v[12:15], v[132:135], v[216:219], v[12:15]
	v_mfma_f32_16x16x32_bf16 v[8:11], v[140:143], v[216:219], v[8:11]
	v_mfma_f32_16x16x32_bf16 v[52:55], v[144:147], v[178:181], v[52:55]
	v_mfma_f32_16x16x32_bf16 v[48:51], v[152:155], v[178:181], v[48:51]
	v_mfma_f32_16x16x32_bf16 v[36:39], v[144:147], v[196:199], v[36:39]
	v_mfma_f32_16x16x32_bf16 v[32:35], v[152:155], v[196:199], v[32:35]
	v_mfma_f32_16x16x32_bf16 v[20:23], v[144:147], v[204:207], v[20:23]
	v_mfma_f32_16x16x32_bf16 v[16:19], v[152:155], v[204:207], v[16:19]
	v_mfma_f32_16x16x32_bf16 v[4:7], v[144:147], v[212:215], v[4:7]
	v_mfma_f32_16x16x32_bf16 v[0:3], v[152:155], v[212:215], v[0:3]
	v_mfma_f32_16x16x32_bf16 v[52:55], v[148:151], v[192:195], v[52:55]
	v_mfma_f32_16x16x32_bf16 v[48:51], v[156:159], v[192:195], v[48:51]
	v_mfma_f32_16x16x32_bf16 v[36:39], v[148:151], v[200:203], v[36:39]
	v_mfma_f32_16x16x32_bf16 v[32:35], v[156:159], v[200:203], v[32:35]
	v_mfma_f32_16x16x32_bf16 v[20:23], v[148:151], v[208:211], v[20:23]
	v_mfma_f32_16x16x32_bf16 v[16:19], v[156:159], v[208:211], v[16:19]
	v_mfma_f32_16x16x32_bf16 v[4:7], v[148:151], v[216:219], v[4:7]
	v_mfma_f32_16x16x32_bf16 v[0:3], v[156:159], v[216:219], v[0:3]
	s_barrier
	s_add_i32 s61, s61, 2
	s_add_u32 s59, s59, 0x100
	s_addc_u32 s60, s60, 0
	s_cmp_gt_u32 s61, 17
	s_mov_b64 s[0:1], s[16:17]
	s_cbranch_scc0 .LBB0_551

.LBB0_635:
	s_ashr_i32 s13, s12, 31
	s_lshl_b64 s[14:15], s[12:13], 19
	s_add_u32 s14, s64, s14
	s_addc_u32 s15, s65, s15
	s_and_b64 s[16:17], s[2:3], exec
	s_cselect_b32 s13, s15, s1
	s_cselect_b32 s48, s14, s0
	s_ashr_i32 s11, s10, 31
	s_lshl_b64 s[16:17], s[10:11], 19
	s_add_u32 s16, s36, s16
	s_addc_u32 s17, s37, s17
	s_and_b64 s[34:35], s[2:3], exec
	s_cselect_b32 s11, s17, s31
	s_cselect_b32 s49, s16, s30
	s_add_u32 s0, s0, 0x40080
	s_addc_u32 s1, s1, 0
	s_add_u32 s50, s30, 0x100
	s_addc_u32 s51, s31, 0
	s_mov_b32 s52, -2
	v_lshl_add_u32 v248, s28, 8, v156
	v_ashrrev_i32_e32 v249, 31, v248
	v_lshl_add_u64 v[248:249], v[248:249], 2, s[26:27]
	global_load_dword v240, v[248:249], off
	global_load_dword v241, v[248:249], off offset:64
	global_load_dword v242, v[248:249], off offset:128
	global_load_dword v243, v[248:249], off offset:192
	global_load_dword v244, v[248:249], off offset:512
	global_load_dword v245, v[248:249], off offset:576
	global_load_dword v246, v[248:249], off offset:640
	global_load_dword v247, v[248:249], off offset:704
	ds_read_b128 v[144:147], v159
	ds_read_b128 v[148:151], v159 offset:1024
	ds_read_b128 v[152:155], v159 offset:2048
	ds_read_b128 v[166:169], v159 offset:3072
	ds_read_b128 v[170:173], v162
	ds_read_b128 v[174:177], v162 offset:1024
	ds_read_b128 v[178:181], v162 offset:2048
	ds_read_b128 v[182:185], v162 offset:3072
	s_add_u32 s30, s0, 0xfffc0080
	s_addc_u32 s31, s1, -1
	s_cmp_eq_u32 s52, 12
	s_cselect_b32 s35, s13, s31
	s_cselect_b32 s34, s48, s30
	s_cselect_b32 s31, s11, s51
	s_cselect_b32 s30, s49, s50
	v_lshl_add_u64 v[218:219], s[0:1], 0, v[136:137]
	s_add_i32 m0, s29, 0xc000
	ds_read_b128 v[186:189], v163
	ds_read_b128 v[190:193], v163 offset:1024
	ds_read_b128 v[194:197], v163 offset:2048
	ds_read_b128 v[198:201], v163 offset:3072
	ds_read_b128 v[202:205], v163 offset:4096
	ds_read_b128 v[206:209], v163 offset:5120
	ds_read_b128 v[210:213], v163 offset:6144
	ds_read_b128 v[214:217], v163 offset:7168
	global_load_lds_dwordx4 v[218:219], off
	v_lshl_add_u64 v[218:219], s[0:1], 0, v[138:139]
	s_add_i32 m0, s29, 0xe000
	s_nop 0
	global_load_lds_dwordx4 v[218:219], off
	s_waitcnt vmcnt(8)
	s_waitcnt lgkmcnt(0)
	s_barrier
	s_waitcnt lgkmcnt(0)
	v_mfma_f32_16x16x32_bf16 v[124:127], v[144:147], v[186:189], 0
	v_mfma_f32_16x16x32_bf16 v[120:123], v[152:155], v[186:189], 0
	v_mfma_f32_16x16x32_bf16 v[116:119], v[144:147], v[194:197], 0
	v_mfma_f32_16x16x32_bf16 v[104:107], v[152:155], v[194:197], 0
	v_mfma_f32_16x16x32_bf16 v[92:95], v[144:147], v[202:205], 0
	v_mfma_f32_16x16x32_bf16 v[88:91], v[152:155], v[202:205], 0
	v_mfma_f32_16x16x32_bf16 v[76:79], v[144:147], v[210:213], 0
	v_mfma_f32_16x16x32_bf16 v[72:75], v[152:155], v[210:213], 0
	v_mfma_f32_16x16x32_bf16 v[124:127], v[148:151], v[190:193], v[124:127]
	v_mfma_f32_16x16x32_bf16 v[120:123], v[166:169], v[190:193], v[120:123]
	v_mfma_f32_16x16x32_bf16 v[116:119], v[148:151], v[198:201], v[116:119]
	v_mfma_f32_16x16x32_bf16 v[104:107], v[166:169], v[198:201], v[104:107]
	v_mfma_f32_16x16x32_bf16 v[92:95], v[148:151], v[206:209], v[92:95]
	v_mfma_f32_16x16x32_bf16 v[88:91], v[166:169], v[206:209], v[88:91]
	v_mfma_f32_16x16x32_bf16 v[76:79], v[148:151], v[214:217], v[76:79]
	v_mfma_f32_16x16x32_bf16 v[72:75], v[166:169], v[214:217], v[72:75]
	v_mfma_f32_16x16x32_bf16 v[112:115], v[170:173], v[186:189], 0
	v_mfma_f32_16x16x32_bf16 v[108:111], v[178:181], v[186:189], 0
	v_mfma_f32_16x16x32_bf16 v[100:103], v[170:173], v[194:197], 0
	v_mfma_f32_16x16x32_bf16 v[96:99], v[178:181], v[194:197], 0
	v_mfma_f32_16x16x32_bf16 v[84:87], v[170:173], v[202:205], 0
	v_mfma_f32_16x16x32_bf16 v[80:83], v[178:181], v[202:205], 0
	v_mfma_f32_16x16x32_bf16 v[68:71], v[170:173], v[210:213], 0
	v_mfma_f32_16x16x32_bf16 v[64:67], v[178:181], v[210:213], 0
	v_mfma_f32_16x16x32_bf16 v[112:115], v[174:177], v[190:193], v[112:115]
	v_mfma_f32_16x16x32_bf16 v[108:111], v[182:185], v[190:193], v[108:111]
	v_mfma_f32_16x16x32_bf16 v[100:103], v[174:177], v[198:201], v[100:103]
	v_mfma_f32_16x16x32_bf16 v[96:99], v[182:185], v[198:201], v[96:99]
	v_mfma_f32_16x16x32_bf16 v[84:87], v[174:177], v[206:209], v[84:87]
	v_mfma_f32_16x16x32_bf16 v[80:83], v[182:185], v[206:209], v[80:83]
	v_mfma_f32_16x16x32_bf16 v[68:71], v[174:177], v[214:217], v[68:71]
	v_mfma_f32_16x16x32_bf16 v[64:67], v[182:185], v[214:217], v[64:67]
	s_barrier
	s_add_i32 s53, s46, s38
	v_lshl_add_u64 v[218:219], s[30:31], 0, v[132:133]
	s_mov_b32 m0, s53
	ds_read_b128 v[186:189], v163 offset:16384
	ds_read_b128 v[190:193], v163 offset:17408
	ds_read_b128 v[194:197], v163 offset:18432
	ds_read_b128 v[198:201], v163 offset:19456
	ds_read_b128 v[202:205], v163 offset:20480
	ds_read_b128 v[206:209], v163 offset:21504
	ds_read_b128 v[210:213], v163 offset:22528
	ds_read_b128 v[214:217], v163 offset:23552
	global_load_lds_dwordx4 v[218:219], off
	s_add_i32 m0, s53, 0x2000
	s_add_u32 s54, s30, 0x40000
	v_lshl_add_u64 v[220:221], s[30:31], 0, v[128:129]
	s_addc_u32 s55, s31, 0
	s_add_i32 s53, s47, s38
	global_load_lds_dwordx4 v[220:221], off
	v_lshl_add_u64 v[222:223], s[54:55], 0, v[132:133]
	s_mov_b32 m0, s53
	v_lshl_add_u64 v[224:225], s[34:35], 0, v[130:131]
	global_load_lds_dwordx4 v[222:223], off
	v_lshl_add_u64 v[222:223], s[54:55], 0, v[128:129]
	s_add_i32 m0, s53, 0x2000
	s_nop 0
	global_load_lds_dwordx4 v[222:223], off
	v_lshl_add_u64 v[222:223], s[34:35], 0, v[134:135]
	s_mov_b32 m0, s29
	s_nop 0
	global_load_lds_dwordx4 v[222:223], off
	s_mov_b32 m0, s40
	s_nop 0
	global_load_lds_dwordx4 v[224:225], off
	s_waitcnt vmcnt(8)
	s_waitcnt lgkmcnt(0)
	s_barrier
	s_waitcnt lgkmcnt(0)
	v_mfma_f32_16x16x32_bf16 v[60:63], v[144:147], v[186:189], 0
	v_mfma_f32_16x16x32_bf16 v[56:59], v[152:155], v[186:189], 0
	v_mfma_f32_16x16x32_bf16 v[44:47], v[144:147], v[194:197], 0
	v_mfma_f32_16x16x32_bf16 v[40:43], v[152:155], v[194:197], 0
	v_mfma_f32_16x16x32_bf16 v[28:31], v[144:147], v[202:205], 0
	v_mfma_f32_16x16x32_bf16 v[24:27], v[152:155], v[202:205], 0
	v_mfma_f32_16x16x32_bf16 v[12:15], v[144:147], v[210:213], 0
	v_mfma_f32_16x16x32_bf16 v[8:11], v[152:155], v[210:213], 0
	v_mfma_f32_16x16x32_bf16 v[60:63], v[148:151], v[190:193], v[60:63]
	v_mfma_f32_16x16x32_bf16 v[56:59], v[166:169], v[190:193], v[56:59]
	v_mfma_f32_16x16x32_bf16 v[44:47], v[148:151], v[198:201], v[44:47]
	v_mfma_f32_16x16x32_bf16 v[40:43], v[166:169], v[198:201], v[40:43]
	v_mfma_f32_16x16x32_bf16 v[28:31], v[148:151], v[206:209], v[28:31]
	v_mfma_f32_16x16x32_bf16 v[24:27], v[166:169], v[206:209], v[24:27]
	v_mfma_f32_16x16x32_bf16 v[12:15], v[148:151], v[214:217], v[12:15]
	v_mfma_f32_16x16x32_bf16 v[8:11], v[166:169], v[214:217], v[8:11]
	v_mfma_f32_16x16x32_bf16 v[52:55], v[170:173], v[186:189], 0
	v_mfma_f32_16x16x32_bf16 v[48:51], v[178:181], v[186:189], 0
	v_mfma_f32_16x16x32_bf16 v[36:39], v[170:173], v[194:197], 0
	v_mfma_f32_16x16x32_bf16 v[32:35], v[178:181], v[194:197], 0
	v_mfma_f32_16x16x32_bf16 v[20:23], v[170:173], v[202:205], 0
	v_mfma_f32_16x16x32_bf16 v[16:19], v[178:181], v[202:205], 0
	v_mfma_f32_16x16x32_bf16 v[4:7], v[170:173], v[210:213], 0
	v_mfma_f32_16x16x32_bf16 v[0:3], v[178:181], v[210:213], 0
	v_mfma_f32_16x16x32_bf16 v[52:55], v[174:177], v[190:193], v[52:55]
	v_mfma_f32_16x16x32_bf16 v[48:51], v[182:185], v[190:193], v[48:51]
	v_mfma_f32_16x16x32_bf16 v[36:39], v[174:177], v[198:201], v[36:39]
	v_mfma_f32_16x16x32_bf16 v[32:35], v[182:185], v[198:201], v[32:35]
	v_mfma_f32_16x16x32_bf16 v[20:23], v[174:177], v[206:209], v[20:23]
	v_mfma_f32_16x16x32_bf16 v[16:19], v[182:185], v[206:209], v[16:19]
	v_mfma_f32_16x16x32_bf16 v[4:7], v[174:177], v[214:217], v[4:7]
	v_mfma_f32_16x16x32_bf16 v[0:3], v[182:185], v[214:217], v[0:3]
	s_barrier
	s_add_i32 s53, 0, 0x18000
	v_add_u32_e32 v165, s53, v157
	s_add_i32 s54, 0, 0x1c000
	ds_read_b128 v[144:147], v165
	ds_read_b128 v[148:151], v165 offset:1024
	ds_read_b128 v[152:155], v165 offset:2048
	ds_read_b128 v[166:169], v165 offset:3072
	v_add_u32_e32 v165, s54, v157
	ds_read_b128 v[170:173], v165
	ds_read_b128 v[174:177], v165 offset:1024
	ds_read_b128 v[178:181], v165 offset:2048
	ds_read_b128 v[182:185], v165 offset:3072
	s_add_u32 s34, s34, 0x40000
	s_addc_u32 s35, s35, 0
	s_mov_b32 m0, s41
	v_lshl_add_u64 v[226:227], s[34:35], 0, v[134:135]
	ds_read_b128 v[186:189], v163 offset:32768
	ds_read_b128 v[190:193], v163 offset:33792
	ds_read_b128 v[194:197], v163 offset:34816
	ds_read_b128 v[198:201], v163 offset:35840
	ds_read_b128 v[202:205], v163 offset:36864
	ds_read_b128 v[206:209], v163 offset:37888
	ds_read_b128 v[210:213], v163 offset:38912
	ds_read_b128 v[214:217], v163 offset:39936
	global_load_lds_dwordx4 v[226:227], off
	v_lshl_add_u64 v[226:227], s[34:35], 0, v[130:131]
	s_mov_b32 m0, s42
	s_nop 0
	global_load_lds_dwordx4 v[226:227], off
	s_waitcnt vmcnt(8)
	s_waitcnt lgkmcnt(0)
	s_barrier
	s_waitcnt lgkmcnt(0)
	v_mfma_f32_16x16x32_bf16 v[124:127], v[144:147], v[186:189], v[124:127]
	v_mfma_f32_16x16x32_bf16 v[120:123], v[152:155], v[186:189], v[120:123]
	v_mfma_f32_16x16x32_bf16 v[116:119], v[144:147], v[194:197], v[116:119]
	v_mfma_f32_16x16x32_bf16 v[104:107], v[152:155], v[194:197], v[104:107]
	v_mfma_f32_16x16x32_bf16 v[92:95], v[144:147], v[202:205], v[92:95]
	v_mfma_f32_16x16x32_bf16 v[88:91], v[152:155], v[202:205], v[88:91]
	v_mfma_f32_16x16x32_bf16 v[76:79], v[144:147], v[210:213], v[76:79]
	v_mfma_f32_16x16x32_bf16 v[72:75], v[152:155], v[210:213], v[72:75]
	v_mfma_f32_16x16x32_bf16 v[124:127], v[148:151], v[190:193], v[124:127]
	v_mfma_f32_16x16x32_bf16 v[120:123], v[166:169], v[190:193], v[120:123]
	v_mfma_f32_16x16x32_bf16 v[116:119], v[148:151], v[198:201], v[116:119]
	v_mfma_f32_16x16x32_bf16 v[104:107], v[166:169], v[198:201], v[104:107]
	v_mfma_f32_16x16x32_bf16 v[92:95], v[148:151], v[206:209], v[92:95]
	v_mfma_f32_16x16x32_bf16 v[88:91], v[166:169], v[206:209], v[88:91]
	v_mfma_f32_16x16x32_bf16 v[76:79], v[148:151], v[214:217], v[76:79]
	v_mfma_f32_16x16x32_bf16 v[72:75], v[166:169], v[214:217], v[72:75]
	v_mfma_f32_16x16x32_bf16 v[112:115], v[170:173], v[186:189], v[112:115]
	v_mfma_f32_16x16x32_bf16 v[108:111], v[178:181], v[186:189], v[108:111]
	v_mfma_f32_16x16x32_bf16 v[100:103], v[170:173], v[194:197], v[100:103]
	v_mfma_f32_16x16x32_bf16 v[96:99], v[178:181], v[194:197], v[96:99]
	v_mfma_f32_16x16x32_bf16 v[84:87], v[170:173], v[202:205], v[84:87]
	v_mfma_f32_16x16x32_bf16 v[80:83], v[178:181], v[202:205], v[80:83]
	v_mfma_f32_16x16x32_bf16 v[68:71], v[170:173], v[210:213], v[68:71]
	v_mfma_f32_16x16x32_bf16 v[64:67], v[178:181], v[210:213], v[64:67]
	v_mfma_f32_16x16x32_bf16 v[112:115], v[174:177], v[190:193], v[112:115]
	v_mfma_f32_16x16x32_bf16 v[108:111], v[182:185], v[190:193], v[108:111]
	v_mfma_f32_16x16x32_bf16 v[100:103], v[174:177], v[198:201], v[100:103]
	v_mfma_f32_16x16x32_bf16 v[96:99], v[182:185], v[198:201], v[96:99]
	v_mfma_f32_16x16x32_bf16 v[84:87], v[174:177], v[206:209], v[84:87]
	v_mfma_f32_16x16x32_bf16 v[80:83], v[182:185], v[206:209], v[80:83]
	v_mfma_f32_16x16x32_bf16 v[68:71], v[174:177], v[214:217], v[68:71]
	v_mfma_f32_16x16x32_bf16 v[64:67], v[182:185], v[214:217], v[64:67]
	s_barrier
	s_add_i32 s34, s53, s38
	v_lshl_add_u64 v[218:219], v[218:219], 0, s[6:7]
	s_mov_b32 m0, s34
	ds_read_b128 v[186:189], v163 offset:49152
	ds_read_b128 v[190:193], v163 offset:50176
	ds_read_b128 v[194:197], v163 offset:51200
	ds_read_b128 v[198:201], v163 offset:52224
	ds_read_b128 v[202:205], v163 offset:53248
	ds_read_b128 v[206:209], v163 offset:54272
	ds_read_b128 v[210:213], v163 offset:55296
	ds_read_b128 v[214:217], v163 offset:56320
	global_load_lds_dwordx4 v[218:219], off
	s_add_i32 m0, s34, 0x2000
	s_add_u32 s30, s30, 0x40080
	v_lshl_add_u64 v[218:219], v[220:221], 0, s[6:7]
	s_addc_u32 s31, s31, 0
	s_add_i32 s34, s54, s38
	global_load_lds_dwordx4 v[218:219], off
	v_lshl_add_u64 v[218:219], s[30:31], 0, v[132:133]
	s_mov_b32 m0, s34
	s_nop 0
	global_load_lds_dwordx4 v[218:219], off
	v_lshl_add_u64 v[218:219], s[30:31], 0, v[128:129]
	s_add_i32 m0, s34, 0x2000
	s_nop 0
	global_load_lds_dwordx4 v[218:219], off
	v_lshl_add_u64 v[218:219], v[222:223], 0, s[6:7]
	s_mov_b32 m0, s44
	s_nop 0
	global_load_lds_dwordx4 v[218:219], off
	v_lshl_add_u64 v[218:219], v[224:225], 0, s[6:7]
	s_mov_b32 m0, s45
	s_nop 0
	global_load_lds_dwordx4 v[218:219], off
	s_waitcnt vmcnt(8)
	s_waitcnt lgkmcnt(0)
	s_barrier
	s_waitcnt lgkmcnt(0)
	v_mfma_f32_16x16x32_bf16 v[60:63], v[144:147], v[186:189], v[60:63]
	v_mfma_f32_16x16x32_bf16 v[56:59], v[152:155], v[186:189], v[56:59]
	v_mfma_f32_16x16x32_bf16 v[44:47], v[144:147], v[194:197], v[44:47]
	v_mfma_f32_16x16x32_bf16 v[40:43], v[152:155], v[194:197], v[40:43]
	v_mfma_f32_16x16x32_bf16 v[28:31], v[144:147], v[202:205], v[28:31]
	v_mfma_f32_16x16x32_bf16 v[24:27], v[152:155], v[202:205], v[24:27]
	v_mfma_f32_16x16x32_bf16 v[12:15], v[144:147], v[210:213], v[12:15]
	v_mfma_f32_16x16x32_bf16 v[8:11], v[152:155], v[210:213], v[8:11]
	v_mfma_f32_16x16x32_bf16 v[60:63], v[148:151], v[190:193], v[60:63]
	v_mfma_f32_16x16x32_bf16 v[56:59], v[166:169], v[190:193], v[56:59]
	v_mfma_f32_16x16x32_bf16 v[44:47], v[148:151], v[198:201], v[44:47]
	v_mfma_f32_16x16x32_bf16 v[40:43], v[166:169], v[198:201], v[40:43]
	v_mfma_f32_16x16x32_bf16 v[28:31], v[148:151], v[206:209], v[28:31]
	v_mfma_f32_16x16x32_bf16 v[24:27], v[166:169], v[206:209], v[24:27]
	v_mfma_f32_16x16x32_bf16 v[12:15], v[148:151], v[214:217], v[12:15]
	v_mfma_f32_16x16x32_bf16 v[8:11], v[166:169], v[214:217], v[8:11]
	v_mfma_f32_16x16x32_bf16 v[52:55], v[170:173], v[186:189], v[52:55]
	v_mfma_f32_16x16x32_bf16 v[48:51], v[178:181], v[186:189], v[48:51]
	v_mfma_f32_16x16x32_bf16 v[36:39], v[170:173], v[194:197], v[36:39]
	v_mfma_f32_16x16x32_bf16 v[32:35], v[178:181], v[194:197], v[32:35]
	v_mfma_f32_16x16x32_bf16 v[20:23], v[170:173], v[202:205], v[20:23]
	v_mfma_f32_16x16x32_bf16 v[16:19], v[178:181], v[202:205], v[16:19]
	v_mfma_f32_16x16x32_bf16 v[4:7], v[170:173], v[210:213], v[4:7]
	v_mfma_f32_16x16x32_bf16 v[0:3], v[178:181], v[210:213], v[0:3]
	v_mfma_f32_16x16x32_bf16 v[52:55], v[174:177], v[190:193], v[52:55]
	v_mfma_f32_16x16x32_bf16 v[48:51], v[182:185], v[190:193], v[48:51]
	v_mfma_f32_16x16x32_bf16 v[36:39], v[174:177], v[198:201], v[36:39]
	v_mfma_f32_16x16x32_bf16 v[32:35], v[182:185], v[198:201], v[32:35]
	v_mfma_f32_16x16x32_bf16 v[20:23], v[174:177], v[206:209], v[20:23]
	v_mfma_f32_16x16x32_bf16 v[16:19], v[182:185], v[206:209], v[16:19]
	v_mfma_f32_16x16x32_bf16 v[4:7], v[174:177], v[214:217], v[4:7]
	v_mfma_f32_16x16x32_bf16 v[0:3], v[182:185], v[214:217], v[0:3]
	s_barrier
	s_add_i32 s52, s52, 2
	s_add_u32 s0, s0, 0x100
	s_addc_u32 s1, s1, 0
	s_add_u32 s50, s50, 0x100
	s_addc_u32 s51, s51, 0
	s_cmp_gt_u32 s52, 13
	s_cbranch_scc0 .LBB0_636
	s_branch .Lpeel_exit_3
.LBB0_636:
	ds_read_b128 v[144:147], v159
	ds_read_b128 v[148:151], v159 offset:1024
	ds_read_b128 v[152:155], v159 offset:2048
	ds_read_b128 v[166:169], v159 offset:3072
	ds_read_b128 v[170:173], v162
	ds_read_b128 v[174:177], v162 offset:1024
	ds_read_b128 v[178:181], v162 offset:2048
	ds_read_b128 v[182:185], v162 offset:3072
	s_add_u32 s30, s0, 0xfffc0080
	s_addc_u32 s31, s1, -1
	s_cmp_eq_u32 s52, 12
	s_cselect_b32 s35, s13, s31
	s_cselect_b32 s34, s48, s30
	s_cselect_b32 s31, s11, s51
	s_cselect_b32 s30, s49, s50
	v_lshl_add_u64 v[218:219], s[0:1], 0, v[136:137]
	s_add_i32 m0, s29, 0xc000
	ds_read_b128 v[186:189], v163
	ds_read_b128 v[190:193], v163 offset:1024
	ds_read_b128 v[194:197], v163 offset:2048
	ds_read_b128 v[198:201], v163 offset:3072
	ds_read_b128 v[202:205], v163 offset:4096
	ds_read_b128 v[206:209], v163 offset:5120
	ds_read_b128 v[210:213], v163 offset:6144
	ds_read_b128 v[214:217], v163 offset:7168
	global_load_lds_dwordx4 v[218:219], off
	v_lshl_add_u64 v[218:219], s[0:1], 0, v[138:139]
	s_add_i32 m0, s29, 0xe000
	s_nop 0
	global_load_lds_dwordx4 v[218:219], off
	s_waitcnt vmcnt(8)
	s_waitcnt lgkmcnt(0)
	s_barrier
	s_waitcnt lgkmcnt(0)
	v_mfma_f32_16x16x32_bf16 v[124:127], v[144:147], v[186:189], v[124:127]
	v_mfma_f32_16x16x32_bf16 v[120:123], v[152:155], v[186:189], v[120:123]
	v_mfma_f32_16x16x32_bf16 v[116:119], v[144:147], v[194:197], v[116:119]
	v_mfma_f32_16x16x32_bf16 v[104:107], v[152:155], v[194:197], v[104:107]
	v_mfma_f32_16x16x32_bf16 v[92:95], v[144:147], v[202:205], v[92:95]
	v_mfma_f32_16x16x32_bf16 v[88:91], v[152:155], v[202:205], v[88:91]
	v_mfma_f32_16x16x32_bf16 v[76:79], v[144:147], v[210:213], v[76:79]
	v_mfma_f32_16x16x32_bf16 v[72:75], v[152:155], v[210:213], v[72:75]
	v_mfma_f32_16x16x32_bf16 v[124:127], v[148:151], v[190:193], v[124:127]
	v_mfma_f32_16x16x32_bf16 v[120:123], v[166:169], v[190:193], v[120:123]
	v_mfma_f32_16x16x32_bf16 v[116:119], v[148:151], v[198:201], v[116:119]
	v_mfma_f32_16x16x32_bf16 v[104:107], v[166:169], v[198:201], v[104:107]
	v_mfma_f32_16x16x32_bf16 v[92:95], v[148:151], v[206:209], v[92:95]
	v_mfma_f32_16x16x32_bf16 v[88:91], v[166:169], v[206:209], v[88:91]
	v_mfma_f32_16x16x32_bf16 v[76:79], v[148:151], v[214:217], v[76:79]
	v_mfma_f32_16x16x32_bf16 v[72:75], v[166:169], v[214:217], v[72:75]
	v_mfma_f32_16x16x32_bf16 v[112:115], v[170:173], v[186:189], v[112:115]
	v_mfma_f32_16x16x32_bf16 v[108:111], v[178:181], v[186:189], v[108:111]
	v_mfma_f32_16x16x32_bf16 v[100:103], v[170:173], v[194:197], v[100:103]
	v_mfma_f32_16x16x32_bf16 v[96:99], v[178:181], v[194:197], v[96:99]
	v_mfma_f32_16x16x32_bf16 v[84:87], v[170:173], v[202:205], v[84:87]
	v_mfma_f32_16x16x32_bf16 v[80:83], v[178:181], v[202:205], v[80:83]
	v_mfma_f32_16x16x32_bf16 v[68:71], v[170:173], v[210:213], v[68:71]
	v_mfma_f32_16x16x32_bf16 v[64:67], v[178:181], v[210:213], v[64:67]
	v_mfma_f32_16x16x32_bf16 v[112:115], v[174:177], v[190:193], v[112:115]
	v_mfma_f32_16x16x32_bf16 v[108:111], v[182:185], v[190:193], v[108:111]
	v_mfma_f32_16x16x32_bf16 v[100:103], v[174:177], v[198:201], v[100:103]
	v_mfma_f32_16x16x32_bf16 v[96:99], v[182:185], v[198:201], v[96:99]
	v_mfma_f32_16x16x32_bf16 v[84:87], v[174:177], v[206:209], v[84:87]
	v_mfma_f32_16x16x32_bf16 v[80:83], v[182:185], v[206:209], v[80:83]
	v_mfma_f32_16x16x32_bf16 v[68:71], v[174:177], v[214:217], v[68:71]
	v_mfma_f32_16x16x32_bf16 v[64:67], v[182:185], v[214:217], v[64:67]
	s_barrier
	s_add_i32 s53, s46, s38
	v_lshl_add_u64 v[218:219], s[30:31], 0, v[132:133]
	s_mov_b32 m0, s53
	ds_read_b128 v[186:189], v163 offset:16384
	ds_read_b128 v[190:193], v163 offset:17408
	ds_read_b128 v[194:197], v163 offset:18432
	ds_read_b128 v[198:201], v163 offset:19456
	ds_read_b128 v[202:205], v163 offset:20480
	ds_read_b128 v[206:209], v163 offset:21504
	ds_read_b128 v[210:213], v163 offset:22528
	ds_read_b128 v[214:217], v163 offset:23552
	global_load_lds_dwordx4 v[218:219], off
	s_add_i32 m0, s53, 0x2000
	s_add_u32 s54, s30, 0x40000
	v_lshl_add_u64 v[220:221], s[30:31], 0, v[128:129]
	s_addc_u32 s55, s31, 0
	s_add_i32 s53, s47, s38
	global_load_lds_dwordx4 v[220:221], off
	v_lshl_add_u64 v[222:223], s[54:55], 0, v[132:133]
	s_mov_b32 m0, s53
	v_lshl_add_u64 v[224:225], s[34:35], 0, v[130:131]
	global_load_lds_dwordx4 v[222:223], off
	v_lshl_add_u64 v[222:223], s[54:55], 0, v[128:129]
	s_add_i32 m0, s53, 0x2000
	s_nop 0
	global_load_lds_dwordx4 v[222:223], off
	v_lshl_add_u64 v[222:223], s[34:35], 0, v[134:135]
	s_mov_b32 m0, s29
	s_nop 0
	global_load_lds_dwordx4 v[222:223], off
	s_mov_b32 m0, s40
	s_nop 0
	global_load_lds_dwordx4 v[224:225], off
	s_waitcnt vmcnt(8)
	s_waitcnt lgkmcnt(0)
	s_barrier
	s_waitcnt lgkmcnt(0)
	v_mfma_f32_16x16x32_bf16 v[60:63], v[144:147], v[186:189], v[60:63]
	v_mfma_f32_16x16x32_bf16 v[56:59], v[152:155], v[186:189], v[56:59]
	v_mfma_f32_16x16x32_bf16 v[44:47], v[144:147], v[194:197], v[44:47]
	v_mfma_f32_16x16x32_bf16 v[40:43], v[152:155], v[194:197], v[40:43]
	v_mfma_f32_16x16x32_bf16 v[28:31], v[144:147], v[202:205], v[28:31]
	v_mfma_f32_16x16x32_bf16 v[24:27], v[152:155], v[202:205], v[24:27]
	v_mfma_f32_16x16x32_bf16 v[12:15], v[144:147], v[210:213], v[12:15]
	v_mfma_f32_16x16x32_bf16 v[8:11], v[152:155], v[210:213], v[8:11]
	v_mfma_f32_16x16x32_bf16 v[60:63], v[148:151], v[190:193], v[60:63]
	v_mfma_f32_16x16x32_bf16 v[56:59], v[166:169], v[190:193], v[56:59]
	v_mfma_f32_16x16x32_bf16 v[44:47], v[148:151], v[198:201], v[44:47]
	v_mfma_f32_16x16x32_bf16 v[40:43], v[166:169], v[198:201], v[40:43]
	v_mfma_f32_16x16x32_bf16 v[28:31], v[148:151], v[206:209], v[28:31]
	v_mfma_f32_16x16x32_bf16 v[24:27], v[166:169], v[206:209], v[24:27]
	v_mfma_f32_16x16x32_bf16 v[12:15], v[148:151], v[214:217], v[12:15]
	v_mfma_f32_16x16x32_bf16 v[8:11], v[166:169], v[214:217], v[8:11]
	v_mfma_f32_16x16x32_bf16 v[52:55], v[170:173], v[186:189], v[52:55]
	v_mfma_f32_16x16x32_bf16 v[48:51], v[178:181], v[186:189], v[48:51]
	v_mfma_f32_16x16x32_bf16 v[36:39], v[170:173], v[194:197], v[36:39]
	v_mfma_f32_16x16x32_bf16 v[32:35], v[178:181], v[194:197], v[32:35]
	v_mfma_f32_16x16x32_bf16 v[20:23], v[170:173], v[202:205], v[20:23]
	v_mfma_f32_16x16x32_bf16 v[16:19], v[178:181], v[202:205], v[16:19]
	v_mfma_f32_16x16x32_bf16 v[4:7], v[170:173], v[210:213], v[4:7]
	v_mfma_f32_16x16x32_bf16 v[0:3], v[178:181], v[210:213], v[0:3]
	v_mfma_f32_16x16x32_bf16 v[52:55], v[174:177], v[190:193], v[52:55]
	v_mfma_f32_16x16x32_bf16 v[48:51], v[182:185], v[190:193], v[48:51]
	v_mfma_f32_16x16x32_bf16 v[36:39], v[174:177], v[198:201], v[36:39]
	v_mfma_f32_16x16x32_bf16 v[32:35], v[182:185], v[198:201], v[32:35]
	v_mfma_f32_16x16x32_bf16 v[20:23], v[174:177], v[206:209], v[20:23]
	v_mfma_f32_16x16x32_bf16 v[16:19], v[182:185], v[206:209], v[16:19]
	v_mfma_f32_16x16x32_bf16 v[4:7], v[174:177], v[214:217], v[4:7]
	v_mfma_f32_16x16x32_bf16 v[0:3], v[182:185], v[214:217], v[0:3]
	s_barrier
	s_add_i32 s53, 0, 0x18000
	v_add_u32_e32 v165, s53, v157
	s_add_i32 s54, 0, 0x1c000
	ds_read_b128 v[144:147], v165
	ds_read_b128 v[148:151], v165 offset:1024
	ds_read_b128 v[152:155], v165 offset:2048
	ds_read_b128 v[166:169], v165 offset:3072
	v_add_u32_e32 v165, s54, v157
	ds_read_b128 v[170:173], v165
	ds_read_b128 v[174:177], v165 offset:1024
	ds_read_b128 v[178:181], v165 offset:2048
	ds_read_b128 v[182:185], v165 offset:3072
	s_add_u32 s34, s34, 0x40000
	s_addc_u32 s35, s35, 0
	s_mov_b32 m0, s41
	v_lshl_add_u64 v[226:227], s[34:35], 0, v[134:135]
	ds_read_b128 v[186:189], v163 offset:32768
	ds_read_b128 v[190:193], v163 offset:33792
	ds_read_b128 v[194:197], v163 offset:34816
	ds_read_b128 v[198:201], v163 offset:35840
	ds_read_b128 v[202:205], v163 offset:36864
	ds_read_b128 v[206:209], v163 offset:37888
	ds_read_b128 v[210:213], v163 offset:38912
	ds_read_b128 v[214:217], v163 offset:39936
	global_load_lds_dwordx4 v[226:227], off
	v_lshl_add_u64 v[226:227], s[34:35], 0, v[130:131]
	s_mov_b32 m0, s42
	s_nop 0
	global_load_lds_dwordx4 v[226:227], off
	s_waitcnt vmcnt(8)
	s_waitcnt lgkmcnt(0)
	s_barrier
	s_waitcnt lgkmcnt(0)
	v_mfma_f32_16x16x32_bf16 v[124:127], v[144:147], v[186:189], v[124:127]
	v_mfma_f32_16x16x32_bf16 v[120:123], v[152:155], v[186:189], v[120:123]
	v_mfma_f32_16x16x32_bf16 v[116:119], v[144:147], v[194:197], v[116:119]
	v_mfma_f32_16x16x32_bf16 v[104:107], v[152:155], v[194:197], v[104:107]
	v_mfma_f32_16x16x32_bf16 v[92:95], v[144:147], v[202:205], v[92:95]
	v_mfma_f32_16x16x32_bf16 v[88:91], v[152:155], v[202:205], v[88:91]
	v_mfma_f32_16x16x32_bf16 v[76:79], v[144:147], v[210:213], v[76:79]
	v_mfma_f32_16x16x32_bf16 v[72:75], v[152:155], v[210:213], v[72:75]
	v_mfma_f32_16x16x32_bf16 v[124:127], v[148:151], v[190:193], v[124:127]
	v_mfma_f32_16x16x32_bf16 v[120:123], v[166:169], v[190:193], v[120:123]
	v_mfma_f32_16x16x32_bf16 v[116:119], v[148:151], v[198:201], v[116:119]
	v_mfma_f32_16x16x32_bf16 v[104:107], v[166:169], v[198:201], v[104:107]
	v_mfma_f32_16x16x32_bf16 v[92:95], v[148:151], v[206:209], v[92:95]
	v_mfma_f32_16x16x32_bf16 v[88:91], v[166:169], v[206:209], v[88:91]
	v_mfma_f32_16x16x32_bf16 v[76:79], v[148:151], v[214:217], v[76:79]
	v_mfma_f32_16x16x32_bf16 v[72:75], v[166:169], v[214:217], v[72:75]
	v_mfma_f32_16x16x32_bf16 v[112:115], v[170:173], v[186:189], v[112:115]
	v_mfma_f32_16x16x32_bf16 v[108:111], v[178:181], v[186:189], v[108:111]
	v_mfma_f32_16x16x32_bf16 v[100:103], v[170:173], v[194:197], v[100:103]
	v_mfma_f32_16x16x32_bf16 v[96:99], v[178:181], v[194:197], v[96:99]
	v_mfma_f32_16x16x32_bf16 v[84:87], v[170:173], v[202:205], v[84:87]
	v_mfma_f32_16x16x32_bf16 v[80:83], v[178:181], v[202:205], v[80:83]
	v_mfma_f32_16x16x32_bf16 v[68:71], v[170:173], v[210:213], v[68:71]
	v_mfma_f32_16x16x32_bf16 v[64:67], v[178:181], v[210:213], v[64:67]
	v_mfma_f32_16x16x32_bf16 v[112:115], v[174:177], v[190:193], v[112:115]
	v_mfma_f32_16x16x32_bf16 v[108:111], v[182:185], v[190:193], v[108:111]
	v_mfma_f32_16x16x32_bf16 v[100:103], v[174:177], v[198:201], v[100:103]
	v_mfma_f32_16x16x32_bf16 v[96:99], v[182:185], v[198:201], v[96:99]
	v_mfma_f32_16x16x32_bf16 v[84:87], v[174:177], v[206:209], v[84:87]
	v_mfma_f32_16x16x32_bf16 v[80:83], v[182:185], v[206:209], v[80:83]
	v_mfma_f32_16x16x32_bf16 v[68:71], v[174:177], v[214:217], v[68:71]
	v_mfma_f32_16x16x32_bf16 v[64:67], v[182:185], v[214:217], v[64:67]
	s_barrier
	s_add_i32 s34, s53, s38
	v_lshl_add_u64 v[218:219], v[218:219], 0, s[6:7]
	s_mov_b32 m0, s34
	ds_read_b128 v[186:189], v163 offset:49152
	ds_read_b128 v[190:193], v163 offset:50176
	ds_read_b128 v[194:197], v163 offset:51200
	ds_read_b128 v[198:201], v163 offset:52224
	ds_read_b128 v[202:205], v163 offset:53248
	ds_read_b128 v[206:209], v163 offset:54272
	ds_read_b128 v[210:213], v163 offset:55296
	ds_read_b128 v[214:217], v163 offset:56320
	global_load_lds_dwordx4 v[218:219], off
	s_add_i32 m0, s34, 0x2000
	s_add_u32 s30, s30, 0x40080
	v_lshl_add_u64 v[218:219], v[220:221], 0, s[6:7]
	s_addc_u32 s31, s31, 0
	s_add_i32 s34, s54, s38
	global_load_lds_dwordx4 v[218:219], off
	v_lshl_add_u64 v[218:219], s[30:31], 0, v[132:133]
	s_mov_b32 m0, s34
	s_nop 0
	global_load_lds_dwordx4 v[218:219], off
	v_lshl_add_u64 v[218:219], s[30:31], 0, v[128:129]
	s_add_i32 m0, s34, 0x2000
	s_nop 0
	global_load_lds_dwordx4 v[218:219], off
	v_lshl_add_u64 v[218:219], v[222:223], 0, s[6:7]
	s_mov_b32 m0, s44
	s_nop 0
	global_load_lds_dwordx4 v[218:219], off
	v_lshl_add_u64 v[218:219], v[224:225], 0, s[6:7]
	s_mov_b32 m0, s45
	s_nop 0
	global_load_lds_dwordx4 v[218:219], off
	s_waitcnt vmcnt(8)
	s_waitcnt lgkmcnt(0)
	s_barrier
	s_waitcnt lgkmcnt(0)
	v_mfma_f32_16x16x32_bf16 v[60:63], v[144:147], v[186:189], v[60:63]
	v_mfma_f32_16x16x32_bf16 v[56:59], v[152:155], v[186:189], v[56:59]
	v_mfma_f32_16x16x32_bf16 v[44:47], v[144:147], v[194:197], v[44:47]
	v_mfma_f32_16x16x32_bf16 v[40:43], v[152:155], v[194:197], v[40:43]
	v_mfma_f32_16x16x32_bf16 v[28:31], v[144:147], v[202:205], v[28:31]
	v_mfma_f32_16x16x32_bf16 v[24:27], v[152:155], v[202:205], v[24:27]
	v_mfma_f32_16x16x32_bf16 v[12:15], v[144:147], v[210:213], v[12:15]
	v_mfma_f32_16x16x32_bf16 v[8:11], v[152:155], v[210:213], v[8:11]
	v_mfma_f32_16x16x32_bf16 v[60:63], v[148:151], v[190:193], v[60:63]
	v_mfma_f32_16x16x32_bf16 v[56:59], v[166:169], v[190:193], v[56:59]
	v_mfma_f32_16x16x32_bf16 v[44:47], v[148:151], v[198:201], v[44:47]
	v_mfma_f32_16x16x32_bf16 v[40:43], v[166:169], v[198:201], v[40:43]
	v_mfma_f32_16x16x32_bf16 v[28:31], v[148:151], v[206:209], v[28:31]
	v_mfma_f32_16x16x32_bf16 v[24:27], v[166:169], v[206:209], v[24:27]
	v_mfma_f32_16x16x32_bf16 v[12:15], v[148:151], v[214:217], v[12:15]
	v_mfma_f32_16x16x32_bf16 v[8:11], v[166:169], v[214:217], v[8:11]
	v_mfma_f32_16x16x32_bf16 v[52:55], v[170:173], v[186:189], v[52:55]
	v_mfma_f32_16x16x32_bf16 v[48:51], v[178:181], v[186:189], v[48:51]
	v_mfma_f32_16x16x32_bf16 v[36:39], v[170:173], v[194:197], v[36:39]
	v_mfma_f32_16x16x32_bf16 v[32:35], v[178:181], v[194:197], v[32:35]
	v_mfma_f32_16x16x32_bf16 v[20:23], v[170:173], v[202:205], v[20:23]
	v_mfma_f32_16x16x32_bf16 v[16:19], v[178:181], v[202:205], v[16:19]
	v_mfma_f32_16x16x32_bf16 v[4:7], v[170:173], v[210:213], v[4:7]
	v_mfma_f32_16x16x32_bf16 v[0:3], v[178:181], v[210:213], v[0:3]
	v_mfma_f32_16x16x32_bf16 v[52:55], v[174:177], v[190:193], v[52:55]
	v_mfma_f32_16x16x32_bf16 v[48:51], v[182:185], v[190:193], v[48:51]
	v_mfma_f32_16x16x32_bf16 v[36:39], v[174:177], v[198:201], v[36:39]
	v_mfma_f32_16x16x32_bf16 v[32:35], v[182:185], v[198:201], v[32:35]
	v_mfma_f32_16x16x32_bf16 v[20:23], v[174:177], v[206:209], v[20:23]
	v_mfma_f32_16x16x32_bf16 v[16:19], v[182:185], v[206:209], v[16:19]
	v_mfma_f32_16x16x32_bf16 v[4:7], v[174:177], v[214:217], v[4:7]
	v_mfma_f32_16x16x32_bf16 v[0:3], v[182:185], v[214:217], v[0:3]
	s_barrier
	s_add_i32 s52, s52, 2
	s_add_u32 s0, s0, 0x100
	s_addc_u32 s1, s1, 0
	s_add_u32 s50, s50, 0x100
	s_addc_u32 s51, s51, 0
	s_cmp_gt_u32 s52, 13
	s_cbranch_scc0 .LBB0_636

.LBB0_710:
	s_ashr_i32 s17, s16, 31
	s_lshl_b64 s[26:27], s[16:17], 21
	s_add_u32 s26, s92, s26
	s_addc_u32 s27, s93, s27
	s_and_b64 s[28:29], s[6:7], exec
	s_cselect_b32 s17, s27, s1
	s_cselect_b32 s33, s26, s0
	s_ashr_i32 s15, s14, 31
	s_lshl_b64 s[28:29], s[14:15], 21
	s_add_u32 s28, s56, s28
	s_addc_u32 s29, s57, s29
	s_and_b64 s[38:39], s[6:7], exec
	s_cselect_b32 s15, s29, s37
	s_cselect_b32 s55, s28, s36
	s_add_u32 s0, s0, 0x100080
	s_addc_u32 s1, s1, 0
	s_add_u32 s58, s36, 0x100
	s_addc_u32 s59, s37, 0
	s_mov_b32 s60, -2
	s_waitcnt lgkmcnt(0)
	ds_read_b128 v[128:131], v188
	ds_read_b128 v[132:135], v188 offset:1024
	ds_read_b128 v[136:139], v188 offset:2048
	ds_read_b128 v[140:143], v188 offset:3072
	ds_read_b128 v[144:147], v189
	ds_read_b128 v[148:151], v189 offset:1024
	ds_read_b128 v[152:155], v189 offset:2048
	ds_read_b128 v[156:159], v189 offset:3072
	s_add_u32 s36, s0, 0xfff00080
	s_addc_u32 s37, s1, -1
	s_cmp_eq_u32 s60, 60
	s_cselect_b32 s39, s17, s37
	s_cselect_b32 s38, s33, s36
	s_cselect_b32 s37, s15, s59
	s_cselect_b32 s36, s55, s58
	v_lshl_add_u64 v[220:221], s[0:1], 0, v[170:171]
	s_add_i32 m0, s31, 0xc000
	ds_read_b128 v[178:181], v190
	ds_read_b128 v[192:195], v190 offset:1024
	ds_read_b128 v[196:199], v190 offset:2048
	ds_read_b128 v[200:203], v190 offset:3072
	ds_read_b128 v[204:207], v190 offset:4096
	ds_read_b128 v[208:211], v190 offset:5120
	ds_read_b128 v[212:215], v190 offset:6144
	ds_read_b128 v[216:219], v190 offset:7168
	global_load_lds_dwordx4 v[220:221], off
	v_lshl_add_u64 v[220:221], s[0:1], 0, v[172:173]
	s_add_i32 m0, s31, 0xe000
	s_nop 0
	global_load_lds_dwordx4 v[220:221], off
	s_waitcnt vmcnt(8)
	s_waitcnt lgkmcnt(0)
	s_barrier
	s_waitcnt lgkmcnt(0)
	v_mfma_f32_16x16x32_bf16 v[124:127], v[128:131], v[178:181], 0
	v_mfma_f32_16x16x32_bf16 v[120:123], v[136:139], v[178:181], 0
	v_mfma_f32_16x16x32_bf16 v[108:111], v[128:131], v[196:199], 0
	v_mfma_f32_16x16x32_bf16 v[104:107], v[136:139], v[196:199], 0
	v_mfma_f32_16x16x32_bf16 v[92:95], v[128:131], v[204:207], 0
	v_mfma_f32_16x16x32_bf16 v[88:91], v[136:139], v[204:207], 0
	v_mfma_f32_16x16x32_bf16 v[76:79], v[128:131], v[212:215], 0
	v_mfma_f32_16x16x32_bf16 v[72:75], v[136:139], v[212:215], 0
	v_mfma_f32_16x16x32_bf16 v[124:127], v[132:135], v[192:195], v[124:127]
	v_mfma_f32_16x16x32_bf16 v[120:123], v[140:143], v[192:195], v[120:123]
	v_mfma_f32_16x16x32_bf16 v[108:111], v[132:135], v[200:203], v[108:111]
	v_mfma_f32_16x16x32_bf16 v[104:107], v[140:143], v[200:203], v[104:107]
	v_mfma_f32_16x16x32_bf16 v[92:95], v[132:135], v[208:211], v[92:95]
	v_mfma_f32_16x16x32_bf16 v[88:91], v[140:143], v[208:211], v[88:91]
	v_mfma_f32_16x16x32_bf16 v[76:79], v[132:135], v[216:219], v[76:79]
	v_mfma_f32_16x16x32_bf16 v[72:75], v[140:143], v[216:219], v[72:75]
	v_mfma_f32_16x16x32_bf16 v[116:119], v[144:147], v[178:181], 0
	v_mfma_f32_16x16x32_bf16 v[112:115], v[152:155], v[178:181], 0
	v_mfma_f32_16x16x32_bf16 v[100:103], v[144:147], v[196:199], 0
	v_mfma_f32_16x16x32_bf16 v[96:99], v[152:155], v[196:199], 0
	v_mfma_f32_16x16x32_bf16 v[84:87], v[144:147], v[204:207], 0
	v_mfma_f32_16x16x32_bf16 v[80:83], v[152:155], v[204:207], 0
	v_mfma_f32_16x16x32_bf16 v[68:71], v[144:147], v[212:215], 0
	v_mfma_f32_16x16x32_bf16 v[64:67], v[152:155], v[212:215], 0
	v_mfma_f32_16x16x32_bf16 v[116:119], v[148:151], v[192:195], v[116:119]
	v_mfma_f32_16x16x32_bf16 v[112:115], v[156:159], v[192:195], v[112:115]
	v_mfma_f32_16x16x32_bf16 v[100:103], v[148:151], v[200:203], v[100:103]
	v_mfma_f32_16x16x32_bf16 v[96:99], v[156:159], v[200:203], v[96:99]
	v_mfma_f32_16x16x32_bf16 v[84:87], v[148:151], v[208:211], v[84:87]
	v_mfma_f32_16x16x32_bf16 v[80:83], v[156:159], v[208:211], v[80:83]
	v_mfma_f32_16x16x32_bf16 v[68:71], v[148:151], v[216:219], v[68:71]
	v_mfma_f32_16x16x32_bf16 v[64:67], v[156:159], v[216:219], v[64:67]
	s_barrier
	s_add_i32 s61, s49, s40
	v_lshl_add_u64 v[220:221], s[36:37], 0, v[164:165]
	s_mov_b32 m0, s61
	ds_read_b128 v[178:181], v190 offset:16384
	ds_read_b128 v[192:195], v190 offset:17408
	ds_read_b128 v[196:199], v190 offset:18432
	ds_read_b128 v[200:203], v190 offset:19456
	ds_read_b128 v[204:207], v190 offset:20480
	ds_read_b128 v[208:211], v190 offset:21504
	ds_read_b128 v[212:215], v190 offset:22528
	ds_read_b128 v[216:219], v190 offset:23552
	global_load_lds_dwordx4 v[220:221], off
	s_add_i32 m0, s61, 0x2000
	s_add_u32 s62, s36, 0x100000
	v_lshl_add_u64 v[222:223], s[36:37], 0, v[168:169]
	s_addc_u32 s63, s37, 0
	s_add_i32 s61, s50, s40
	global_load_lds_dwordx4 v[222:223], off
	v_lshl_add_u64 v[224:225], s[62:63], 0, v[164:165]
	s_mov_b32 m0, s61
	v_lshl_add_u64 v[226:227], s[38:39], 0, v[166:167]
	global_load_lds_dwordx4 v[224:225], off
	v_lshl_add_u64 v[224:225], s[62:63], 0, v[168:169]
	s_add_i32 m0, s61, 0x2000
	s_nop 0
	global_load_lds_dwordx4 v[224:225], off
	v_lshl_add_u64 v[224:225], s[38:39], 0, v[162:163]
	s_mov_b32 m0, s31
	s_nop 0
	global_load_lds_dwordx4 v[224:225], off
	s_mov_b32 m0, s35
	s_nop 0
	global_load_lds_dwordx4 v[226:227], off
	s_waitcnt vmcnt(8)
	s_waitcnt lgkmcnt(0)
	s_barrier
	s_waitcnt lgkmcnt(0)
	v_mfma_f32_16x16x32_bf16 v[60:63], v[128:131], v[178:181], 0
	v_mfma_f32_16x16x32_bf16 v[56:59], v[136:139], v[178:181], 0
	v_mfma_f32_16x16x32_bf16 v[44:47], v[128:131], v[196:199], 0
	v_mfma_f32_16x16x32_bf16 v[40:43], v[136:139], v[196:199], 0
	v_mfma_f32_16x16x32_bf16 v[28:31], v[128:131], v[204:207], 0
	v_mfma_f32_16x16x32_bf16 v[24:27], v[136:139], v[204:207], 0
	v_mfma_f32_16x16x32_bf16 v[12:15], v[128:131], v[212:215], 0
	v_mfma_f32_16x16x32_bf16 v[8:11], v[136:139], v[212:215], 0
	v_mfma_f32_16x16x32_bf16 v[60:63], v[132:135], v[192:195], v[60:63]
	v_mfma_f32_16x16x32_bf16 v[56:59], v[140:143], v[192:195], v[56:59]
	v_mfma_f32_16x16x32_bf16 v[44:47], v[132:135], v[200:203], v[44:47]
	v_mfma_f32_16x16x32_bf16 v[40:43], v[140:143], v[200:203], v[40:43]
	v_mfma_f32_16x16x32_bf16 v[28:31], v[132:135], v[208:211], v[28:31]
	v_mfma_f32_16x16x32_bf16 v[24:27], v[140:143], v[208:211], v[24:27]
	v_mfma_f32_16x16x32_bf16 v[12:15], v[132:135], v[216:219], v[12:15]
	v_mfma_f32_16x16x32_bf16 v[8:11], v[140:143], v[216:219], v[8:11]
	v_mfma_f32_16x16x32_bf16 v[52:55], v[144:147], v[178:181], 0
	v_mfma_f32_16x16x32_bf16 v[48:51], v[152:155], v[178:181], 0
	v_mfma_f32_16x16x32_bf16 v[36:39], v[144:147], v[196:199], 0
	v_mfma_f32_16x16x32_bf16 v[32:35], v[152:155], v[196:199], 0
	v_mfma_f32_16x16x32_bf16 v[20:23], v[144:147], v[204:207], 0
	v_mfma_f32_16x16x32_bf16 v[16:19], v[152:155], v[204:207], 0
	v_mfma_f32_16x16x32_bf16 v[4:7], v[144:147], v[212:215], 0
	v_mfma_f32_16x16x32_bf16 v[0:3], v[152:155], v[212:215], 0
	v_mfma_f32_16x16x32_bf16 v[52:55], v[148:151], v[192:195], v[52:55]
	v_mfma_f32_16x16x32_bf16 v[48:51], v[156:159], v[192:195], v[48:51]
	v_mfma_f32_16x16x32_bf16 v[36:39], v[148:151], v[200:203], v[36:39]
	v_mfma_f32_16x16x32_bf16 v[32:35], v[156:159], v[200:203], v[32:35]
	v_mfma_f32_16x16x32_bf16 v[20:23], v[148:151], v[208:211], v[20:23]
	v_mfma_f32_16x16x32_bf16 v[16:19], v[156:159], v[208:211], v[16:19]
	v_mfma_f32_16x16x32_bf16 v[4:7], v[148:151], v[216:219], v[4:7]
	v_mfma_f32_16x16x32_bf16 v[0:3], v[156:159], v[216:219], v[0:3]
	s_barrier
	s_add_i32 s61, 0, 0x18000
	s_add_i32 s62, 0, 0x1c000
	v_add_u32_e32 v140, s61, v183
	v_add_u32_e32 v156, s62, v183
	ds_read_b128 v[128:131], v140
	ds_read_b128 v[132:135], v140 offset:1024
	ds_read_b128 v[136:139], v140 offset:2048
	ds_read_b128 v[140:143], v140 offset:3072
	ds_read_b128 v[144:147], v156
	ds_read_b128 v[148:151], v156 offset:1024
	ds_read_b128 v[152:155], v156 offset:2048
	ds_read_b128 v[156:159], v156 offset:3072
	s_add_u32 s38, s38, 0x100000
	s_addc_u32 s39, s39, 0
	s_mov_b32 m0, s41
	v_lshl_add_u64 v[228:229], s[38:39], 0, v[162:163]
	ds_read_b128 v[178:181], v190 offset:32768
	ds_read_b128 v[192:195], v190 offset:33792
	ds_read_b128 v[196:199], v190 offset:34816
	ds_read_b128 v[200:203], v190 offset:35840
	ds_read_b128 v[204:207], v190 offset:36864
	ds_read_b128 v[208:211], v190 offset:37888
	ds_read_b128 v[212:215], v190 offset:38912
	ds_read_b128 v[216:219], v190 offset:39936
	global_load_lds_dwordx4 v[228:229], off
	v_lshl_add_u64 v[228:229], s[38:39], 0, v[166:167]
	s_mov_b32 m0, s42
	s_nop 0
	global_load_lds_dwordx4 v[228:229], off
	s_waitcnt vmcnt(8)
	s_waitcnt lgkmcnt(0)
	s_barrier
	s_waitcnt lgkmcnt(0)
	v_mfma_f32_16x16x32_bf16 v[124:127], v[128:131], v[178:181], v[124:127]
	v_mfma_f32_16x16x32_bf16 v[120:123], v[136:139], v[178:181], v[120:123]
	v_mfma_f32_16x16x32_bf16 v[108:111], v[128:131], v[196:199], v[108:111]
	v_mfma_f32_16x16x32_bf16 v[104:107], v[136:139], v[196:199], v[104:107]
	v_mfma_f32_16x16x32_bf16 v[92:95], v[128:131], v[204:207], v[92:95]
	v_mfma_f32_16x16x32_bf16 v[88:91], v[136:139], v[204:207], v[88:91]
	v_mfma_f32_16x16x32_bf16 v[76:79], v[128:131], v[212:215], v[76:79]
	v_mfma_f32_16x16x32_bf16 v[72:75], v[136:139], v[212:215], v[72:75]
	v_mfma_f32_16x16x32_bf16 v[124:127], v[132:135], v[192:195], v[124:127]
	v_mfma_f32_16x16x32_bf16 v[120:123], v[140:143], v[192:195], v[120:123]
	v_mfma_f32_16x16x32_bf16 v[108:111], v[132:135], v[200:203], v[108:111]
	v_mfma_f32_16x16x32_bf16 v[104:107], v[140:143], v[200:203], v[104:107]
	v_mfma_f32_16x16x32_bf16 v[92:95], v[132:135], v[208:211], v[92:95]
	v_mfma_f32_16x16x32_bf16 v[88:91], v[140:143], v[208:211], v[88:91]
	v_mfma_f32_16x16x32_bf16 v[76:79], v[132:135], v[216:219], v[76:79]
	v_mfma_f32_16x16x32_bf16 v[72:75], v[140:143], v[216:219], v[72:75]
	v_mfma_f32_16x16x32_bf16 v[116:119], v[144:147], v[178:181], v[116:119]
	v_mfma_f32_16x16x32_bf16 v[112:115], v[152:155], v[178:181], v[112:115]
	v_mfma_f32_16x16x32_bf16 v[100:103], v[144:147], v[196:199], v[100:103]
	v_mfma_f32_16x16x32_bf16 v[96:99], v[152:155], v[196:199], v[96:99]
	v_mfma_f32_16x16x32_bf16 v[84:87], v[144:147], v[204:207], v[84:87]
	v_mfma_f32_16x16x32_bf16 v[80:83], v[152:155], v[204:207], v[80:83]
	v_mfma_f32_16x16x32_bf16 v[68:71], v[144:147], v[212:215], v[68:71]
	v_mfma_f32_16x16x32_bf16 v[64:67], v[152:155], v[212:215], v[64:67]
	v_mfma_f32_16x16x32_bf16 v[116:119], v[148:151], v[192:195], v[116:119]
	v_mfma_f32_16x16x32_bf16 v[112:115], v[156:159], v[192:195], v[112:115]
	v_mfma_f32_16x16x32_bf16 v[100:103], v[148:151], v[200:203], v[100:103]
	v_mfma_f32_16x16x32_bf16 v[96:99], v[156:159], v[200:203], v[96:99]
	v_mfma_f32_16x16x32_bf16 v[84:87], v[148:151], v[208:211], v[84:87]
	v_mfma_f32_16x16x32_bf16 v[80:83], v[156:159], v[208:211], v[80:83]
	v_mfma_f32_16x16x32_bf16 v[68:71], v[148:151], v[216:219], v[68:71]
	v_mfma_f32_16x16x32_bf16 v[64:67], v[156:159], v[216:219], v[64:67]
	s_barrier
	s_add_i32 s38, s61, s40
	v_lshl_add_u64 v[220:221], v[220:221], 0, s[8:9]
	s_mov_b32 m0, s38
	ds_read_b128 v[178:181], v190 offset:49152
	ds_read_b128 v[192:195], v190 offset:50176
	ds_read_b128 v[196:199], v190 offset:51200
	ds_read_b128 v[200:203], v190 offset:52224
	ds_read_b128 v[204:207], v190 offset:53248
	ds_read_b128 v[208:211], v190 offset:54272
	ds_read_b128 v[212:215], v190 offset:55296
	ds_read_b128 v[216:219], v190 offset:56320
	global_load_lds_dwordx4 v[220:221], off
	s_add_i32 m0, s38, 0x2000
	s_add_u32 s36, s36, 0x100080
	v_lshl_add_u64 v[220:221], v[222:223], 0, s[8:9]
	s_addc_u32 s37, s37, 0
	s_add_i32 s38, s62, s40
	global_load_lds_dwordx4 v[220:221], off
	v_lshl_add_u64 v[220:221], s[36:37], 0, v[164:165]
	s_mov_b32 m0, s38
	s_nop 0
	global_load_lds_dwordx4 v[220:221], off
	v_lshl_add_u64 v[220:221], s[36:37], 0, v[168:169]
	s_add_i32 m0, s38, 0x2000
	s_nop 0
	global_load_lds_dwordx4 v[220:221], off
	v_lshl_add_u64 v[220:221], v[224:225], 0, s[8:9]
	s_mov_b32 m0, s45
	s_nop 0
	global_load_lds_dwordx4 v[220:221], off
	v_lshl_add_u64 v[220:221], v[226:227], 0, s[8:9]
	s_mov_b32 m0, s46
	s_nop 0
	global_load_lds_dwordx4 v[220:221], off
	s_waitcnt vmcnt(8)
	s_waitcnt lgkmcnt(0)
	s_barrier
	s_waitcnt lgkmcnt(0)
	v_mfma_f32_16x16x32_bf16 v[60:63], v[128:131], v[178:181], v[60:63]
	v_mfma_f32_16x16x32_bf16 v[56:59], v[136:139], v[178:181], v[56:59]
	v_mfma_f32_16x16x32_bf16 v[44:47], v[128:131], v[196:199], v[44:47]
	v_mfma_f32_16x16x32_bf16 v[40:43], v[136:139], v[196:199], v[40:43]
	v_mfma_f32_16x16x32_bf16 v[28:31], v[128:131], v[204:207], v[28:31]
	v_mfma_f32_16x16x32_bf16 v[24:27], v[136:139], v[204:207], v[24:27]
	v_mfma_f32_16x16x32_bf16 v[12:15], v[128:131], v[212:215], v[12:15]
	v_mfma_f32_16x16x32_bf16 v[8:11], v[136:139], v[212:215], v[8:11]
	v_mfma_f32_16x16x32_bf16 v[60:63], v[132:135], v[192:195], v[60:63]
	v_mfma_f32_16x16x32_bf16 v[56:59], v[140:143], v[192:195], v[56:59]
	v_mfma_f32_16x16x32_bf16 v[44:47], v[132:135], v[200:203], v[44:47]
	v_mfma_f32_16x16x32_bf16 v[40:43], v[140:143], v[200:203], v[40:43]
	v_mfma_f32_16x16x32_bf16 v[28:31], v[132:135], v[208:211], v[28:31]
	v_mfma_f32_16x16x32_bf16 v[24:27], v[140:143], v[208:211], v[24:27]
	v_mfma_f32_16x16x32_bf16 v[12:15], v[132:135], v[216:219], v[12:15]
	v_mfma_f32_16x16x32_bf16 v[8:11], v[140:143], v[216:219], v[8:11]
	v_mfma_f32_16x16x32_bf16 v[52:55], v[144:147], v[178:181], v[52:55]
	v_mfma_f32_16x16x32_bf16 v[48:51], v[152:155], v[178:181], v[48:51]
	v_mfma_f32_16x16x32_bf16 v[36:39], v[144:147], v[196:199], v[36:39]
	v_mfma_f32_16x16x32_bf16 v[32:35], v[152:155], v[196:199], v[32:35]
	v_mfma_f32_16x16x32_bf16 v[20:23], v[144:147], v[204:207], v[20:23]
	v_mfma_f32_16x16x32_bf16 v[16:19], v[152:155], v[204:207], v[16:19]
	v_mfma_f32_16x16x32_bf16 v[4:7], v[144:147], v[212:215], v[4:7]
	v_mfma_f32_16x16x32_bf16 v[0:3], v[152:155], v[212:215], v[0:3]
	v_mfma_f32_16x16x32_bf16 v[52:55], v[148:151], v[192:195], v[52:55]
	v_mfma_f32_16x16x32_bf16 v[48:51], v[156:159], v[192:195], v[48:51]
	v_mfma_f32_16x16x32_bf16 v[36:39], v[148:151], v[200:203], v[36:39]
	v_mfma_f32_16x16x32_bf16 v[32:35], v[156:159], v[200:203], v[32:35]
	v_mfma_f32_16x16x32_bf16 v[20:23], v[148:151], v[208:211], v[20:23]
	v_mfma_f32_16x16x32_bf16 v[16:19], v[156:159], v[208:211], v[16:19]
	v_mfma_f32_16x16x32_bf16 v[4:7], v[148:151], v[216:219], v[4:7]
	v_mfma_f32_16x16x32_bf16 v[0:3], v[156:159], v[216:219], v[0:3]
	s_barrier
	s_add_i32 s60, s60, 2
	s_add_u32 s0, s0, 0x100
	s_addc_u32 s1, s1, 0
	s_add_u32 s58, s58, 0x100
	s_addc_u32 s59, s59, 0
	s_cmp_gt_u32 s60, 61
	s_cbranch_scc0 .LBB0_711
	s_branch .Lpeel_exit_4
.LBB0_711:
	ds_read_b128 v[128:131], v188
	ds_read_b128 v[132:135], v188 offset:1024
	ds_read_b128 v[136:139], v188 offset:2048
	ds_read_b128 v[140:143], v188 offset:3072
	ds_read_b128 v[144:147], v189
	ds_read_b128 v[148:151], v189 offset:1024
	ds_read_b128 v[152:155], v189 offset:2048
	ds_read_b128 v[156:159], v189 offset:3072
	s_add_u32 s36, s0, 0xfff00080
	s_addc_u32 s37, s1, -1
	s_cmp_eq_u32 s60, 60
	s_cselect_b32 s39, s17, s37
	s_cselect_b32 s38, s33, s36
	s_cselect_b32 s37, s15, s59
	s_cselect_b32 s36, s55, s58
	v_lshl_add_u64 v[220:221], s[0:1], 0, v[170:171]
	s_add_i32 m0, s31, 0xc000
	ds_read_b128 v[178:181], v190
	ds_read_b128 v[192:195], v190 offset:1024
	ds_read_b128 v[196:199], v190 offset:2048
	ds_read_b128 v[200:203], v190 offset:3072
	ds_read_b128 v[204:207], v190 offset:4096
	ds_read_b128 v[208:211], v190 offset:5120
	ds_read_b128 v[212:215], v190 offset:6144
	ds_read_b128 v[216:219], v190 offset:7168
	global_load_lds_dwordx4 v[220:221], off
	v_lshl_add_u64 v[220:221], s[0:1], 0, v[172:173]
	s_add_i32 m0, s31, 0xe000
	s_nop 0
	global_load_lds_dwordx4 v[220:221], off
	s_waitcnt vmcnt(8)
	s_waitcnt lgkmcnt(0)
	s_barrier
	s_waitcnt lgkmcnt(0)
	v_mfma_f32_16x16x32_bf16 v[124:127], v[128:131], v[178:181], v[124:127]
	v_mfma_f32_16x16x32_bf16 v[120:123], v[136:139], v[178:181], v[120:123]
	v_mfma_f32_16x16x32_bf16 v[108:111], v[128:131], v[196:199], v[108:111]
	v_mfma_f32_16x16x32_bf16 v[104:107], v[136:139], v[196:199], v[104:107]
	v_mfma_f32_16x16x32_bf16 v[92:95], v[128:131], v[204:207], v[92:95]
	v_mfma_f32_16x16x32_bf16 v[88:91], v[136:139], v[204:207], v[88:91]
	v_mfma_f32_16x16x32_bf16 v[76:79], v[128:131], v[212:215], v[76:79]
	v_mfma_f32_16x16x32_bf16 v[72:75], v[136:139], v[212:215], v[72:75]
	v_mfma_f32_16x16x32_bf16 v[124:127], v[132:135], v[192:195], v[124:127]
	v_mfma_f32_16x16x32_bf16 v[120:123], v[140:143], v[192:195], v[120:123]
	v_mfma_f32_16x16x32_bf16 v[108:111], v[132:135], v[200:203], v[108:111]
	v_mfma_f32_16x16x32_bf16 v[104:107], v[140:143], v[200:203], v[104:107]
	v_mfma_f32_16x16x32_bf16 v[92:95], v[132:135], v[208:211], v[92:95]
	v_mfma_f32_16x16x32_bf16 v[88:91], v[140:143], v[208:211], v[88:91]
	v_mfma_f32_16x16x32_bf16 v[76:79], v[132:135], v[216:219], v[76:79]
	v_mfma_f32_16x16x32_bf16 v[72:75], v[140:143], v[216:219], v[72:75]
	v_mfma_f32_16x16x32_bf16 v[116:119], v[144:147], v[178:181], v[116:119]
	v_mfma_f32_16x16x32_bf16 v[112:115], v[152:155], v[178:181], v[112:115]
	v_mfma_f32_16x16x32_bf16 v[100:103], v[144:147], v[196:199], v[100:103]
	v_mfma_f32_16x16x32_bf16 v[96:99], v[152:155], v[196:199], v[96:99]
	v_mfma_f32_16x16x32_bf16 v[84:87], v[144:147], v[204:207], v[84:87]
	v_mfma_f32_16x16x32_bf16 v[80:83], v[152:155], v[204:207], v[80:83]
	v_mfma_f32_16x16x32_bf16 v[68:71], v[144:147], v[212:215], v[68:71]
	v_mfma_f32_16x16x32_bf16 v[64:67], v[152:155], v[212:215], v[64:67]
	v_mfma_f32_16x16x32_bf16 v[116:119], v[148:151], v[192:195], v[116:119]
	v_mfma_f32_16x16x32_bf16 v[112:115], v[156:159], v[192:195], v[112:115]
	v_mfma_f32_16x16x32_bf16 v[100:103], v[148:151], v[200:203], v[100:103]
	v_mfma_f32_16x16x32_bf16 v[96:99], v[156:159], v[200:203], v[96:99]
	v_mfma_f32_16x16x32_bf16 v[84:87], v[148:151], v[208:211], v[84:87]
	v_mfma_f32_16x16x32_bf16 v[80:83], v[156:159], v[208:211], v[80:83]
	v_mfma_f32_16x16x32_bf16 v[68:71], v[148:151], v[216:219], v[68:71]
	v_mfma_f32_16x16x32_bf16 v[64:67], v[156:159], v[216:219], v[64:67]
	s_barrier
	s_add_i32 s61, s49, s40
	v_lshl_add_u64 v[220:221], s[36:37], 0, v[164:165]
	s_mov_b32 m0, s61
	ds_read_b128 v[178:181], v190 offset:16384
	ds_read_b128 v[192:195], v190 offset:17408
	ds_read_b128 v[196:199], v190 offset:18432
	ds_read_b128 v[200:203], v190 offset:19456
	ds_read_b128 v[204:207], v190 offset:20480
	ds_read_b128 v[208:211], v190 offset:21504
	ds_read_b128 v[212:215], v190 offset:22528
	ds_read_b128 v[216:219], v190 offset:23552
	global_load_lds_dwordx4 v[220:221], off
	s_add_i32 m0, s61, 0x2000
	s_add_u32 s62, s36, 0x100000
	v_lshl_add_u64 v[222:223], s[36:37], 0, v[168:169]
	s_addc_u32 s63, s37, 0
	s_add_i32 s61, s50, s40
	global_load_lds_dwordx4 v[222:223], off
	v_lshl_add_u64 v[224:225], s[62:63], 0, v[164:165]
	s_mov_b32 m0, s61
	v_lshl_add_u64 v[226:227], s[38:39], 0, v[166:167]
	global_load_lds_dwordx4 v[224:225], off
	v_lshl_add_u64 v[224:225], s[62:63], 0, v[168:169]
	s_add_i32 m0, s61, 0x2000
	s_nop 0
	global_load_lds_dwordx4 v[224:225], off
	v_lshl_add_u64 v[224:225], s[38:39], 0, v[162:163]
	s_mov_b32 m0, s31
	s_nop 0
	global_load_lds_dwordx4 v[224:225], off
	s_mov_b32 m0, s35
	s_nop 0
	global_load_lds_dwordx4 v[226:227], off
	s_waitcnt vmcnt(8)
	s_waitcnt lgkmcnt(0)
	s_barrier
	s_waitcnt lgkmcnt(0)
	v_mfma_f32_16x16x32_bf16 v[60:63], v[128:131], v[178:181], v[60:63]
	v_mfma_f32_16x16x32_bf16 v[56:59], v[136:139], v[178:181], v[56:59]
	v_mfma_f32_16x16x32_bf16 v[44:47], v[128:131], v[196:199], v[44:47]
	v_mfma_f32_16x16x32_bf16 v[40:43], v[136:139], v[196:199], v[40:43]
	v_mfma_f32_16x16x32_bf16 v[28:31], v[128:131], v[204:207], v[28:31]
	v_mfma_f32_16x16x32_bf16 v[24:27], v[136:139], v[204:207], v[24:27]
	v_mfma_f32_16x16x32_bf16 v[12:15], v[128:131], v[212:215], v[12:15]
	v_mfma_f32_16x16x32_bf16 v[8:11], v[136:139], v[212:215], v[8:11]
	v_mfma_f32_16x16x32_bf16 v[60:63], v[132:135], v[192:195], v[60:63]
	v_mfma_f32_16x16x32_bf16 v[56:59], v[140:143], v[192:195], v[56:59]
	v_mfma_f32_16x16x32_bf16 v[44:47], v[132:135], v[200:203], v[44:47]
	v_mfma_f32_16x16x32_bf16 v[40:43], v[140:143], v[200:203], v[40:43]
	v_mfma_f32_16x16x32_bf16 v[28:31], v[132:135], v[208:211], v[28:31]
	v_mfma_f32_16x16x32_bf16 v[24:27], v[140:143], v[208:211], v[24:27]
	v_mfma_f32_16x16x32_bf16 v[12:15], v[132:135], v[216:219], v[12:15]
	v_mfma_f32_16x16x32_bf16 v[8:11], v[140:143], v[216:219], v[8:11]
	v_mfma_f32_16x16x32_bf16 v[52:55], v[144:147], v[178:181], v[52:55]
	v_mfma_f32_16x16x32_bf16 v[48:51], v[152:155], v[178:181], v[48:51]
	v_mfma_f32_16x16x32_bf16 v[36:39], v[144:147], v[196:199], v[36:39]
	v_mfma_f32_16x16x32_bf16 v[32:35], v[152:155], v[196:199], v[32:35]
	v_mfma_f32_16x16x32_bf16 v[20:23], v[144:147], v[204:207], v[20:23]
	v_mfma_f32_16x16x32_bf16 v[16:19], v[152:155], v[204:207], v[16:19]
	v_mfma_f32_16x16x32_bf16 v[4:7], v[144:147], v[212:215], v[4:7]
	v_mfma_f32_16x16x32_bf16 v[0:3], v[152:155], v[212:215], v[0:3]
	v_mfma_f32_16x16x32_bf16 v[52:55], v[148:151], v[192:195], v[52:55]
	v_mfma_f32_16x16x32_bf16 v[48:51], v[156:159], v[192:195], v[48:51]
	v_mfma_f32_16x16x32_bf16 v[36:39], v[148:151], v[200:203], v[36:39]
	v_mfma_f32_16x16x32_bf16 v[32:35], v[156:159], v[200:203], v[32:35]
	v_mfma_f32_16x16x32_bf16 v[20:23], v[148:151], v[208:211], v[20:23]
	v_mfma_f32_16x16x32_bf16 v[16:19], v[156:159], v[208:211], v[16:19]
	v_mfma_f32_16x16x32_bf16 v[4:7], v[148:151], v[216:219], v[4:7]
	v_mfma_f32_16x16x32_bf16 v[0:3], v[156:159], v[216:219], v[0:3]
	s_barrier
	s_add_i32 s61, 0, 0x18000
	s_add_i32 s62, 0, 0x1c000
	v_add_u32_e32 v140, s61, v183
	v_add_u32_e32 v156, s62, v183
	ds_read_b128 v[128:131], v140
	ds_read_b128 v[132:135], v140 offset:1024
	ds_read_b128 v[136:139], v140 offset:2048
	ds_read_b128 v[140:143], v140 offset:3072
	ds_read_b128 v[144:147], v156
	ds_read_b128 v[148:151], v156 offset:1024
	ds_read_b128 v[152:155], v156 offset:2048
	ds_read_b128 v[156:159], v156 offset:3072
	s_add_u32 s38, s38, 0x100000
	s_addc_u32 s39, s39, 0
	s_mov_b32 m0, s41
	v_lshl_add_u64 v[228:229], s[38:39], 0, v[162:163]
	ds_read_b128 v[178:181], v190 offset:32768
	ds_read_b128 v[192:195], v190 offset:33792
	ds_read_b128 v[196:199], v190 offset:34816
	ds_read_b128 v[200:203], v190 offset:35840
	ds_read_b128 v[204:207], v190 offset:36864
	ds_read_b128 v[208:211], v190 offset:37888
	ds_read_b128 v[212:215], v190 offset:38912
	ds_read_b128 v[216:219], v190 offset:39936
	global_load_lds_dwordx4 v[228:229], off
	v_lshl_add_u64 v[228:229], s[38:39], 0, v[166:167]
	s_mov_b32 m0, s42
	s_nop 0
	global_load_lds_dwordx4 v[228:229], off
	s_waitcnt vmcnt(8)
	s_waitcnt lgkmcnt(0)
	s_barrier
	s_waitcnt lgkmcnt(0)
	v_mfma_f32_16x16x32_bf16 v[124:127], v[128:131], v[178:181], v[124:127]
	v_mfma_f32_16x16x32_bf16 v[120:123], v[136:139], v[178:181], v[120:123]
	v_mfma_f32_16x16x32_bf16 v[108:111], v[128:131], v[196:199], v[108:111]
	v_mfma_f32_16x16x32_bf16 v[104:107], v[136:139], v[196:199], v[104:107]
	v_mfma_f32_16x16x32_bf16 v[92:95], v[128:131], v[204:207], v[92:95]
	v_mfma_f32_16x16x32_bf16 v[88:91], v[136:139], v[204:207], v[88:91]
	v_mfma_f32_16x16x32_bf16 v[76:79], v[128:131], v[212:215], v[76:79]
	v_mfma_f32_16x16x32_bf16 v[72:75], v[136:139], v[212:215], v[72:75]
	v_mfma_f32_16x16x32_bf16 v[124:127], v[132:135], v[192:195], v[124:127]
	v_mfma_f32_16x16x32_bf16 v[120:123], v[140:143], v[192:195], v[120:123]
	v_mfma_f32_16x16x32_bf16 v[108:111], v[132:135], v[200:203], v[108:111]
	v_mfma_f32_16x16x32_bf16 v[104:107], v[140:143], v[200:203], v[104:107]
	v_mfma_f32_16x16x32_bf16 v[92:95], v[132:135], v[208:211], v[92:95]
	v_mfma_f32_16x16x32_bf16 v[88:91], v[140:143], v[208:211], v[88:91]
	v_mfma_f32_16x16x32_bf16 v[76:79], v[132:135], v[216:219], v[76:79]
	v_mfma_f32_16x16x32_bf16 v[72:75], v[140:143], v[216:219], v[72:75]
	v_mfma_f32_16x16x32_bf16 v[116:119], v[144:147], v[178:181], v[116:119]
	v_mfma_f32_16x16x32_bf16 v[112:115], v[152:155], v[178:181], v[112:115]
	v_mfma_f32_16x16x32_bf16 v[100:103], v[144:147], v[196:199], v[100:103]
	v_mfma_f32_16x16x32_bf16 v[96:99], v[152:155], v[196:199], v[96:99]
	v_mfma_f32_16x16x32_bf16 v[84:87], v[144:147], v[204:207], v[84:87]
	v_mfma_f32_16x16x32_bf16 v[80:83], v[152:155], v[204:207], v[80:83]
	v_mfma_f32_16x16x32_bf16 v[68:71], v[144:147], v[212:215], v[68:71]
	v_mfma_f32_16x16x32_bf16 v[64:67], v[152:155], v[212:215], v[64:67]
	v_mfma_f32_16x16x32_bf16 v[116:119], v[148:151], v[192:195], v[116:119]
	v_mfma_f32_16x16x32_bf16 v[112:115], v[156:159], v[192:195], v[112:115]
	v_mfma_f32_16x16x32_bf16 v[100:103], v[148:151], v[200:203], v[100:103]
	v_mfma_f32_16x16x32_bf16 v[96:99], v[156:159], v[200:203], v[96:99]
	v_mfma_f32_16x16x32_bf16 v[84:87], v[148:151], v[208:211], v[84:87]
	v_mfma_f32_16x16x32_bf16 v[80:83], v[156:159], v[208:211], v[80:83]
	v_mfma_f32_16x16x32_bf16 v[68:71], v[148:151], v[216:219], v[68:71]
	v_mfma_f32_16x16x32_bf16 v[64:67], v[156:159], v[216:219], v[64:67]
	s_barrier
	s_add_i32 s38, s61, s40
	v_lshl_add_u64 v[220:221], v[220:221], 0, s[8:9]
	s_mov_b32 m0, s38
	ds_read_b128 v[178:181], v190 offset:49152
	ds_read_b128 v[192:195], v190 offset:50176
	ds_read_b128 v[196:199], v190 offset:51200
	ds_read_b128 v[200:203], v190 offset:52224
	ds_read_b128 v[204:207], v190 offset:53248
	ds_read_b128 v[208:211], v190 offset:54272
	ds_read_b128 v[212:215], v190 offset:55296
	ds_read_b128 v[216:219], v190 offset:56320
	global_load_lds_dwordx4 v[220:221], off
	s_add_i32 m0, s38, 0x2000
	s_add_u32 s36, s36, 0x100080
	v_lshl_add_u64 v[220:221], v[222:223], 0, s[8:9]
	s_addc_u32 s37, s37, 0
	s_add_i32 s38, s62, s40
	global_load_lds_dwordx4 v[220:221], off
	v_lshl_add_u64 v[220:221], s[36:37], 0, v[164:165]
	s_mov_b32 m0, s38
	s_nop 0
	global_load_lds_dwordx4 v[220:221], off
	v_lshl_add_u64 v[220:221], s[36:37], 0, v[168:169]
	s_add_i32 m0, s38, 0x2000
	s_nop 0
	global_load_lds_dwordx4 v[220:221], off
	v_lshl_add_u64 v[220:221], v[224:225], 0, s[8:9]
	s_mov_b32 m0, s45
	s_nop 0
	global_load_lds_dwordx4 v[220:221], off
	v_lshl_add_u64 v[220:221], v[226:227], 0, s[8:9]
	s_mov_b32 m0, s46
	s_nop 0
	global_load_lds_dwordx4 v[220:221], off
	s_waitcnt vmcnt(8)
	s_waitcnt lgkmcnt(0)
	s_barrier
	s_waitcnt lgkmcnt(0)
	v_mfma_f32_16x16x32_bf16 v[60:63], v[128:131], v[178:181], v[60:63]
	v_mfma_f32_16x16x32_bf16 v[56:59], v[136:139], v[178:181], v[56:59]
	v_mfma_f32_16x16x32_bf16 v[44:47], v[128:131], v[196:199], v[44:47]
	v_mfma_f32_16x16x32_bf16 v[40:43], v[136:139], v[196:199], v[40:43]
	v_mfma_f32_16x16x32_bf16 v[28:31], v[128:131], v[204:207], v[28:31]
	v_mfma_f32_16x16x32_bf16 v[24:27], v[136:139], v[204:207], v[24:27]
	v_mfma_f32_16x16x32_bf16 v[12:15], v[128:131], v[212:215], v[12:15]
	v_mfma_f32_16x16x32_bf16 v[8:11], v[136:139], v[212:215], v[8:11]
	v_mfma_f32_16x16x32_bf16 v[60:63], v[132:135], v[192:195], v[60:63]
	v_mfma_f32_16x16x32_bf16 v[56:59], v[140:143], v[192:195], v[56:59]
	v_mfma_f32_16x16x32_bf16 v[44:47], v[132:135], v[200:203], v[44:47]
	v_mfma_f32_16x16x32_bf16 v[40:43], v[140:143], v[200:203], v[40:43]
	v_mfma_f32_16x16x32_bf16 v[28:31], v[132:135], v[208:211], v[28:31]
	v_mfma_f32_16x16x32_bf16 v[24:27], v[140:143], v[208:211], v[24:27]
	v_mfma_f32_16x16x32_bf16 v[12:15], v[132:135], v[216:219], v[12:15]
	v_mfma_f32_16x16x32_bf16 v[8:11], v[140:143], v[216:219], v[8:11]
	v_mfma_f32_16x16x32_bf16 v[52:55], v[144:147], v[178:181], v[52:55]
	v_mfma_f32_16x16x32_bf16 v[48:51], v[152:155], v[178:181], v[48:51]
	v_mfma_f32_16x16x32_bf16 v[36:39], v[144:147], v[196:199], v[36:39]
	v_mfma_f32_16x16x32_bf16 v[32:35], v[152:155], v[196:199], v[32:35]
	v_mfma_f32_16x16x32_bf16 v[20:23], v[144:147], v[204:207], v[20:23]
	v_mfma_f32_16x16x32_bf16 v[16:19], v[152:155], v[204:207], v[16:19]
	v_mfma_f32_16x16x32_bf16 v[4:7], v[144:147], v[212:215], v[4:7]
	v_mfma_f32_16x16x32_bf16 v[0:3], v[152:155], v[212:215], v[0:3]
	v_mfma_f32_16x16x32_bf16 v[52:55], v[148:151], v[192:195], v[52:55]
	v_mfma_f32_16x16x32_bf16 v[48:51], v[156:159], v[192:195], v[48:51]
	v_mfma_f32_16x16x32_bf16 v[36:39], v[148:151], v[200:203], v[36:39]
	v_mfma_f32_16x16x32_bf16 v[32:35], v[156:159], v[200:203], v[32:35]
	v_mfma_f32_16x16x32_bf16 v[20:23], v[148:151], v[208:211], v[20:23]
	v_mfma_f32_16x16x32_bf16 v[16:19], v[156:159], v[208:211], v[16:19]
	v_mfma_f32_16x16x32_bf16 v[4:7], v[148:151], v[216:219], v[4:7]
	v_mfma_f32_16x16x32_bf16 v[0:3], v[156:159], v[216:219], v[0:3]
	s_barrier
	s_add_i32 s60, s60, 2
	s_add_u32 s0, s0, 0x100
	s_addc_u32 s1, s1, 0
	s_add_u32 s58, s58, 0x100
	s_addc_u32 s59, s59, 0
	s_cmp_gt_u32 s60, 61
	s_cbranch_scc0 .LBB0_711

.LBB0_798:
	s_ashr_i32 s29, s28, 31
	s_lshl_b64 s[30:31], s[28:29], 19
	s_add_u32 s30, s96, s30
	s_addc_u32 s31, s97, s31
	s_and_b64 s[34:35], s[4:5], exec
	s_cselect_b32 s3, s31, s1
	s_cselect_b32 s7, s30, s0
	s_ashr_i32 s27, s26, 31
	s_lshl_b64 s[34:35], s[26:27], 19
	s_add_u32 s34, s58, s34
	s_addc_u32 s35, s59, s35
	s_and_b64 s[36:37], s[4:5], exec
	s_cselect_b32 s27, s35, s9
	s_cselect_b32 s29, s34, s8
	s_add_u32 s0, s0, 0x40080
	s_addc_u32 s1, s1, 0
	s_add_u32 s33, s8, 0x100
	s_addc_u32 s38, s9, 0
	s_mov_b32 s39, -2
	ds_read_b128 v[128:131], v177
	ds_read_b128 v[154:157], v177 offset:1024
	ds_read_b128 v[162:165], v177 offset:2048
	ds_read_b128 v[166:169], v177 offset:3072
	ds_read_b128 v[182:185], v178
	ds_read_b128 v[186:189], v178 offset:1024
	ds_read_b128 v[190:193], v178 offset:2048
	ds_read_b128 v[194:197], v178 offset:3072
	s_add_u32 s8, s0, 0xfffc0080
	s_addc_u32 s9, s1, -1
	s_cmp_eq_u32 s39, 12
	s_cselect_b32 s37, s3, s9
	s_cselect_b32 s36, s7, s8
	s_cselect_b32 s9, s27, s38
	s_cselect_b32 s8, s29, s33
	v_lshl_add_u64 v[158:159], s[0:1], 0, v[146:147]
	s_add_i32 m0, s62, 0xc000
	ds_read_b128 v[198:201], v179
	ds_read_b128 v[202:205], v179 offset:1024
	ds_read_b128 v[206:209], v179 offset:2048
	ds_read_b128 v[210:213], v179 offset:3072
	ds_read_b128 v[214:217], v179 offset:4096
	ds_read_b128 v[218:221], v179 offset:5120
	ds_read_b128 v[222:225], v179 offset:6144
	ds_read_b128 v[226:229], v179 offset:7168
	global_load_lds_dwordx4 v[158:159], off
	v_lshl_add_u64 v[158:159], s[0:1], 0, v[148:149]
	s_add_i32 m0, s62, 0xe000
	s_nop 0
	global_load_lds_dwordx4 v[158:159], off
	s_waitcnt vmcnt(8)
	s_waitcnt lgkmcnt(0)
	s_barrier
	s_waitcnt lgkmcnt(0)
	v_mfma_f32_16x16x32_bf16 v[124:127], v[128:131], v[198:201], 0
	v_mfma_f32_16x16x32_bf16 v[120:123], v[162:165], v[198:201], 0
	v_mfma_f32_16x16x32_bf16 v[108:111], v[128:131], v[206:209], 0
	v_mfma_f32_16x16x32_bf16 v[104:107], v[162:165], v[206:209], 0
	v_mfma_f32_16x16x32_bf16 v[92:95], v[128:131], v[214:217], 0
	v_mfma_f32_16x16x32_bf16 v[88:91], v[162:165], v[214:217], 0
	v_mfma_f32_16x16x32_bf16 v[76:79], v[128:131], v[222:225], 0
	v_mfma_f32_16x16x32_bf16 v[72:75], v[162:165], v[222:225], 0
	v_mfma_f32_16x16x32_bf16 v[124:127], v[154:157], v[202:205], v[124:127]
	v_mfma_f32_16x16x32_bf16 v[120:123], v[166:169], v[202:205], v[120:123]
	v_mfma_f32_16x16x32_bf16 v[108:111], v[154:157], v[210:213], v[108:111]
	v_mfma_f32_16x16x32_bf16 v[104:107], v[166:169], v[210:213], v[104:107]
	v_mfma_f32_16x16x32_bf16 v[92:95], v[154:157], v[218:221], v[92:95]
	v_mfma_f32_16x16x32_bf16 v[88:91], v[166:169], v[218:221], v[88:91]
	v_mfma_f32_16x16x32_bf16 v[76:79], v[154:157], v[226:229], v[76:79]
	v_mfma_f32_16x16x32_bf16 v[72:75], v[166:169], v[226:229], v[72:75]
	v_mfma_f32_16x16x32_bf16 v[116:119], v[182:185], v[198:201], 0
	v_mfma_f32_16x16x32_bf16 v[112:115], v[190:193], v[198:201], 0
	v_mfma_f32_16x16x32_bf16 v[100:103], v[182:185], v[206:209], 0
	v_mfma_f32_16x16x32_bf16 v[96:99], v[190:193], v[206:209], 0
	v_mfma_f32_16x16x32_bf16 v[84:87], v[182:185], v[214:217], 0
	v_mfma_f32_16x16x32_bf16 v[80:83], v[190:193], v[214:217], 0
	v_mfma_f32_16x16x32_bf16 v[68:71], v[182:185], v[222:225], 0
	v_mfma_f32_16x16x32_bf16 v[64:67], v[190:193], v[222:225], 0
	v_mfma_f32_16x16x32_bf16 v[116:119], v[186:189], v[202:205], v[116:119]
	v_mfma_f32_16x16x32_bf16 v[112:115], v[194:197], v[202:205], v[112:115]
	v_mfma_f32_16x16x32_bf16 v[100:103], v[186:189], v[210:213], v[100:103]
	v_mfma_f32_16x16x32_bf16 v[96:99], v[194:197], v[210:213], v[96:99]
	v_mfma_f32_16x16x32_bf16 v[84:87], v[186:189], v[218:221], v[84:87]
	v_mfma_f32_16x16x32_bf16 v[80:83], v[194:197], v[218:221], v[80:83]
	v_mfma_f32_16x16x32_bf16 v[68:71], v[186:189], v[226:229], v[68:71]
	v_mfma_f32_16x16x32_bf16 v[64:67], v[194:197], v[226:229], v[64:67]
	s_barrier
	s_add_i32 s40, s78, s61
	v_lshl_add_u64 v[158:159], s[8:9], 0, v[134:135]
	s_mov_b32 m0, s40
	ds_read_b128 v[198:201], v179 offset:16384
	ds_read_b128 v[202:205], v179 offset:17408
	ds_read_b128 v[206:209], v179 offset:18432
	ds_read_b128 v[210:213], v179 offset:19456
	ds_read_b128 v[214:217], v179 offset:20480
	ds_read_b128 v[218:221], v179 offset:21504
	ds_read_b128 v[222:225], v179 offset:22528
	ds_read_b128 v[226:229], v179 offset:23552
	global_load_lds_dwordx4 v[158:159], off
	s_add_i32 m0, s40, 0x2000
	s_add_u32 s40, s8, 0x40000
	v_lshl_add_u64 v[230:231], s[8:9], 0, v[138:139]
	s_addc_u32 s41, s9, 0
	s_add_i32 s42, s79, s61
	global_load_lds_dwordx4 v[230:231], off
	v_lshl_add_u64 v[232:233], s[40:41], 0, v[134:135]
	s_mov_b32 m0, s42
	v_lshl_add_u64 v[234:235], s[36:37], 0, v[136:137]
	global_load_lds_dwordx4 v[232:233], off
	v_lshl_add_u64 v[232:233], s[40:41], 0, v[138:139]
	s_add_i32 m0, s42, 0x2000
	s_nop 0
	global_load_lds_dwordx4 v[232:233], off
	v_lshl_add_u64 v[232:233], s[36:37], 0, v[132:133]
	s_mov_b32 m0, s62
	s_nop 0
	global_load_lds_dwordx4 v[232:233], off
	s_mov_b32 m0, s63
	s_nop 0
	global_load_lds_dwordx4 v[234:235], off
	s_waitcnt vmcnt(8)
	s_waitcnt lgkmcnt(0)
	s_barrier
	s_waitcnt lgkmcnt(0)
	v_mfma_f32_16x16x32_bf16 v[60:63], v[128:131], v[198:201], 0
	v_mfma_f32_16x16x32_bf16 v[56:59], v[162:165], v[198:201], 0
	v_mfma_f32_16x16x32_bf16 v[44:47], v[128:131], v[206:209], 0
	v_mfma_f32_16x16x32_bf16 v[40:43], v[162:165], v[206:209], 0
	v_mfma_f32_16x16x32_bf16 v[28:31], v[128:131], v[214:217], 0
	v_mfma_f32_16x16x32_bf16 v[24:27], v[162:165], v[214:217], 0
	v_mfma_f32_16x16x32_bf16 v[12:15], v[128:131], v[222:225], 0
	v_mfma_f32_16x16x32_bf16 v[8:11], v[162:165], v[222:225], 0
	v_mfma_f32_16x16x32_bf16 v[60:63], v[154:157], v[202:205], v[60:63]
	v_mfma_f32_16x16x32_bf16 v[56:59], v[166:169], v[202:205], v[56:59]
	v_mfma_f32_16x16x32_bf16 v[44:47], v[154:157], v[210:213], v[44:47]
	v_mfma_f32_16x16x32_bf16 v[40:43], v[166:169], v[210:213], v[40:43]
	v_mfma_f32_16x16x32_bf16 v[28:31], v[154:157], v[218:221], v[28:31]
	v_mfma_f32_16x16x32_bf16 v[24:27], v[166:169], v[218:221], v[24:27]
	v_mfma_f32_16x16x32_bf16 v[12:15], v[154:157], v[226:229], v[12:15]
	v_mfma_f32_16x16x32_bf16 v[8:11], v[166:169], v[226:229], v[8:11]
	v_mfma_f32_16x16x32_bf16 v[52:55], v[182:185], v[198:201], 0
	v_mfma_f32_16x16x32_bf16 v[48:51], v[190:193], v[198:201], 0
	v_mfma_f32_16x16x32_bf16 v[36:39], v[182:185], v[206:209], 0
	v_mfma_f32_16x16x32_bf16 v[32:35], v[190:193], v[206:209], 0
	v_mfma_f32_16x16x32_bf16 v[20:23], v[182:185], v[214:217], 0
	v_mfma_f32_16x16x32_bf16 v[16:19], v[190:193], v[214:217], 0
	v_mfma_f32_16x16x32_bf16 v[4:7], v[182:185], v[222:225], 0
	v_mfma_f32_16x16x32_bf16 v[0:3], v[190:193], v[222:225], 0
	v_mfma_f32_16x16x32_bf16 v[52:55], v[186:189], v[202:205], v[52:55]
	v_mfma_f32_16x16x32_bf16 v[48:51], v[194:197], v[202:205], v[48:51]
	v_mfma_f32_16x16x32_bf16 v[36:39], v[186:189], v[210:213], v[36:39]
	v_mfma_f32_16x16x32_bf16 v[32:35], v[194:197], v[210:213], v[32:35]
	v_mfma_f32_16x16x32_bf16 v[20:23], v[186:189], v[218:221], v[20:23]
	v_mfma_f32_16x16x32_bf16 v[16:19], v[194:197], v[218:221], v[16:19]
	v_mfma_f32_16x16x32_bf16 v[4:7], v[186:189], v[226:229], v[4:7]
	v_mfma_f32_16x16x32_bf16 v[0:3], v[194:197], v[226:229], v[0:3]
	s_barrier
	s_add_i32 s40, 0, 0x18000
	v_add_u32_e32 v140, s40, v171
	s_add_i32 s41, 0, 0x1c000
	ds_read_b128 v[128:131], v140
	ds_read_b128 v[154:157], v140 offset:1024
	ds_read_b128 v[162:165], v140 offset:2048
	ds_read_b128 v[166:169], v140 offset:3072
	v_add_u32_e32 v140, s41, v171
	ds_read_b128 v[182:185], v140
	ds_read_b128 v[186:189], v140 offset:1024
	ds_read_b128 v[190:193], v140 offset:2048
	ds_read_b128 v[194:197], v140 offset:3072
	s_add_u32 s36, s36, 0x40000
	s_addc_u32 s37, s37, 0
	s_mov_b32 m0, s64
	v_lshl_add_u64 v[236:237], s[36:37], 0, v[132:133]
	ds_read_b128 v[198:201], v179 offset:32768
	ds_read_b128 v[202:205], v179 offset:33792
	ds_read_b128 v[206:209], v179 offset:34816
	ds_read_b128 v[210:213], v179 offset:35840
	ds_read_b128 v[214:217], v179 offset:36864
	ds_read_b128 v[218:221], v179 offset:37888
	ds_read_b128 v[222:225], v179 offset:38912
	ds_read_b128 v[226:229], v179 offset:39936
	global_load_lds_dwordx4 v[236:237], off
	v_lshl_add_u64 v[236:237], s[36:37], 0, v[136:137]
	s_mov_b32 m0, s65
	s_nop 0
	global_load_lds_dwordx4 v[236:237], off
	s_waitcnt vmcnt(8)
	s_waitcnt lgkmcnt(0)
	s_barrier
	s_waitcnt lgkmcnt(0)
	v_mfma_f32_16x16x32_bf16 v[124:127], v[128:131], v[198:201], v[124:127]
	v_mfma_f32_16x16x32_bf16 v[120:123], v[162:165], v[198:201], v[120:123]
	v_mfma_f32_16x16x32_bf16 v[108:111], v[128:131], v[206:209], v[108:111]
	v_mfma_f32_16x16x32_bf16 v[104:107], v[162:165], v[206:209], v[104:107]
	v_mfma_f32_16x16x32_bf16 v[92:95], v[128:131], v[214:217], v[92:95]
	v_mfma_f32_16x16x32_bf16 v[88:91], v[162:165], v[214:217], v[88:91]
	v_mfma_f32_16x16x32_bf16 v[76:79], v[128:131], v[222:225], v[76:79]
	v_mfma_f32_16x16x32_bf16 v[72:75], v[162:165], v[222:225], v[72:75]
	v_mfma_f32_16x16x32_bf16 v[124:127], v[154:157], v[202:205], v[124:127]
	v_mfma_f32_16x16x32_bf16 v[120:123], v[166:169], v[202:205], v[120:123]
	v_mfma_f32_16x16x32_bf16 v[108:111], v[154:157], v[210:213], v[108:111]
	v_mfma_f32_16x16x32_bf16 v[104:107], v[166:169], v[210:213], v[104:107]
	v_mfma_f32_16x16x32_bf16 v[92:95], v[154:157], v[218:221], v[92:95]
	v_mfma_f32_16x16x32_bf16 v[88:91], v[166:169], v[218:221], v[88:91]
	v_mfma_f32_16x16x32_bf16 v[76:79], v[154:157], v[226:229], v[76:79]
	v_mfma_f32_16x16x32_bf16 v[72:75], v[166:169], v[226:229], v[72:75]
	v_mfma_f32_16x16x32_bf16 v[116:119], v[182:185], v[198:201], v[116:119]
	v_mfma_f32_16x16x32_bf16 v[112:115], v[190:193], v[198:201], v[112:115]
	v_mfma_f32_16x16x32_bf16 v[100:103], v[182:185], v[206:209], v[100:103]
	v_mfma_f32_16x16x32_bf16 v[96:99], v[190:193], v[206:209], v[96:99]
	v_mfma_f32_16x16x32_bf16 v[84:87], v[182:185], v[214:217], v[84:87]
	v_mfma_f32_16x16x32_bf16 v[80:83], v[190:193], v[214:217], v[80:83]
	v_mfma_f32_16x16x32_bf16 v[68:71], v[182:185], v[222:225], v[68:71]
	v_mfma_f32_16x16x32_bf16 v[64:67], v[190:193], v[222:225], v[64:67]
	v_mfma_f32_16x16x32_bf16 v[116:119], v[186:189], v[202:205], v[116:119]
	v_mfma_f32_16x16x32_bf16 v[112:115], v[194:197], v[202:205], v[112:115]
	v_mfma_f32_16x16x32_bf16 v[100:103], v[186:189], v[210:213], v[100:103]
	v_mfma_f32_16x16x32_bf16 v[96:99], v[194:197], v[210:213], v[96:99]
	v_mfma_f32_16x16x32_bf16 v[84:87], v[186:189], v[218:221], v[84:87]
	v_mfma_f32_16x16x32_bf16 v[80:83], v[194:197], v[218:221], v[80:83]
	v_mfma_f32_16x16x32_bf16 v[68:71], v[186:189], v[226:229], v[68:71]
	v_mfma_f32_16x16x32_bf16 v[64:67], v[194:197], v[226:229], v[64:67]
	s_barrier
	s_add_i32 s36, s40, s61
	v_lshl_add_u64 v[158:159], v[158:159], 0, s[14:15]
	s_mov_b32 m0, s36
	ds_read_b128 v[198:201], v179 offset:49152
	ds_read_b128 v[202:205], v179 offset:50176
	ds_read_b128 v[206:209], v179 offset:51200
	ds_read_b128 v[210:213], v179 offset:52224
	ds_read_b128 v[214:217], v179 offset:53248
	ds_read_b128 v[218:221], v179 offset:54272
	ds_read_b128 v[222:225], v179 offset:55296
	ds_read_b128 v[226:229], v179 offset:56320
	global_load_lds_dwordx4 v[158:159], off
	s_add_i32 m0, s36, 0x2000
	s_add_u32 s8, s8, 0x40080
	v_lshl_add_u64 v[158:159], v[230:231], 0, s[14:15]
	s_addc_u32 s9, s9, 0
	s_add_i32 s36, s41, s61
	global_load_lds_dwordx4 v[158:159], off
	v_lshl_add_u64 v[158:159], s[8:9], 0, v[134:135]
	s_mov_b32 m0, s36
	s_nop 0
	global_load_lds_dwordx4 v[158:159], off
	v_lshl_add_u64 v[158:159], s[8:9], 0, v[138:139]
	s_add_i32 m0, s36, 0x2000
	s_nop 0
	global_load_lds_dwordx4 v[158:159], off
	v_lshl_add_u64 v[158:159], v[232:233], 0, s[14:15]
	s_mov_b32 m0, s76
	s_nop 0
	global_load_lds_dwordx4 v[158:159], off
	v_lshl_add_u64 v[158:159], v[234:235], 0, s[14:15]
	s_mov_b32 m0, s77
	s_nop 0
	global_load_lds_dwordx4 v[158:159], off
	s_waitcnt vmcnt(8)
	s_waitcnt lgkmcnt(0)
	s_barrier
	s_waitcnt lgkmcnt(0)
	v_mfma_f32_16x16x32_bf16 v[60:63], v[128:131], v[198:201], v[60:63]
	v_mfma_f32_16x16x32_bf16 v[56:59], v[162:165], v[198:201], v[56:59]
	v_mfma_f32_16x16x32_bf16 v[44:47], v[128:131], v[206:209], v[44:47]
	v_mfma_f32_16x16x32_bf16 v[40:43], v[162:165], v[206:209], v[40:43]
	v_mfma_f32_16x16x32_bf16 v[28:31], v[128:131], v[214:217], v[28:31]
	v_mfma_f32_16x16x32_bf16 v[24:27], v[162:165], v[214:217], v[24:27]
	v_mfma_f32_16x16x32_bf16 v[12:15], v[128:131], v[222:225], v[12:15]
	v_mfma_f32_16x16x32_bf16 v[8:11], v[162:165], v[222:225], v[8:11]
	v_mfma_f32_16x16x32_bf16 v[60:63], v[154:157], v[202:205], v[60:63]
	v_mfma_f32_16x16x32_bf16 v[56:59], v[166:169], v[202:205], v[56:59]
	v_mfma_f32_16x16x32_bf16 v[44:47], v[154:157], v[210:213], v[44:47]
	v_mfma_f32_16x16x32_bf16 v[40:43], v[166:169], v[210:213], v[40:43]
	v_mfma_f32_16x16x32_bf16 v[28:31], v[154:157], v[218:221], v[28:31]
	v_mfma_f32_16x16x32_bf16 v[24:27], v[166:169], v[218:221], v[24:27]
	v_mfma_f32_16x16x32_bf16 v[12:15], v[154:157], v[226:229], v[12:15]
	v_mfma_f32_16x16x32_bf16 v[8:11], v[166:169], v[226:229], v[8:11]
	v_mfma_f32_16x16x32_bf16 v[52:55], v[182:185], v[198:201], v[52:55]
	v_mfma_f32_16x16x32_bf16 v[48:51], v[190:193], v[198:201], v[48:51]
	v_mfma_f32_16x16x32_bf16 v[36:39], v[182:185], v[206:209], v[36:39]
	v_mfma_f32_16x16x32_bf16 v[32:35], v[190:193], v[206:209], v[32:35]
	v_mfma_f32_16x16x32_bf16 v[20:23], v[182:185], v[214:217], v[20:23]
	v_mfma_f32_16x16x32_bf16 v[16:19], v[190:193], v[214:217], v[16:19]
	v_mfma_f32_16x16x32_bf16 v[4:7], v[182:185], v[222:225], v[4:7]
	v_mfma_f32_16x16x32_bf16 v[0:3], v[190:193], v[222:225], v[0:3]
	v_mfma_f32_16x16x32_bf16 v[52:55], v[186:189], v[202:205], v[52:55]
	v_mfma_f32_16x16x32_bf16 v[48:51], v[194:197], v[202:205], v[48:51]
	v_mfma_f32_16x16x32_bf16 v[36:39], v[186:189], v[210:213], v[36:39]
	v_mfma_f32_16x16x32_bf16 v[32:35], v[194:197], v[210:213], v[32:35]
	v_mfma_f32_16x16x32_bf16 v[20:23], v[186:189], v[218:221], v[20:23]
	v_mfma_f32_16x16x32_bf16 v[16:19], v[194:197], v[218:221], v[16:19]
	v_mfma_f32_16x16x32_bf16 v[4:7], v[186:189], v[226:229], v[4:7]
	v_mfma_f32_16x16x32_bf16 v[0:3], v[194:197], v[226:229], v[0:3]
	s_barrier
	s_add_i32 s39, s39, 2
	s_add_u32 s0, s0, 0x100
	s_addc_u32 s1, s1, 0
	s_add_u32 s33, s33, 0x100
	s_addc_u32 s38, s38, 0
	s_cmp_gt_u32 s39, 13
	s_cbranch_scc0 .LBB0_799
	s_branch .Lpeel_exit_5
.LBB0_799:
	ds_read_b128 v[128:131], v177
	ds_read_b128 v[154:157], v177 offset:1024
	ds_read_b128 v[162:165], v177 offset:2048
	ds_read_b128 v[166:169], v177 offset:3072
	ds_read_b128 v[182:185], v178
	ds_read_b128 v[186:189], v178 offset:1024
	ds_read_b128 v[190:193], v178 offset:2048
	ds_read_b128 v[194:197], v178 offset:3072
	s_add_u32 s8, s0, 0xfffc0080
	s_addc_u32 s9, s1, -1
	s_cmp_eq_u32 s39, 12
	s_cselect_b32 s37, s3, s9
	s_cselect_b32 s36, s7, s8
	s_cselect_b32 s9, s27, s38
	s_cselect_b32 s8, s29, s33
	v_lshl_add_u64 v[158:159], s[0:1], 0, v[146:147]
	s_add_i32 m0, s62, 0xc000
	ds_read_b128 v[198:201], v179
	ds_read_b128 v[202:205], v179 offset:1024
	ds_read_b128 v[206:209], v179 offset:2048
	ds_read_b128 v[210:213], v179 offset:3072
	ds_read_b128 v[214:217], v179 offset:4096
	ds_read_b128 v[218:221], v179 offset:5120
	ds_read_b128 v[222:225], v179 offset:6144
	ds_read_b128 v[226:229], v179 offset:7168
	global_load_lds_dwordx4 v[158:159], off
	v_lshl_add_u64 v[158:159], s[0:1], 0, v[148:149]
	s_add_i32 m0, s62, 0xe000
	s_nop 0
	global_load_lds_dwordx4 v[158:159], off
	s_waitcnt vmcnt(8)
	s_waitcnt lgkmcnt(0)
	s_barrier
	s_waitcnt lgkmcnt(0)
	v_mfma_f32_16x16x32_bf16 v[124:127], v[128:131], v[198:201], v[124:127]
	v_mfma_f32_16x16x32_bf16 v[120:123], v[162:165], v[198:201], v[120:123]
	v_mfma_f32_16x16x32_bf16 v[108:111], v[128:131], v[206:209], v[108:111]
	v_mfma_f32_16x16x32_bf16 v[104:107], v[162:165], v[206:209], v[104:107]
	v_mfma_f32_16x16x32_bf16 v[92:95], v[128:131], v[214:217], v[92:95]
	v_mfma_f32_16x16x32_bf16 v[88:91], v[162:165], v[214:217], v[88:91]
	v_mfma_f32_16x16x32_bf16 v[76:79], v[128:131], v[222:225], v[76:79]
	v_mfma_f32_16x16x32_bf16 v[72:75], v[162:165], v[222:225], v[72:75]
	v_mfma_f32_16x16x32_bf16 v[124:127], v[154:157], v[202:205], v[124:127]
	v_mfma_f32_16x16x32_bf16 v[120:123], v[166:169], v[202:205], v[120:123]
	v_mfma_f32_16x16x32_bf16 v[108:111], v[154:157], v[210:213], v[108:111]
	v_mfma_f32_16x16x32_bf16 v[104:107], v[166:169], v[210:213], v[104:107]
	v_mfma_f32_16x16x32_bf16 v[92:95], v[154:157], v[218:221], v[92:95]
	v_mfma_f32_16x16x32_bf16 v[88:91], v[166:169], v[218:221], v[88:91]
	v_mfma_f32_16x16x32_bf16 v[76:79], v[154:157], v[226:229], v[76:79]
	v_mfma_f32_16x16x32_bf16 v[72:75], v[166:169], v[226:229], v[72:75]
	v_mfma_f32_16x16x32_bf16 v[116:119], v[182:185], v[198:201], v[116:119]
	v_mfma_f32_16x16x32_bf16 v[112:115], v[190:193], v[198:201], v[112:115]
	v_mfma_f32_16x16x32_bf16 v[100:103], v[182:185], v[206:209], v[100:103]
	v_mfma_f32_16x16x32_bf16 v[96:99], v[190:193], v[206:209], v[96:99]
	v_mfma_f32_16x16x32_bf16 v[84:87], v[182:185], v[214:217], v[84:87]
	v_mfma_f32_16x16x32_bf16 v[80:83], v[190:193], v[214:217], v[80:83]
	v_mfma_f32_16x16x32_bf16 v[68:71], v[182:185], v[222:225], v[68:71]
	v_mfma_f32_16x16x32_bf16 v[64:67], v[190:193], v[222:225], v[64:67]
	v_mfma_f32_16x16x32_bf16 v[116:119], v[186:189], v[202:205], v[116:119]
	v_mfma_f32_16x16x32_bf16 v[112:115], v[194:197], v[202:205], v[112:115]
	v_mfma_f32_16x16x32_bf16 v[100:103], v[186:189], v[210:213], v[100:103]
	v_mfma_f32_16x16x32_bf16 v[96:99], v[194:197], v[210:213], v[96:99]
	v_mfma_f32_16x16x32_bf16 v[84:87], v[186:189], v[218:221], v[84:87]
	v_mfma_f32_16x16x32_bf16 v[80:83], v[194:197], v[218:221], v[80:83]
	v_mfma_f32_16x16x32_bf16 v[68:71], v[186:189], v[226:229], v[68:71]
	v_mfma_f32_16x16x32_bf16 v[64:67], v[194:197], v[226:229], v[64:67]
	s_barrier
	s_add_i32 s40, s78, s61
	v_lshl_add_u64 v[158:159], s[8:9], 0, v[134:135]
	s_mov_b32 m0, s40
	ds_read_b128 v[198:201], v179 offset:16384
	ds_read_b128 v[202:205], v179 offset:17408
	ds_read_b128 v[206:209], v179 offset:18432
	ds_read_b128 v[210:213], v179 offset:19456
	ds_read_b128 v[214:217], v179 offset:20480
	ds_read_b128 v[218:221], v179 offset:21504
	ds_read_b128 v[222:225], v179 offset:22528
	ds_read_b128 v[226:229], v179 offset:23552
	global_load_lds_dwordx4 v[158:159], off
	s_add_i32 m0, s40, 0x2000
	s_add_u32 s40, s8, 0x40000
	v_lshl_add_u64 v[230:231], s[8:9], 0, v[138:139]
	s_addc_u32 s41, s9, 0
	s_add_i32 s42, s79, s61
	global_load_lds_dwordx4 v[230:231], off
	v_lshl_add_u64 v[232:233], s[40:41], 0, v[134:135]
	s_mov_b32 m0, s42
	v_lshl_add_u64 v[234:235], s[36:37], 0, v[136:137]
	global_load_lds_dwordx4 v[232:233], off
	v_lshl_add_u64 v[232:233], s[40:41], 0, v[138:139]
	s_add_i32 m0, s42, 0x2000
	s_nop 0
	global_load_lds_dwordx4 v[232:233], off
	v_lshl_add_u64 v[232:233], s[36:37], 0, v[132:133]
	s_mov_b32 m0, s62
	s_nop 0
	global_load_lds_dwordx4 v[232:233], off
	s_mov_b32 m0, s63
	s_nop 0
	global_load_lds_dwordx4 v[234:235], off
	s_waitcnt vmcnt(8)
	s_waitcnt lgkmcnt(0)
	s_barrier
	s_waitcnt lgkmcnt(0)
	v_mfma_f32_16x16x32_bf16 v[60:63], v[128:131], v[198:201], v[60:63]
	v_mfma_f32_16x16x32_bf16 v[56:59], v[162:165], v[198:201], v[56:59]
	v_mfma_f32_16x16x32_bf16 v[44:47], v[128:131], v[206:209], v[44:47]
	v_mfma_f32_16x16x32_bf16 v[40:43], v[162:165], v[206:209], v[40:43]
	v_mfma_f32_16x16x32_bf16 v[28:31], v[128:131], v[214:217], v[28:31]
	v_mfma_f32_16x16x32_bf16 v[24:27], v[162:165], v[214:217], v[24:27]
	v_mfma_f32_16x16x32_bf16 v[12:15], v[128:131], v[222:225], v[12:15]
	v_mfma_f32_16x16x32_bf16 v[8:11], v[162:165], v[222:225], v[8:11]
	v_mfma_f32_16x16x32_bf16 v[60:63], v[154:157], v[202:205], v[60:63]
	v_mfma_f32_16x16x32_bf16 v[56:59], v[166:169], v[202:205], v[56:59]
	v_mfma_f32_16x16x32_bf16 v[44:47], v[154:157], v[210:213], v[44:47]
	v_mfma_f32_16x16x32_bf16 v[40:43], v[166:169], v[210:213], v[40:43]
	v_mfma_f32_16x16x32_bf16 v[28:31], v[154:157], v[218:221], v[28:31]
	v_mfma_f32_16x16x32_bf16 v[24:27], v[166:169], v[218:221], v[24:27]
	v_mfma_f32_16x16x32_bf16 v[12:15], v[154:157], v[226:229], v[12:15]
	v_mfma_f32_16x16x32_bf16 v[8:11], v[166:169], v[226:229], v[8:11]
	v_mfma_f32_16x16x32_bf16 v[52:55], v[182:185], v[198:201], v[52:55]
	v_mfma_f32_16x16x32_bf16 v[48:51], v[190:193], v[198:201], v[48:51]
	v_mfma_f32_16x16x32_bf16 v[36:39], v[182:185], v[206:209], v[36:39]
	v_mfma_f32_16x16x32_bf16 v[32:35], v[190:193], v[206:209], v[32:35]
	v_mfma_f32_16x16x32_bf16 v[20:23], v[182:185], v[214:217], v[20:23]
	v_mfma_f32_16x16x32_bf16 v[16:19], v[190:193], v[214:217], v[16:19]
	v_mfma_f32_16x16x32_bf16 v[4:7], v[182:185], v[222:225], v[4:7]
	v_mfma_f32_16x16x32_bf16 v[0:3], v[190:193], v[222:225], v[0:3]
	v_mfma_f32_16x16x32_bf16 v[52:55], v[186:189], v[202:205], v[52:55]
	v_mfma_f32_16x16x32_bf16 v[48:51], v[194:197], v[202:205], v[48:51]
	v_mfma_f32_16x16x32_bf16 v[36:39], v[186:189], v[210:213], v[36:39]
	v_mfma_f32_16x16x32_bf16 v[32:35], v[194:197], v[210:213], v[32:35]
	v_mfma_f32_16x16x32_bf16 v[20:23], v[186:189], v[218:221], v[20:23]
	v_mfma_f32_16x16x32_bf16 v[16:19], v[194:197], v[218:221], v[16:19]
	v_mfma_f32_16x16x32_bf16 v[4:7], v[186:189], v[226:229], v[4:7]
	v_mfma_f32_16x16x32_bf16 v[0:3], v[194:197], v[226:229], v[0:3]
	s_barrier
	s_add_i32 s40, 0, 0x18000
	v_add_u32_e32 v140, s40, v171
	s_add_i32 s41, 0, 0x1c000
	ds_read_b128 v[128:131], v140
	ds_read_b128 v[154:157], v140 offset:1024
	ds_read_b128 v[162:165], v140 offset:2048
	ds_read_b128 v[166:169], v140 offset:3072
	v_add_u32_e32 v140, s41, v171
	ds_read_b128 v[182:185], v140
	ds_read_b128 v[186:189], v140 offset:1024
	ds_read_b128 v[190:193], v140 offset:2048
	ds_read_b128 v[194:197], v140 offset:3072
	s_add_u32 s36, s36, 0x40000
	s_addc_u32 s37, s37, 0
	s_mov_b32 m0, s64
	v_lshl_add_u64 v[236:237], s[36:37], 0, v[132:133]
	ds_read_b128 v[198:201], v179 offset:32768
	ds_read_b128 v[202:205], v179 offset:33792
	ds_read_b128 v[206:209], v179 offset:34816
	ds_read_b128 v[210:213], v179 offset:35840
	ds_read_b128 v[214:217], v179 offset:36864
	ds_read_b128 v[218:221], v179 offset:37888
	ds_read_b128 v[222:225], v179 offset:38912
	ds_read_b128 v[226:229], v179 offset:39936
	global_load_lds_dwordx4 v[236:237], off
	v_lshl_add_u64 v[236:237], s[36:37], 0, v[136:137]
	s_mov_b32 m0, s65
	s_nop 0
	global_load_lds_dwordx4 v[236:237], off
	s_waitcnt vmcnt(8)
	s_waitcnt lgkmcnt(0)
	s_barrier
	s_waitcnt lgkmcnt(0)
	v_mfma_f32_16x16x32_bf16 v[124:127], v[128:131], v[198:201], v[124:127]
	v_mfma_f32_16x16x32_bf16 v[120:123], v[162:165], v[198:201], v[120:123]
	v_mfma_f32_16x16x32_bf16 v[108:111], v[128:131], v[206:209], v[108:111]
	v_mfma_f32_16x16x32_bf16 v[104:107], v[162:165], v[206:209], v[104:107]
	v_mfma_f32_16x16x32_bf16 v[92:95], v[128:131], v[214:217], v[92:95]
	v_mfma_f32_16x16x32_bf16 v[88:91], v[162:165], v[214:217], v[88:91]
	v_mfma_f32_16x16x32_bf16 v[76:79], v[128:131], v[222:225], v[76:79]
	v_mfma_f32_16x16x32_bf16 v[72:75], v[162:165], v[222:225], v[72:75]
	v_mfma_f32_16x16x32_bf16 v[124:127], v[154:157], v[202:205], v[124:127]
	v_mfma_f32_16x16x32_bf16 v[120:123], v[166:169], v[202:205], v[120:123]
	v_mfma_f32_16x16x32_bf16 v[108:111], v[154:157], v[210:213], v[108:111]
	v_mfma_f32_16x16x32_bf16 v[104:107], v[166:169], v[210:213], v[104:107]
	v_mfma_f32_16x16x32_bf16 v[92:95], v[154:157], v[218:221], v[92:95]
	v_mfma_f32_16x16x32_bf16 v[88:91], v[166:169], v[218:221], v[88:91]
	v_mfma_f32_16x16x32_bf16 v[76:79], v[154:157], v[226:229], v[76:79]
	v_mfma_f32_16x16x32_bf16 v[72:75], v[166:169], v[226:229], v[72:75]
	v_mfma_f32_16x16x32_bf16 v[116:119], v[182:185], v[198:201], v[116:119]
	v_mfma_f32_16x16x32_bf16 v[112:115], v[190:193], v[198:201], v[112:115]
	v_mfma_f32_16x16x32_bf16 v[100:103], v[182:185], v[206:209], v[100:103]
	v_mfma_f32_16x16x32_bf16 v[96:99], v[190:193], v[206:209], v[96:99]
	v_mfma_f32_16x16x32_bf16 v[84:87], v[182:185], v[214:217], v[84:87]
	v_mfma_f32_16x16x32_bf16 v[80:83], v[190:193], v[214:217], v[80:83]
	v_mfma_f32_16x16x32_bf16 v[68:71], v[182:185], v[222:225], v[68:71]
	v_mfma_f32_16x16x32_bf16 v[64:67], v[190:193], v[222:225], v[64:67]
	v_mfma_f32_16x16x32_bf16 v[116:119], v[186:189], v[202:205], v[116:119]
	v_mfma_f32_16x16x32_bf16 v[112:115], v[194:197], v[202:205], v[112:115]
	v_mfma_f32_16x16x32_bf16 v[100:103], v[186:189], v[210:213], v[100:103]
	v_mfma_f32_16x16x32_bf16 v[96:99], v[194:197], v[210:213], v[96:99]
	v_mfma_f32_16x16x32_bf16 v[84:87], v[186:189], v[218:221], v[84:87]
	v_mfma_f32_16x16x32_bf16 v[80:83], v[194:197], v[218:221], v[80:83]
	v_mfma_f32_16x16x32_bf16 v[68:71], v[186:189], v[226:229], v[68:71]
	v_mfma_f32_16x16x32_bf16 v[64:67], v[194:197], v[226:229], v[64:67]
	s_barrier
	s_add_i32 s36, s40, s61
	v_lshl_add_u64 v[158:159], v[158:159], 0, s[14:15]
	s_mov_b32 m0, s36
	ds_read_b128 v[198:201], v179 offset:49152
	ds_read_b128 v[202:205], v179 offset:50176
	ds_read_b128 v[206:209], v179 offset:51200
	ds_read_b128 v[210:213], v179 offset:52224
	ds_read_b128 v[214:217], v179 offset:53248
	ds_read_b128 v[218:221], v179 offset:54272
	ds_read_b128 v[222:225], v179 offset:55296
	ds_read_b128 v[226:229], v179 offset:56320
	global_load_lds_dwordx4 v[158:159], off
	s_add_i32 m0, s36, 0x2000
	s_add_u32 s8, s8, 0x40080
	v_lshl_add_u64 v[158:159], v[230:231], 0, s[14:15]
	s_addc_u32 s9, s9, 0
	s_add_i32 s36, s41, s61
	global_load_lds_dwordx4 v[158:159], off
	v_lshl_add_u64 v[158:159], s[8:9], 0, v[134:135]
	s_mov_b32 m0, s36
	s_nop 0
	global_load_lds_dwordx4 v[158:159], off
	v_lshl_add_u64 v[158:159], s[8:9], 0, v[138:139]
	s_add_i32 m0, s36, 0x2000
	s_nop 0
	global_load_lds_dwordx4 v[158:159], off
	v_lshl_add_u64 v[158:159], v[232:233], 0, s[14:15]
	s_mov_b32 m0, s76
	s_nop 0
	global_load_lds_dwordx4 v[158:159], off
	v_lshl_add_u64 v[158:159], v[234:235], 0, s[14:15]
	s_mov_b32 m0, s77
	s_nop 0
	global_load_lds_dwordx4 v[158:159], off
	s_waitcnt vmcnt(8)
	s_waitcnt lgkmcnt(0)
	s_barrier
	s_waitcnt lgkmcnt(0)
	v_mfma_f32_16x16x32_bf16 v[60:63], v[128:131], v[198:201], v[60:63]
	v_mfma_f32_16x16x32_bf16 v[56:59], v[162:165], v[198:201], v[56:59]
	v_mfma_f32_16x16x32_bf16 v[44:47], v[128:131], v[206:209], v[44:47]
	v_mfma_f32_16x16x32_bf16 v[40:43], v[162:165], v[206:209], v[40:43]
	v_mfma_f32_16x16x32_bf16 v[28:31], v[128:131], v[214:217], v[28:31]
	v_mfma_f32_16x16x32_bf16 v[24:27], v[162:165], v[214:217], v[24:27]
	v_mfma_f32_16x16x32_bf16 v[12:15], v[128:131], v[222:225], v[12:15]
	v_mfma_f32_16x16x32_bf16 v[8:11], v[162:165], v[222:225], v[8:11]
	v_mfma_f32_16x16x32_bf16 v[60:63], v[154:157], v[202:205], v[60:63]
	v_mfma_f32_16x16x32_bf16 v[56:59], v[166:169], v[202:205], v[56:59]
	v_mfma_f32_16x16x32_bf16 v[44:47], v[154:157], v[210:213], v[44:47]
	v_mfma_f32_16x16x32_bf16 v[40:43], v[166:169], v[210:213], v[40:43]
	v_mfma_f32_16x16x32_bf16 v[28:31], v[154:157], v[218:221], v[28:31]
	v_mfma_f32_16x16x32_bf16 v[24:27], v[166:169], v[218:221], v[24:27]
	v_mfma_f32_16x16x32_bf16 v[12:15], v[154:157], v[226:229], v[12:15]
	v_mfma_f32_16x16x32_bf16 v[8:11], v[166:169], v[226:229], v[8:11]
	v_mfma_f32_16x16x32_bf16 v[52:55], v[182:185], v[198:201], v[52:55]
	v_mfma_f32_16x16x32_bf16 v[48:51], v[190:193], v[198:201], v[48:51]
	v_mfma_f32_16x16x32_bf16 v[36:39], v[182:185], v[206:209], v[36:39]
	v_mfma_f32_16x16x32_bf16 v[32:35], v[190:193], v[206:209], v[32:35]
	v_mfma_f32_16x16x32_bf16 v[20:23], v[182:185], v[214:217], v[20:23]
	v_mfma_f32_16x16x32_bf16 v[16:19], v[190:193], v[214:217], v[16:19]
	v_mfma_f32_16x16x32_bf16 v[4:7], v[182:185], v[222:225], v[4:7]
	v_mfma_f32_16x16x32_bf16 v[0:3], v[190:193], v[222:225], v[0:3]
	v_mfma_f32_16x16x32_bf16 v[52:55], v[186:189], v[202:205], v[52:55]
	v_mfma_f32_16x16x32_bf16 v[48:51], v[194:197], v[202:205], v[48:51]
	v_mfma_f32_16x16x32_bf16 v[36:39], v[186:189], v[210:213], v[36:39]
	v_mfma_f32_16x16x32_bf16 v[32:35], v[194:197], v[210:213], v[32:35]
	v_mfma_f32_16x16x32_bf16 v[20:23], v[186:189], v[218:221], v[20:23]
	v_mfma_f32_16x16x32_bf16 v[16:19], v[194:197], v[218:221], v[16:19]
	v_mfma_f32_16x16x32_bf16 v[4:7], v[186:189], v[226:229], v[4:7]
	v_mfma_f32_16x16x32_bf16 v[0:3], v[194:197], v[226:229], v[0:3]
	s_barrier
	s_add_i32 s39, s39, 2
	s_add_u32 s0, s0, 0x100
	s_addc_u32 s1, s1, 0
	s_add_u32 s33, s33, 0x100
	s_addc_u32 s38, s38, 0
	s_cmp_gt_u32 s39, 13
	s_cbranch_scc0 .LBB0_799

.LBB0_1402:
	s_ashr_i32 s17, s16, 31
	s_lshl_b64 s[18:19], s[16:17], 19
	s_add_u32 s18, s76, s18
	s_addc_u32 s19, s78, s19
	s_and_b64 s[20:21], s[6:7], exec
	s_cselect_b32 s17, s19, s1
	s_cselect_b32 s33, s18, s0
	s_ashr_i32 s15, s14, 31
	s_lshl_b64 s[20:21], s[14:15], 19
	s_add_u32 s20, s31, s20
	s_addc_u32 s21, s34, s21
	s_and_b64 s[28:29], s[6:7], exec
	s_cselect_b32 s15, s21, s27
	s_cselect_b32 s50, s20, s26
	s_add_u32 s0, s0, 0x40080
	s_addc_u32 s1, s1, 0
	s_add_u32 s51, s26, 0x100
	s_addc_u32 s52, s27, 0
	s_mov_b32 s53, -2
	s_waitcnt lgkmcnt(0)
	ds_read_b128 v[128:131], v193
	ds_read_b128 v[132:135], v193 offset:1024
	ds_read_b128 v[136:139], v193 offset:2048
	ds_read_b128 v[140:143], v193 offset:3072
	ds_read_b128 v[144:147], v194
	ds_read_b128 v[148:151], v194 offset:1024
	ds_read_b128 v[152:155], v194 offset:2048
	ds_read_b128 v[156:159], v194 offset:3072
	s_add_u32 s26, s0, 0xfffc0080
	s_addc_u32 s27, s1, -1
	s_cmp_eq_u32 s53, 12
	s_cselect_b32 s29, s17, s27
	s_cselect_b32 s28, s33, s26
	s_cselect_b32 s27, s15, s52
	s_cselect_b32 s26, s50, s51
	v_lshl_add_u64 v[224:225], s[0:1], 0, v[170:171]
	s_add_i32 m0, s23, 0xc000
	ds_read_b128 v[178:181], v195
	ds_read_b128 v[196:199], v195 offset:1024
	ds_read_b128 v[200:203], v195 offset:2048
	ds_read_b128 v[204:207], v195 offset:3072
	ds_read_b128 v[208:211], v195 offset:4096
	ds_read_b128 v[212:215], v195 offset:5120
	ds_read_b128 v[216:219], v195 offset:6144
	ds_read_b128 v[220:223], v195 offset:7168
	global_load_lds_dwordx4 v[224:225], off
	v_lshl_add_u64 v[224:225], s[0:1], 0, v[172:173]
	s_add_i32 m0, s23, 0xe000
	s_nop 0
	global_load_lds_dwordx4 v[224:225], off
	s_waitcnt vmcnt(8)
	s_waitcnt lgkmcnt(0)
	s_barrier
	s_waitcnt lgkmcnt(0)
	v_mfma_f32_16x16x32_bf16 v[124:127], v[128:131], v[178:181], 0
	v_mfma_f32_16x16x32_bf16 v[120:123], v[136:139], v[178:181], 0
	v_mfma_f32_16x16x32_bf16 v[108:111], v[128:131], v[200:203], 0
	v_mfma_f32_16x16x32_bf16 v[104:107], v[136:139], v[200:203], 0
	v_mfma_f32_16x16x32_bf16 v[92:95], v[128:131], v[208:211], 0
	v_mfma_f32_16x16x32_bf16 v[88:91], v[136:139], v[208:211], 0
	v_mfma_f32_16x16x32_bf16 v[76:79], v[128:131], v[216:219], 0
	v_mfma_f32_16x16x32_bf16 v[72:75], v[136:139], v[216:219], 0
	v_mfma_f32_16x16x32_bf16 v[124:127], v[132:135], v[196:199], v[124:127]
	v_mfma_f32_16x16x32_bf16 v[120:123], v[140:143], v[196:199], v[120:123]
	v_mfma_f32_16x16x32_bf16 v[108:111], v[132:135], v[204:207], v[108:111]
	v_mfma_f32_16x16x32_bf16 v[104:107], v[140:143], v[204:207], v[104:107]
	v_mfma_f32_16x16x32_bf16 v[92:95], v[132:135], v[212:215], v[92:95]
	v_mfma_f32_16x16x32_bf16 v[88:91], v[140:143], v[212:215], v[88:91]
	v_mfma_f32_16x16x32_bf16 v[76:79], v[132:135], v[220:223], v[76:79]
	v_mfma_f32_16x16x32_bf16 v[72:75], v[140:143], v[220:223], v[72:75]
	v_mfma_f32_16x16x32_bf16 v[116:119], v[144:147], v[178:181], 0
	v_mfma_f32_16x16x32_bf16 v[112:115], v[152:155], v[178:181], 0
	v_mfma_f32_16x16x32_bf16 v[100:103], v[144:147], v[200:203], 0
	v_mfma_f32_16x16x32_bf16 v[96:99], v[152:155], v[200:203], 0
	v_mfma_f32_16x16x32_bf16 v[84:87], v[144:147], v[208:211], 0
	v_mfma_f32_16x16x32_bf16 v[80:83], v[152:155], v[208:211], 0
	v_mfma_f32_16x16x32_bf16 v[68:71], v[144:147], v[216:219], 0
	v_mfma_f32_16x16x32_bf16 v[64:67], v[152:155], v[216:219], 0
	v_mfma_f32_16x16x32_bf16 v[116:119], v[148:151], v[196:199], v[116:119]
	v_mfma_f32_16x16x32_bf16 v[112:115], v[156:159], v[196:199], v[112:115]
	v_mfma_f32_16x16x32_bf16 v[100:103], v[148:151], v[204:207], v[100:103]
	v_mfma_f32_16x16x32_bf16 v[96:99], v[156:159], v[204:207], v[96:99]
	v_mfma_f32_16x16x32_bf16 v[84:87], v[148:151], v[212:215], v[84:87]
	v_mfma_f32_16x16x32_bf16 v[80:83], v[156:159], v[212:215], v[80:83]
	v_mfma_f32_16x16x32_bf16 v[68:71], v[148:151], v[220:223], v[68:71]
	v_mfma_f32_16x16x32_bf16 v[64:67], v[156:159], v[220:223], v[64:67]
	s_barrier
	s_add_i32 s54, s44, s35
	v_lshl_add_u64 v[224:225], s[26:27], 0, v[164:165]
	s_mov_b32 m0, s54
	ds_read_b128 v[178:181], v195 offset:16384
	ds_read_b128 v[196:199], v195 offset:17408
	ds_read_b128 v[200:203], v195 offset:18432
	ds_read_b128 v[204:207], v195 offset:19456
	ds_read_b128 v[208:211], v195 offset:20480
	ds_read_b128 v[212:215], v195 offset:21504
	ds_read_b128 v[216:219], v195 offset:22528
	ds_read_b128 v[220:223], v195 offset:23552
	global_load_lds_dwordx4 v[224:225], off
	s_add_i32 m0, s54, 0x2000
	s_add_u32 s54, s26, 0x40000
	v_lshl_add_u64 v[226:227], s[26:27], 0, v[168:169]
	s_addc_u32 s55, s27, 0
	s_add_i32 s56, s45, s35
	global_load_lds_dwordx4 v[226:227], off
	v_lshl_add_u64 v[228:229], s[54:55], 0, v[164:165]
	s_mov_b32 m0, s56
	v_lshl_add_u64 v[230:231], s[28:29], 0, v[166:167]
	global_load_lds_dwordx4 v[228:229], off
	v_lshl_add_u64 v[228:229], s[54:55], 0, v[168:169]
	s_add_i32 m0, s56, 0x2000
	s_nop 0
	global_load_lds_dwordx4 v[228:229], off
	v_lshl_add_u64 v[228:229], s[28:29], 0, v[162:163]
	s_mov_b32 m0, s23
	s_nop 0
	global_load_lds_dwordx4 v[228:229], off
	s_mov_b32 m0, s25
	s_nop 0
	global_load_lds_dwordx4 v[230:231], off
	s_waitcnt vmcnt(8)
	s_waitcnt lgkmcnt(0)
	s_barrier
	s_waitcnt lgkmcnt(0)
	v_mfma_f32_16x16x32_bf16 v[60:63], v[128:131], v[178:181], 0
	v_mfma_f32_16x16x32_bf16 v[56:59], v[136:139], v[178:181], 0
	v_mfma_f32_16x16x32_bf16 v[44:47], v[128:131], v[200:203], 0
	v_mfma_f32_16x16x32_bf16 v[40:43], v[136:139], v[200:203], 0
	v_mfma_f32_16x16x32_bf16 v[28:31], v[128:131], v[208:211], 0
	v_mfma_f32_16x16x32_bf16 v[24:27], v[136:139], v[208:211], 0
	v_mfma_f32_16x16x32_bf16 v[12:15], v[128:131], v[216:219], 0
	v_mfma_f32_16x16x32_bf16 v[8:11], v[136:139], v[216:219], 0
	v_mfma_f32_16x16x32_bf16 v[60:63], v[132:135], v[196:199], v[60:63]
	v_mfma_f32_16x16x32_bf16 v[56:59], v[140:143], v[196:199], v[56:59]
	v_mfma_f32_16x16x32_bf16 v[44:47], v[132:135], v[204:207], v[44:47]
	v_mfma_f32_16x16x32_bf16 v[40:43], v[140:143], v[204:207], v[40:43]
	v_mfma_f32_16x16x32_bf16 v[28:31], v[132:135], v[212:215], v[28:31]
	v_mfma_f32_16x16x32_bf16 v[24:27], v[140:143], v[212:215], v[24:27]
	v_mfma_f32_16x16x32_bf16 v[12:15], v[132:135], v[220:223], v[12:15]
	v_mfma_f32_16x16x32_bf16 v[8:11], v[140:143], v[220:223], v[8:11]
	v_mfma_f32_16x16x32_bf16 v[52:55], v[144:147], v[178:181], 0
	v_mfma_f32_16x16x32_bf16 v[48:51], v[152:155], v[178:181], 0
	v_mfma_f32_16x16x32_bf16 v[36:39], v[144:147], v[200:203], 0
	v_mfma_f32_16x16x32_bf16 v[32:35], v[152:155], v[200:203], 0
	v_mfma_f32_16x16x32_bf16 v[20:23], v[144:147], v[208:211], 0
	v_mfma_f32_16x16x32_bf16 v[16:19], v[152:155], v[208:211], 0
	v_mfma_f32_16x16x32_bf16 v[4:7], v[144:147], v[216:219], 0
	v_mfma_f32_16x16x32_bf16 v[0:3], v[152:155], v[216:219], 0
	v_mfma_f32_16x16x32_bf16 v[52:55], v[148:151], v[196:199], v[52:55]
	v_mfma_f32_16x16x32_bf16 v[48:51], v[156:159], v[196:199], v[48:51]
	v_mfma_f32_16x16x32_bf16 v[36:39], v[148:151], v[204:207], v[36:39]
	v_mfma_f32_16x16x32_bf16 v[32:35], v[156:159], v[204:207], v[32:35]
	v_mfma_f32_16x16x32_bf16 v[20:23], v[148:151], v[212:215], v[20:23]
	v_mfma_f32_16x16x32_bf16 v[16:19], v[156:159], v[212:215], v[16:19]
	v_mfma_f32_16x16x32_bf16 v[4:7], v[148:151], v[220:223], v[4:7]
	v_mfma_f32_16x16x32_bf16 v[0:3], v[156:159], v[220:223], v[0:3]
	s_barrier
	s_add_i32 s54, 0, 0x18000
	s_add_i32 s55, 0, 0x1c000
	v_add_u32_e32 v140, s54, v188
	v_add_u32_e32 v156, s55, v188
	ds_read_b128 v[128:131], v140
	ds_read_b128 v[132:135], v140 offset:1024
	ds_read_b128 v[136:139], v140 offset:2048
	ds_read_b128 v[140:143], v140 offset:3072
	ds_read_b128 v[144:147], v156
	ds_read_b128 v[148:151], v156 offset:1024
	ds_read_b128 v[152:155], v156 offset:2048
	ds_read_b128 v[156:159], v156 offset:3072
	s_add_u32 s28, s28, 0x40000
	s_addc_u32 s29, s29, 0
	s_mov_b32 m0, s36
	v_lshl_add_u64 v[232:233], s[28:29], 0, v[162:163]
	ds_read_b128 v[178:181], v195 offset:32768
	ds_read_b128 v[196:199], v195 offset:33792
	ds_read_b128 v[200:203], v195 offset:34816
	ds_read_b128 v[204:207], v195 offset:35840
	ds_read_b128 v[208:211], v195 offset:36864
	ds_read_b128 v[212:215], v195 offset:37888
	ds_read_b128 v[216:219], v195 offset:38912
	ds_read_b128 v[220:223], v195 offset:39936
	global_load_lds_dwordx4 v[232:233], off
	v_lshl_add_u64 v[232:233], s[28:29], 0, v[166:167]
	s_mov_b32 m0, s37
	s_nop 0
	global_load_lds_dwordx4 v[232:233], off
	s_waitcnt vmcnt(8)
	s_waitcnt lgkmcnt(0)
	s_barrier
	s_waitcnt lgkmcnt(0)
	v_mfma_f32_16x16x32_bf16 v[124:127], v[128:131], v[178:181], v[124:127]
	v_mfma_f32_16x16x32_bf16 v[120:123], v[136:139], v[178:181], v[120:123]
	v_mfma_f32_16x16x32_bf16 v[108:111], v[128:131], v[200:203], v[108:111]
	v_mfma_f32_16x16x32_bf16 v[104:107], v[136:139], v[200:203], v[104:107]
	v_mfma_f32_16x16x32_bf16 v[92:95], v[128:131], v[208:211], v[92:95]
	v_mfma_f32_16x16x32_bf16 v[88:91], v[136:139], v[208:211], v[88:91]
	v_mfma_f32_16x16x32_bf16 v[76:79], v[128:131], v[216:219], v[76:79]
	v_mfma_f32_16x16x32_bf16 v[72:75], v[136:139], v[216:219], v[72:75]
	v_mfma_f32_16x16x32_bf16 v[124:127], v[132:135], v[196:199], v[124:127]
	v_mfma_f32_16x16x32_bf16 v[120:123], v[140:143], v[196:199], v[120:123]
	v_mfma_f32_16x16x32_bf16 v[108:111], v[132:135], v[204:207], v[108:111]
	v_mfma_f32_16x16x32_bf16 v[104:107], v[140:143], v[204:207], v[104:107]
	v_mfma_f32_16x16x32_bf16 v[92:95], v[132:135], v[212:215], v[92:95]
	v_mfma_f32_16x16x32_bf16 v[88:91], v[140:143], v[212:215], v[88:91]
	v_mfma_f32_16x16x32_bf16 v[76:79], v[132:135], v[220:223], v[76:79]
	v_mfma_f32_16x16x32_bf16 v[72:75], v[140:143], v[220:223], v[72:75]
	v_mfma_f32_16x16x32_bf16 v[116:119], v[144:147], v[178:181], v[116:119]
	v_mfma_f32_16x16x32_bf16 v[112:115], v[152:155], v[178:181], v[112:115]
	v_mfma_f32_16x16x32_bf16 v[100:103], v[144:147], v[200:203], v[100:103]
	v_mfma_f32_16x16x32_bf16 v[96:99], v[152:155], v[200:203], v[96:99]
	v_mfma_f32_16x16x32_bf16 v[84:87], v[144:147], v[208:211], v[84:87]
	v_mfma_f32_16x16x32_bf16 v[80:83], v[152:155], v[208:211], v[80:83]
	v_mfma_f32_16x16x32_bf16 v[68:71], v[144:147], v[216:219], v[68:71]
	v_mfma_f32_16x16x32_bf16 v[64:67], v[152:155], v[216:219], v[64:67]
	v_mfma_f32_16x16x32_bf16 v[116:119], v[148:151], v[196:199], v[116:119]
	v_mfma_f32_16x16x32_bf16 v[112:115], v[156:159], v[196:199], v[112:115]
	v_mfma_f32_16x16x32_bf16 v[100:103], v[148:151], v[204:207], v[100:103]
	v_mfma_f32_16x16x32_bf16 v[96:99], v[156:159], v[204:207], v[96:99]
	v_mfma_f32_16x16x32_bf16 v[84:87], v[148:151], v[212:215], v[84:87]
	v_mfma_f32_16x16x32_bf16 v[80:83], v[156:159], v[212:215], v[80:83]
	v_mfma_f32_16x16x32_bf16 v[68:71], v[148:151], v[220:223], v[68:71]
	v_mfma_f32_16x16x32_bf16 v[64:67], v[156:159], v[220:223], v[64:67]
	s_barrier
	s_add_i32 s28, s54, s35
	v_lshl_add_u64 v[224:225], v[224:225], 0, s[10:11]
	s_mov_b32 m0, s28
	ds_read_b128 v[178:181], v195 offset:49152
	ds_read_b128 v[196:199], v195 offset:50176
	ds_read_b128 v[200:203], v195 offset:51200
	ds_read_b128 v[204:207], v195 offset:52224
	ds_read_b128 v[208:211], v195 offset:53248
	ds_read_b128 v[212:215], v195 offset:54272
	ds_read_b128 v[216:219], v195 offset:55296
	ds_read_b128 v[220:223], v195 offset:56320
	global_load_lds_dwordx4 v[224:225], off
	s_add_i32 m0, s28, 0x2000
	s_add_u32 s26, s26, 0x40080
	v_lshl_add_u64 v[224:225], v[226:227], 0, s[10:11]
	s_addc_u32 s27, s27, 0
	s_add_i32 s28, s55, s35
	global_load_lds_dwordx4 v[224:225], off
	v_lshl_add_u64 v[224:225], s[26:27], 0, v[164:165]
	s_mov_b32 m0, s28
	s_nop 0
	global_load_lds_dwordx4 v[224:225], off
	v_lshl_add_u64 v[224:225], s[26:27], 0, v[168:169]
	s_add_i32 m0, s28, 0x2000
	s_nop 0
	global_load_lds_dwordx4 v[224:225], off
	v_lshl_add_u64 v[224:225], v[228:229], 0, s[10:11]
	s_mov_b32 m0, s40
	s_nop 0
	global_load_lds_dwordx4 v[224:225], off
	v_lshl_add_u64 v[224:225], v[230:231], 0, s[10:11]
	s_mov_b32 m0, s41
	s_nop 0
	global_load_lds_dwordx4 v[224:225], off
	s_waitcnt vmcnt(8)
	s_waitcnt lgkmcnt(0)
	s_barrier
	s_waitcnt lgkmcnt(0)
	v_mfma_f32_16x16x32_bf16 v[60:63], v[128:131], v[178:181], v[60:63]
	v_mfma_f32_16x16x32_bf16 v[56:59], v[136:139], v[178:181], v[56:59]
	v_mfma_f32_16x16x32_bf16 v[44:47], v[128:131], v[200:203], v[44:47]
	v_mfma_f32_16x16x32_bf16 v[40:43], v[136:139], v[200:203], v[40:43]
	v_mfma_f32_16x16x32_bf16 v[28:31], v[128:131], v[208:211], v[28:31]
	v_mfma_f32_16x16x32_bf16 v[24:27], v[136:139], v[208:211], v[24:27]
	v_mfma_f32_16x16x32_bf16 v[12:15], v[128:131], v[216:219], v[12:15]
	v_mfma_f32_16x16x32_bf16 v[8:11], v[136:139], v[216:219], v[8:11]
	v_mfma_f32_16x16x32_bf16 v[60:63], v[132:135], v[196:199], v[60:63]
	v_mfma_f32_16x16x32_bf16 v[56:59], v[140:143], v[196:199], v[56:59]
	v_mfma_f32_16x16x32_bf16 v[44:47], v[132:135], v[204:207], v[44:47]
	v_mfma_f32_16x16x32_bf16 v[40:43], v[140:143], v[204:207], v[40:43]
	v_mfma_f32_16x16x32_bf16 v[28:31], v[132:135], v[212:215], v[28:31]
	v_mfma_f32_16x16x32_bf16 v[24:27], v[140:143], v[212:215], v[24:27]
	v_mfma_f32_16x16x32_bf16 v[12:15], v[132:135], v[220:223], v[12:15]
	v_mfma_f32_16x16x32_bf16 v[8:11], v[140:143], v[220:223], v[8:11]
	v_mfma_f32_16x16x32_bf16 v[52:55], v[144:147], v[178:181], v[52:55]
	v_mfma_f32_16x16x32_bf16 v[48:51], v[152:155], v[178:181], v[48:51]
	v_mfma_f32_16x16x32_bf16 v[36:39], v[144:147], v[200:203], v[36:39]
	v_mfma_f32_16x16x32_bf16 v[32:35], v[152:155], v[200:203], v[32:35]
	v_mfma_f32_16x16x32_bf16 v[20:23], v[144:147], v[208:211], v[20:23]
	v_mfma_f32_16x16x32_bf16 v[16:19], v[152:155], v[208:211], v[16:19]
	v_mfma_f32_16x16x32_bf16 v[4:7], v[144:147], v[216:219], v[4:7]
	v_mfma_f32_16x16x32_bf16 v[0:3], v[152:155], v[216:219], v[0:3]
	v_mfma_f32_16x16x32_bf16 v[52:55], v[148:151], v[196:199], v[52:55]
	v_mfma_f32_16x16x32_bf16 v[48:51], v[156:159], v[196:199], v[48:51]
	v_mfma_f32_16x16x32_bf16 v[36:39], v[148:151], v[204:207], v[36:39]
	v_mfma_f32_16x16x32_bf16 v[32:35], v[156:159], v[204:207], v[32:35]
	v_mfma_f32_16x16x32_bf16 v[20:23], v[148:151], v[212:215], v[20:23]
	v_mfma_f32_16x16x32_bf16 v[16:19], v[156:159], v[212:215], v[16:19]
	v_mfma_f32_16x16x32_bf16 v[4:7], v[148:151], v[220:223], v[4:7]
	v_mfma_f32_16x16x32_bf16 v[0:3], v[156:159], v[220:223], v[0:3]
	s_barrier
	s_add_i32 s53, s53, 2
	s_add_u32 s0, s0, 0x100
	s_addc_u32 s1, s1, 0
	s_add_u32 s51, s51, 0x100
	s_addc_u32 s52, s52, 0
	s_cmp_gt_u32 s53, 13
	s_cbranch_scc0 .LBB0_1403
	s_branch .Lpeel_exit_6
.LBB0_1403:
	ds_read_b128 v[128:131], v193
	ds_read_b128 v[132:135], v193 offset:1024
	ds_read_b128 v[136:139], v193 offset:2048
	ds_read_b128 v[140:143], v193 offset:3072
	ds_read_b128 v[144:147], v194
	ds_read_b128 v[148:151], v194 offset:1024
	ds_read_b128 v[152:155], v194 offset:2048
	ds_read_b128 v[156:159], v194 offset:3072
	s_add_u32 s26, s0, 0xfffc0080
	s_addc_u32 s27, s1, -1
	s_cmp_eq_u32 s53, 12
	s_cselect_b32 s29, s17, s27
	s_cselect_b32 s28, s33, s26
	s_cselect_b32 s27, s15, s52
	s_cselect_b32 s26, s50, s51
	v_lshl_add_u64 v[224:225], s[0:1], 0, v[170:171]
	s_add_i32 m0, s23, 0xc000
	ds_read_b128 v[178:181], v195
	ds_read_b128 v[196:199], v195 offset:1024
	ds_read_b128 v[200:203], v195 offset:2048
	ds_read_b128 v[204:207], v195 offset:3072
	ds_read_b128 v[208:211], v195 offset:4096
	ds_read_b128 v[212:215], v195 offset:5120
	ds_read_b128 v[216:219], v195 offset:6144
	ds_read_b128 v[220:223], v195 offset:7168
	global_load_lds_dwordx4 v[224:225], off
	v_lshl_add_u64 v[224:225], s[0:1], 0, v[172:173]
	s_add_i32 m0, s23, 0xe000
	s_nop 0
	global_load_lds_dwordx4 v[224:225], off
	s_waitcnt vmcnt(8)
	s_waitcnt lgkmcnt(0)
	s_barrier
	s_waitcnt lgkmcnt(0)
	v_mfma_f32_16x16x32_bf16 v[124:127], v[128:131], v[178:181], v[124:127]
	v_mfma_f32_16x16x32_bf16 v[120:123], v[136:139], v[178:181], v[120:123]
	v_mfma_f32_16x16x32_bf16 v[108:111], v[128:131], v[200:203], v[108:111]
	v_mfma_f32_16x16x32_bf16 v[104:107], v[136:139], v[200:203], v[104:107]
	v_mfma_f32_16x16x32_bf16 v[92:95], v[128:131], v[208:211], v[92:95]
	v_mfma_f32_16x16x32_bf16 v[88:91], v[136:139], v[208:211], v[88:91]
	v_mfma_f32_16x16x32_bf16 v[76:79], v[128:131], v[216:219], v[76:79]
	v_mfma_f32_16x16x32_bf16 v[72:75], v[136:139], v[216:219], v[72:75]
	v_mfma_f32_16x16x32_bf16 v[124:127], v[132:135], v[196:199], v[124:127]
	v_mfma_f32_16x16x32_bf16 v[120:123], v[140:143], v[196:199], v[120:123]
	v_mfma_f32_16x16x32_bf16 v[108:111], v[132:135], v[204:207], v[108:111]
	v_mfma_f32_16x16x32_bf16 v[104:107], v[140:143], v[204:207], v[104:107]
	v_mfma_f32_16x16x32_bf16 v[92:95], v[132:135], v[212:215], v[92:95]
	v_mfma_f32_16x16x32_bf16 v[88:91], v[140:143], v[212:215], v[88:91]
	v_mfma_f32_16x16x32_bf16 v[76:79], v[132:135], v[220:223], v[76:79]
	v_mfma_f32_16x16x32_bf16 v[72:75], v[140:143], v[220:223], v[72:75]
	v_mfma_f32_16x16x32_bf16 v[116:119], v[144:147], v[178:181], v[116:119]
	v_mfma_f32_16x16x32_bf16 v[112:115], v[152:155], v[178:181], v[112:115]
	v_mfma_f32_16x16x32_bf16 v[100:103], v[144:147], v[200:203], v[100:103]
	v_mfma_f32_16x16x32_bf16 v[96:99], v[152:155], v[200:203], v[96:99]
	v_mfma_f32_16x16x32_bf16 v[84:87], v[144:147], v[208:211], v[84:87]
	v_mfma_f32_16x16x32_bf16 v[80:83], v[152:155], v[208:211], v[80:83]
	v_mfma_f32_16x16x32_bf16 v[68:71], v[144:147], v[216:219], v[68:71]
	v_mfma_f32_16x16x32_bf16 v[64:67], v[152:155], v[216:219], v[64:67]
	v_mfma_f32_16x16x32_bf16 v[116:119], v[148:151], v[196:199], v[116:119]
	v_mfma_f32_16x16x32_bf16 v[112:115], v[156:159], v[196:199], v[112:115]
	v_mfma_f32_16x16x32_bf16 v[100:103], v[148:151], v[204:207], v[100:103]
	v_mfma_f32_16x16x32_bf16 v[96:99], v[156:159], v[204:207], v[96:99]
	v_mfma_f32_16x16x32_bf16 v[84:87], v[148:151], v[212:215], v[84:87]
	v_mfma_f32_16x16x32_bf16 v[80:83], v[156:159], v[212:215], v[80:83]
	v_mfma_f32_16x16x32_bf16 v[68:71], v[148:151], v[220:223], v[68:71]
	v_mfma_f32_16x16x32_bf16 v[64:67], v[156:159], v[220:223], v[64:67]
	s_barrier
	s_add_i32 s54, s44, s35
	v_lshl_add_u64 v[224:225], s[26:27], 0, v[164:165]
	s_mov_b32 m0, s54
	ds_read_b128 v[178:181], v195 offset:16384
	ds_read_b128 v[196:199], v195 offset:17408
	ds_read_b128 v[200:203], v195 offset:18432
	ds_read_b128 v[204:207], v195 offset:19456
	ds_read_b128 v[208:211], v195 offset:20480
	ds_read_b128 v[212:215], v195 offset:21504
	ds_read_b128 v[216:219], v195 offset:22528
	ds_read_b128 v[220:223], v195 offset:23552
	global_load_lds_dwordx4 v[224:225], off
	s_add_i32 m0, s54, 0x2000
	s_add_u32 s54, s26, 0x40000
	v_lshl_add_u64 v[226:227], s[26:27], 0, v[168:169]
	s_addc_u32 s55, s27, 0
	s_add_i32 s56, s45, s35
	global_load_lds_dwordx4 v[226:227], off
	v_lshl_add_u64 v[228:229], s[54:55], 0, v[164:165]
	s_mov_b32 m0, s56
	v_lshl_add_u64 v[230:231], s[28:29], 0, v[166:167]
	global_load_lds_dwordx4 v[228:229], off
	v_lshl_add_u64 v[228:229], s[54:55], 0, v[168:169]
	s_add_i32 m0, s56, 0x2000
	s_nop 0
	global_load_lds_dwordx4 v[228:229], off
	v_lshl_add_u64 v[228:229], s[28:29], 0, v[162:163]
	s_mov_b32 m0, s23
	s_nop 0
	global_load_lds_dwordx4 v[228:229], off
	s_mov_b32 m0, s25
	s_nop 0
	global_load_lds_dwordx4 v[230:231], off
	s_waitcnt vmcnt(8)
	s_waitcnt lgkmcnt(0)
	s_barrier
	s_waitcnt lgkmcnt(0)
	v_mfma_f32_16x16x32_bf16 v[60:63], v[128:131], v[178:181], v[60:63]
	v_mfma_f32_16x16x32_bf16 v[56:59], v[136:139], v[178:181], v[56:59]
	v_mfma_f32_16x16x32_bf16 v[44:47], v[128:131], v[200:203], v[44:47]
	v_mfma_f32_16x16x32_bf16 v[40:43], v[136:139], v[200:203], v[40:43]
	v_mfma_f32_16x16x32_bf16 v[28:31], v[128:131], v[208:211], v[28:31]
	v_mfma_f32_16x16x32_bf16 v[24:27], v[136:139], v[208:211], v[24:27]
	v_mfma_f32_16x16x32_bf16 v[12:15], v[128:131], v[216:219], v[12:15]
	v_mfma_f32_16x16x32_bf16 v[8:11], v[136:139], v[216:219], v[8:11]
	v_mfma_f32_16x16x32_bf16 v[60:63], v[132:135], v[196:199], v[60:63]
	v_mfma_f32_16x16x32_bf16 v[56:59], v[140:143], v[196:199], v[56:59]
	v_mfma_f32_16x16x32_bf16 v[44:47], v[132:135], v[204:207], v[44:47]
	v_mfma_f32_16x16x32_bf16 v[40:43], v[140:143], v[204:207], v[40:43]
	v_mfma_f32_16x16x32_bf16 v[28:31], v[132:135], v[212:215], v[28:31]
	v_mfma_f32_16x16x32_bf16 v[24:27], v[140:143], v[212:215], v[24:27]
	v_mfma_f32_16x16x32_bf16 v[12:15], v[132:135], v[220:223], v[12:15]
	v_mfma_f32_16x16x32_bf16 v[8:11], v[140:143], v[220:223], v[8:11]
	v_mfma_f32_16x16x32_bf16 v[52:55], v[144:147], v[178:181], v[52:55]
	v_mfma_f32_16x16x32_bf16 v[48:51], v[152:155], v[178:181], v[48:51]
	v_mfma_f32_16x16x32_bf16 v[36:39], v[144:147], v[200:203], v[36:39]
	v_mfma_f32_16x16x32_bf16 v[32:35], v[152:155], v[200:203], v[32:35]
	v_mfma_f32_16x16x32_bf16 v[20:23], v[144:147], v[208:211], v[20:23]
	v_mfma_f32_16x16x32_bf16 v[16:19], v[152:155], v[208:211], v[16:19]
	v_mfma_f32_16x16x32_bf16 v[4:7], v[144:147], v[216:219], v[4:7]
	v_mfma_f32_16x16x32_bf16 v[0:3], v[152:155], v[216:219], v[0:3]
	v_mfma_f32_16x16x32_bf16 v[52:55], v[148:151], v[196:199], v[52:55]
	v_mfma_f32_16x16x32_bf16 v[48:51], v[156:159], v[196:199], v[48:51]
	v_mfma_f32_16x16x32_bf16 v[36:39], v[148:151], v[204:207], v[36:39]
	v_mfma_f32_16x16x32_bf16 v[32:35], v[156:159], v[204:207], v[32:35]
	v_mfma_f32_16x16x32_bf16 v[20:23], v[148:151], v[212:215], v[20:23]
	v_mfma_f32_16x16x32_bf16 v[16:19], v[156:159], v[212:215], v[16:19]
	v_mfma_f32_16x16x32_bf16 v[4:7], v[148:151], v[220:223], v[4:7]
	v_mfma_f32_16x16x32_bf16 v[0:3], v[156:159], v[220:223], v[0:3]
	s_barrier
	s_add_i32 s54, 0, 0x18000
	s_add_i32 s55, 0, 0x1c000
	v_add_u32_e32 v140, s54, v188
	v_add_u32_e32 v156, s55, v188
	ds_read_b128 v[128:131], v140
	ds_read_b128 v[132:135], v140 offset:1024
	ds_read_b128 v[136:139], v140 offset:2048
	ds_read_b128 v[140:143], v140 offset:3072
	ds_read_b128 v[144:147], v156
	ds_read_b128 v[148:151], v156 offset:1024
	ds_read_b128 v[152:155], v156 offset:2048
	ds_read_b128 v[156:159], v156 offset:3072
	s_add_u32 s28, s28, 0x40000
	s_addc_u32 s29, s29, 0
	s_mov_b32 m0, s36
	v_lshl_add_u64 v[232:233], s[28:29], 0, v[162:163]
	ds_read_b128 v[178:181], v195 offset:32768
	ds_read_b128 v[196:199], v195 offset:33792
	ds_read_b128 v[200:203], v195 offset:34816
	ds_read_b128 v[204:207], v195 offset:35840
	ds_read_b128 v[208:211], v195 offset:36864
	ds_read_b128 v[212:215], v195 offset:37888
	ds_read_b128 v[216:219], v195 offset:38912
	ds_read_b128 v[220:223], v195 offset:39936
	global_load_lds_dwordx4 v[232:233], off
	v_lshl_add_u64 v[232:233], s[28:29], 0, v[166:167]
	s_mov_b32 m0, s37
	s_nop 0
	global_load_lds_dwordx4 v[232:233], off
	s_waitcnt vmcnt(8)
	s_waitcnt lgkmcnt(0)
	s_barrier
	s_waitcnt lgkmcnt(0)
	v_mfma_f32_16x16x32_bf16 v[124:127], v[128:131], v[178:181], v[124:127]
	v_mfma_f32_16x16x32_bf16 v[120:123], v[136:139], v[178:181], v[120:123]
	v_mfma_f32_16x16x32_bf16 v[108:111], v[128:131], v[200:203], v[108:111]
	v_mfma_f32_16x16x32_bf16 v[104:107], v[136:139], v[200:203], v[104:107]
	v_mfma_f32_16x16x32_bf16 v[92:95], v[128:131], v[208:211], v[92:95]
	v_mfma_f32_16x16x32_bf16 v[88:91], v[136:139], v[208:211], v[88:91]
	v_mfma_f32_16x16x32_bf16 v[76:79], v[128:131], v[216:219], v[76:79]
	v_mfma_f32_16x16x32_bf16 v[72:75], v[136:139], v[216:219], v[72:75]
	v_mfma_f32_16x16x32_bf16 v[124:127], v[132:135], v[196:199], v[124:127]
	v_mfma_f32_16x16x32_bf16 v[120:123], v[140:143], v[196:199], v[120:123]
	v_mfma_f32_16x16x32_bf16 v[108:111], v[132:135], v[204:207], v[108:111]
	v_mfma_f32_16x16x32_bf16 v[104:107], v[140:143], v[204:207], v[104:107]
	v_mfma_f32_16x16x32_bf16 v[92:95], v[132:135], v[212:215], v[92:95]
	v_mfma_f32_16x16x32_bf16 v[88:91], v[140:143], v[212:215], v[88:91]
	v_mfma_f32_16x16x32_bf16 v[76:79], v[132:135], v[220:223], v[76:79]
	v_mfma_f32_16x16x32_bf16 v[72:75], v[140:143], v[220:223], v[72:75]
	v_mfma_f32_16x16x32_bf16 v[116:119], v[144:147], v[178:181], v[116:119]
	v_mfma_f32_16x16x32_bf16 v[112:115], v[152:155], v[178:181], v[112:115]
	v_mfma_f32_16x16x32_bf16 v[100:103], v[144:147], v[200:203], v[100:103]
	v_mfma_f32_16x16x32_bf16 v[96:99], v[152:155], v[200:203], v[96:99]
	v_mfma_f32_16x16x32_bf16 v[84:87], v[144:147], v[208:211], v[84:87]
	v_mfma_f32_16x16x32_bf16 v[80:83], v[152:155], v[208:211], v[80:83]
	v_mfma_f32_16x16x32_bf16 v[68:71], v[144:147], v[216:219], v[68:71]
	v_mfma_f32_16x16x32_bf16 v[64:67], v[152:155], v[216:219], v[64:67]
	v_mfma_f32_16x16x32_bf16 v[116:119], v[148:151], v[196:199], v[116:119]
	v_mfma_f32_16x16x32_bf16 v[112:115], v[156:159], v[196:199], v[112:115]
	v_mfma_f32_16x16x32_bf16 v[100:103], v[148:151], v[204:207], v[100:103]
	v_mfma_f32_16x16x32_bf16 v[96:99], v[156:159], v[204:207], v[96:99]
	v_mfma_f32_16x16x32_bf16 v[84:87], v[148:151], v[212:215], v[84:87]
	v_mfma_f32_16x16x32_bf16 v[80:83], v[156:159], v[212:215], v[80:83]
	v_mfma_f32_16x16x32_bf16 v[68:71], v[148:151], v[220:223], v[68:71]
	v_mfma_f32_16x16x32_bf16 v[64:67], v[156:159], v[220:223], v[64:67]
	s_barrier
	s_add_i32 s28, s54, s35
	v_lshl_add_u64 v[224:225], v[224:225], 0, s[10:11]
	s_mov_b32 m0, s28
	ds_read_b128 v[178:181], v195 offset:49152
	ds_read_b128 v[196:199], v195 offset:50176
	ds_read_b128 v[200:203], v195 offset:51200
	ds_read_b128 v[204:207], v195 offset:52224
	ds_read_b128 v[208:211], v195 offset:53248
	ds_read_b128 v[212:215], v195 offset:54272
	ds_read_b128 v[216:219], v195 offset:55296
	ds_read_b128 v[220:223], v195 offset:56320
	global_load_lds_dwordx4 v[224:225], off
	s_add_i32 m0, s28, 0x2000
	s_add_u32 s26, s26, 0x40080
	v_lshl_add_u64 v[224:225], v[226:227], 0, s[10:11]
	s_addc_u32 s27, s27, 0
	s_add_i32 s28, s55, s35
	global_load_lds_dwordx4 v[224:225], off
	v_lshl_add_u64 v[224:225], s[26:27], 0, v[164:165]
	s_mov_b32 m0, s28
	s_nop 0
	global_load_lds_dwordx4 v[224:225], off
	v_lshl_add_u64 v[224:225], s[26:27], 0, v[168:169]
	s_add_i32 m0, s28, 0x2000
	s_nop 0
	global_load_lds_dwordx4 v[224:225], off
	v_lshl_add_u64 v[224:225], v[228:229], 0, s[10:11]
	s_mov_b32 m0, s40
	s_nop 0
	global_load_lds_dwordx4 v[224:225], off
	v_lshl_add_u64 v[224:225], v[230:231], 0, s[10:11]
	s_mov_b32 m0, s41
	s_nop 0
	global_load_lds_dwordx4 v[224:225], off
	s_waitcnt vmcnt(8)
	s_waitcnt lgkmcnt(0)
	s_barrier
	s_waitcnt lgkmcnt(0)
	v_mfma_f32_16x16x32_bf16 v[60:63], v[128:131], v[178:181], v[60:63]
	v_mfma_f32_16x16x32_bf16 v[56:59], v[136:139], v[178:181], v[56:59]
	v_mfma_f32_16x16x32_bf16 v[44:47], v[128:131], v[200:203], v[44:47]
	v_mfma_f32_16x16x32_bf16 v[40:43], v[136:139], v[200:203], v[40:43]
	v_mfma_f32_16x16x32_bf16 v[28:31], v[128:131], v[208:211], v[28:31]
	v_mfma_f32_16x16x32_bf16 v[24:27], v[136:139], v[208:211], v[24:27]
	v_mfma_f32_16x16x32_bf16 v[12:15], v[128:131], v[216:219], v[12:15]
	v_mfma_f32_16x16x32_bf16 v[8:11], v[136:139], v[216:219], v[8:11]
	v_mfma_f32_16x16x32_bf16 v[60:63], v[132:135], v[196:199], v[60:63]
	v_mfma_f32_16x16x32_bf16 v[56:59], v[140:143], v[196:199], v[56:59]
	v_mfma_f32_16x16x32_bf16 v[44:47], v[132:135], v[204:207], v[44:47]
	v_mfma_f32_16x16x32_bf16 v[40:43], v[140:143], v[204:207], v[40:43]
	v_mfma_f32_16x16x32_bf16 v[28:31], v[132:135], v[212:215], v[28:31]
	v_mfma_f32_16x16x32_bf16 v[24:27], v[140:143], v[212:215], v[24:27]
	v_mfma_f32_16x16x32_bf16 v[12:15], v[132:135], v[220:223], v[12:15]
	v_mfma_f32_16x16x32_bf16 v[8:11], v[140:143], v[220:223], v[8:11]
	v_mfma_f32_16x16x32_bf16 v[52:55], v[144:147], v[178:181], v[52:55]
	v_mfma_f32_16x16x32_bf16 v[48:51], v[152:155], v[178:181], v[48:51]
	v_mfma_f32_16x16x32_bf16 v[36:39], v[144:147], v[200:203], v[36:39]
	v_mfma_f32_16x16x32_bf16 v[32:35], v[152:155], v[200:203], v[32:35]
	v_mfma_f32_16x16x32_bf16 v[20:23], v[144:147], v[208:211], v[20:23]
	v_mfma_f32_16x16x32_bf16 v[16:19], v[152:155], v[208:211], v[16:19]
	v_mfma_f32_16x16x32_bf16 v[4:7], v[144:147], v[216:219], v[4:7]
	v_mfma_f32_16x16x32_bf16 v[0:3], v[152:155], v[216:219], v[0:3]
	v_mfma_f32_16x16x32_bf16 v[52:55], v[148:151], v[196:199], v[52:55]
	v_mfma_f32_16x16x32_bf16 v[48:51], v[156:159], v[196:199], v[48:51]
	v_mfma_f32_16x16x32_bf16 v[36:39], v[148:151], v[204:207], v[36:39]
	v_mfma_f32_16x16x32_bf16 v[32:35], v[156:159], v[204:207], v[32:35]
	v_mfma_f32_16x16x32_bf16 v[20:23], v[148:151], v[212:215], v[20:23]
	v_mfma_f32_16x16x32_bf16 v[16:19], v[156:159], v[212:215], v[16:19]
	v_mfma_f32_16x16x32_bf16 v[4:7], v[148:151], v[220:223], v[4:7]
	v_mfma_f32_16x16x32_bf16 v[0:3], v[156:159], v[220:223], v[0:3]
	s_barrier
	s_add_i32 s53, s53, 2
	s_add_u32 s0, s0, 0x100
	s_addc_u32 s1, s1, 0
	s_add_u32 s51, s51, 0x100
	s_addc_u32 s52, s52, 0
	s_cmp_gt_u32 s53, 13
	s_cbranch_scc0 .LBB0_1403

.LBB0_1487:
	s_ashr_i32 s15, s14, 31
	s_lshl_b64 s[16:17], s[14:15], 19
	s_add_u32 s16, s66, s16
	s_addc_u32 s17, s67, s17
	s_and_b64 s[18:19], s[4:5], exec
	s_cselect_b32 s15, s17, s1
	s_cselect_b32 s41, s16, s0
	s_ashr_i32 s13, s12, 31
	s_lshl_b64 s[18:19], s[12:13], 19
	s_add_u32 s18, s26, s18
	s_addc_u32 s19, s27, s19
	s_and_b64 s[24:25], s[4:5], exec
	s_cselect_b32 s13, s19, s23
	s_cselect_b32 s42, s18, s22
	s_add_u32 s0, s0, 0x40080
	s_addc_u32 s1, s1, 0
	s_add_u32 s43, s22, 0x100
	s_addc_u32 s44, s23, 0
	s_mov_b32 s45, -2
	v_lshl_add_u32 v248, s20, 8, v156
	v_ashrrev_i32_e32 v249, 31, v248
	v_lshl_add_u64 v[248:249], v[248:249], 2, s[8:9]
	global_load_dword v240, v[248:249], off
	global_load_dword v241, v[248:249], off offset:64
	global_load_dword v242, v[248:249], off offset:128
	global_load_dword v243, v[248:249], off offset:192
	global_load_dword v244, v[248:249], off offset:512
	global_load_dword v245, v[248:249], off offset:576
	global_load_dword v246, v[248:249], off offset:640
	global_load_dword v247, v[248:249], off offset:704
	ds_read_b128 v[144:147], v159
	ds_read_b128 v[148:151], v159 offset:1024
	ds_read_b128 v[152:155], v159 offset:2048
	ds_read_b128 v[166:169], v159 offset:3072
	ds_read_b128 v[170:173], v162
	ds_read_b128 v[174:177], v162 offset:1024
	ds_read_b128 v[178:181], v162 offset:2048
	ds_read_b128 v[188:191], v162 offset:3072
	s_add_u32 s22, s0, 0xfffc0080
	s_addc_u32 s23, s1, -1
	s_cmp_eq_u32 s45, 12
	s_cselect_b32 s25, s15, s23
	s_cselect_b32 s24, s41, s22
	s_cselect_b32 s23, s13, s44
	s_cselect_b32 s22, s42, s43
	v_lshl_add_u64 v[224:225], s[0:1], 0, v[136:137]
	s_add_i32 m0, s21, 0xc000
	ds_read_b128 v[192:195], v163
	ds_read_b128 v[196:199], v163 offset:1024
	ds_read_b128 v[200:203], v163 offset:2048
	ds_read_b128 v[204:207], v163 offset:3072
	ds_read_b128 v[208:211], v163 offset:4096
	ds_read_b128 v[212:215], v163 offset:5120
	ds_read_b128 v[216:219], v163 offset:6144
	ds_read_b128 v[220:223], v163 offset:7168
	global_load_lds_dwordx4 v[224:225], off
	v_lshl_add_u64 v[224:225], s[0:1], 0, v[138:139]
	s_add_i32 m0, s21, 0xe000
	s_nop 0
	global_load_lds_dwordx4 v[224:225], off
	s_waitcnt vmcnt(8)
	s_waitcnt lgkmcnt(0)
	s_barrier
	s_waitcnt lgkmcnt(0)
	v_mfma_f32_16x16x32_bf16 v[124:127], v[144:147], v[192:195], 0
	v_mfma_f32_16x16x32_bf16 v[120:123], v[152:155], v[192:195], 0
	v_mfma_f32_16x16x32_bf16 v[116:119], v[144:147], v[200:203], 0
	v_mfma_f32_16x16x32_bf16 v[104:107], v[152:155], v[200:203], 0
	v_mfma_f32_16x16x32_bf16 v[92:95], v[144:147], v[208:211], 0
	v_mfma_f32_16x16x32_bf16 v[88:91], v[152:155], v[208:211], 0
	v_mfma_f32_16x16x32_bf16 v[76:79], v[144:147], v[216:219], 0
	v_mfma_f32_16x16x32_bf16 v[72:75], v[152:155], v[216:219], 0
	v_mfma_f32_16x16x32_bf16 v[124:127], v[148:151], v[196:199], v[124:127]
	v_mfma_f32_16x16x32_bf16 v[120:123], v[166:169], v[196:199], v[120:123]
	v_mfma_f32_16x16x32_bf16 v[116:119], v[148:151], v[204:207], v[116:119]
	v_mfma_f32_16x16x32_bf16 v[104:107], v[166:169], v[204:207], v[104:107]
	v_mfma_f32_16x16x32_bf16 v[92:95], v[148:151], v[212:215], v[92:95]
	v_mfma_f32_16x16x32_bf16 v[88:91], v[166:169], v[212:215], v[88:91]
	v_mfma_f32_16x16x32_bf16 v[76:79], v[148:151], v[220:223], v[76:79]
	v_mfma_f32_16x16x32_bf16 v[72:75], v[166:169], v[220:223], v[72:75]
	v_mfma_f32_16x16x32_bf16 v[112:115], v[170:173], v[192:195], 0
	v_mfma_f32_16x16x32_bf16 v[108:111], v[178:181], v[192:195], 0
	v_mfma_f32_16x16x32_bf16 v[100:103], v[170:173], v[200:203], 0
	v_mfma_f32_16x16x32_bf16 v[96:99], v[178:181], v[200:203], 0
	v_mfma_f32_16x16x32_bf16 v[84:87], v[170:173], v[208:211], 0
	v_mfma_f32_16x16x32_bf16 v[80:83], v[178:181], v[208:211], 0
	v_mfma_f32_16x16x32_bf16 v[68:71], v[170:173], v[216:219], 0
	v_mfma_f32_16x16x32_bf16 v[64:67], v[178:181], v[216:219], 0
	v_mfma_f32_16x16x32_bf16 v[112:115], v[174:177], v[196:199], v[112:115]
	v_mfma_f32_16x16x32_bf16 v[108:111], v[188:191], v[196:199], v[108:111]
	v_mfma_f32_16x16x32_bf16 v[100:103], v[174:177], v[204:207], v[100:103]
	v_mfma_f32_16x16x32_bf16 v[96:99], v[188:191], v[204:207], v[96:99]
	v_mfma_f32_16x16x32_bf16 v[84:87], v[174:177], v[212:215], v[84:87]
	v_mfma_f32_16x16x32_bf16 v[80:83], v[188:191], v[212:215], v[80:83]
	v_mfma_f32_16x16x32_bf16 v[68:71], v[174:177], v[220:223], v[68:71]
	v_mfma_f32_16x16x32_bf16 v[64:67], v[188:191], v[220:223], v[64:67]
	s_barrier
	s_add_i32 s46, s39, s28
	v_lshl_add_u64 v[224:225], s[22:23], 0, v[132:133]
	s_mov_b32 m0, s46
	ds_read_b128 v[192:195], v163 offset:16384
	ds_read_b128 v[196:199], v163 offset:17408
	ds_read_b128 v[200:203], v163 offset:18432
	ds_read_b128 v[204:207], v163 offset:19456
	ds_read_b128 v[208:211], v163 offset:20480
	ds_read_b128 v[212:215], v163 offset:21504
	ds_read_b128 v[216:219], v163 offset:22528
	ds_read_b128 v[220:223], v163 offset:23552
	global_load_lds_dwordx4 v[224:225], off
	s_add_i32 m0, s46, 0x2000
	s_add_u32 s46, s22, 0x40000
	v_lshl_add_u64 v[226:227], s[22:23], 0, v[128:129]
	s_addc_u32 s47, s23, 0
	s_add_i32 s48, s40, s28
	global_load_lds_dwordx4 v[226:227], off
	v_lshl_add_u64 v[228:229], s[46:47], 0, v[132:133]
	s_mov_b32 m0, s48
	v_lshl_add_u64 v[230:231], s[24:25], 0, v[130:131]
	global_load_lds_dwordx4 v[228:229], off
	v_lshl_add_u64 v[228:229], s[46:47], 0, v[128:129]
	s_add_i32 m0, s48, 0x2000
	s_nop 0
	global_load_lds_dwordx4 v[228:229], off
	v_lshl_add_u64 v[228:229], s[24:25], 0, v[134:135]
	s_mov_b32 m0, s21
	s_nop 0
	global_load_lds_dwordx4 v[228:229], off
	s_mov_b32 m0, s31
	s_nop 0
	global_load_lds_dwordx4 v[230:231], off
	s_waitcnt vmcnt(8)
	s_waitcnt lgkmcnt(0)
	s_barrier
	s_waitcnt lgkmcnt(0)
	v_mfma_f32_16x16x32_bf16 v[60:63], v[144:147], v[192:195], 0
	v_mfma_f32_16x16x32_bf16 v[56:59], v[152:155], v[192:195], 0
	v_mfma_f32_16x16x32_bf16 v[44:47], v[144:147], v[200:203], 0
	v_mfma_f32_16x16x32_bf16 v[40:43], v[152:155], v[200:203], 0
	v_mfma_f32_16x16x32_bf16 v[28:31], v[144:147], v[208:211], 0
	v_mfma_f32_16x16x32_bf16 v[24:27], v[152:155], v[208:211], 0
	v_mfma_f32_16x16x32_bf16 v[12:15], v[144:147], v[216:219], 0
	v_mfma_f32_16x16x32_bf16 v[8:11], v[152:155], v[216:219], 0
	v_mfma_f32_16x16x32_bf16 v[60:63], v[148:151], v[196:199], v[60:63]
	v_mfma_f32_16x16x32_bf16 v[56:59], v[166:169], v[196:199], v[56:59]
	v_mfma_f32_16x16x32_bf16 v[44:47], v[148:151], v[204:207], v[44:47]
	v_mfma_f32_16x16x32_bf16 v[40:43], v[166:169], v[204:207], v[40:43]
	v_mfma_f32_16x16x32_bf16 v[28:31], v[148:151], v[212:215], v[28:31]
	v_mfma_f32_16x16x32_bf16 v[24:27], v[166:169], v[212:215], v[24:27]
	v_mfma_f32_16x16x32_bf16 v[12:15], v[148:151], v[220:223], v[12:15]
	v_mfma_f32_16x16x32_bf16 v[8:11], v[166:169], v[220:223], v[8:11]
	v_mfma_f32_16x16x32_bf16 v[52:55], v[170:173], v[192:195], 0
	v_mfma_f32_16x16x32_bf16 v[48:51], v[178:181], v[192:195], 0
	v_mfma_f32_16x16x32_bf16 v[36:39], v[170:173], v[200:203], 0
	v_mfma_f32_16x16x32_bf16 v[32:35], v[178:181], v[200:203], 0
	v_mfma_f32_16x16x32_bf16 v[20:23], v[170:173], v[208:211], 0
	v_mfma_f32_16x16x32_bf16 v[16:19], v[178:181], v[208:211], 0
	v_mfma_f32_16x16x32_bf16 v[4:7], v[170:173], v[216:219], 0
	v_mfma_f32_16x16x32_bf16 v[0:3], v[178:181], v[216:219], 0
	v_mfma_f32_16x16x32_bf16 v[52:55], v[174:177], v[196:199], v[52:55]
	v_mfma_f32_16x16x32_bf16 v[48:51], v[188:191], v[196:199], v[48:51]
	v_mfma_f32_16x16x32_bf16 v[36:39], v[174:177], v[204:207], v[36:39]
	v_mfma_f32_16x16x32_bf16 v[32:35], v[188:191], v[204:207], v[32:35]
	v_mfma_f32_16x16x32_bf16 v[20:23], v[174:177], v[212:215], v[20:23]
	v_mfma_f32_16x16x32_bf16 v[16:19], v[188:191], v[212:215], v[16:19]
	v_mfma_f32_16x16x32_bf16 v[4:7], v[174:177], v[220:223], v[4:7]
	v_mfma_f32_16x16x32_bf16 v[0:3], v[188:191], v[220:223], v[0:3]
	s_barrier
	s_add_i32 s46, 0, 0x18000
	v_add_u32_e32 v165, s46, v157
	s_add_i32 s47, 0, 0x1c000
	ds_read_b128 v[144:147], v165
	ds_read_b128 v[148:151], v165 offset:1024
	ds_read_b128 v[152:155], v165 offset:2048
	ds_read_b128 v[166:169], v165 offset:3072
	v_add_u32_e32 v165, s47, v157
	ds_read_b128 v[170:173], v165
	ds_read_b128 v[174:177], v165 offset:1024
	ds_read_b128 v[178:181], v165 offset:2048
	ds_read_b128 v[188:191], v165 offset:3072
	s_add_u32 s24, s24, 0x40000
	s_addc_u32 s25, s25, 0
	s_mov_b32 m0, s34
	v_lshl_add_u64 v[232:233], s[24:25], 0, v[134:135]
	ds_read_b128 v[192:195], v163 offset:32768
	ds_read_b128 v[196:199], v163 offset:33792
	ds_read_b128 v[200:203], v163 offset:34816
	ds_read_b128 v[204:207], v163 offset:35840
	ds_read_b128 v[208:211], v163 offset:36864
	ds_read_b128 v[212:215], v163 offset:37888
	ds_read_b128 v[216:219], v163 offset:38912
	ds_read_b128 v[220:223], v163 offset:39936
	global_load_lds_dwordx4 v[232:233], off
	v_lshl_add_u64 v[232:233], s[24:25], 0, v[130:131]
	s_mov_b32 m0, s35
	s_nop 0
	global_load_lds_dwordx4 v[232:233], off
	s_waitcnt vmcnt(8)
	s_waitcnt lgkmcnt(0)
	s_barrier
	s_waitcnt lgkmcnt(0)
	v_mfma_f32_16x16x32_bf16 v[124:127], v[144:147], v[192:195], v[124:127]
	v_mfma_f32_16x16x32_bf16 v[120:123], v[152:155], v[192:195], v[120:123]
	v_mfma_f32_16x16x32_bf16 v[116:119], v[144:147], v[200:203], v[116:119]
	v_mfma_f32_16x16x32_bf16 v[104:107], v[152:155], v[200:203], v[104:107]
	v_mfma_f32_16x16x32_bf16 v[92:95], v[144:147], v[208:211], v[92:95]
	v_mfma_f32_16x16x32_bf16 v[88:91], v[152:155], v[208:211], v[88:91]
	v_mfma_f32_16x16x32_bf16 v[76:79], v[144:147], v[216:219], v[76:79]
	v_mfma_f32_16x16x32_bf16 v[72:75], v[152:155], v[216:219], v[72:75]
	v_mfma_f32_16x16x32_bf16 v[124:127], v[148:151], v[196:199], v[124:127]
	v_mfma_f32_16x16x32_bf16 v[120:123], v[166:169], v[196:199], v[120:123]
	v_mfma_f32_16x16x32_bf16 v[116:119], v[148:151], v[204:207], v[116:119]
	v_mfma_f32_16x16x32_bf16 v[104:107], v[166:169], v[204:207], v[104:107]
	v_mfma_f32_16x16x32_bf16 v[92:95], v[148:151], v[212:215], v[92:95]
	v_mfma_f32_16x16x32_bf16 v[88:91], v[166:169], v[212:215], v[88:91]
	v_mfma_f32_16x16x32_bf16 v[76:79], v[148:151], v[220:223], v[76:79]
	v_mfma_f32_16x16x32_bf16 v[72:75], v[166:169], v[220:223], v[72:75]
	v_mfma_f32_16x16x32_bf16 v[112:115], v[170:173], v[192:195], v[112:115]
	v_mfma_f32_16x16x32_bf16 v[108:111], v[178:181], v[192:195], v[108:111]
	v_mfma_f32_16x16x32_bf16 v[100:103], v[170:173], v[200:203], v[100:103]
	v_mfma_f32_16x16x32_bf16 v[96:99], v[178:181], v[200:203], v[96:99]
	v_mfma_f32_16x16x32_bf16 v[84:87], v[170:173], v[208:211], v[84:87]
	v_mfma_f32_16x16x32_bf16 v[80:83], v[178:181], v[208:211], v[80:83]
	v_mfma_f32_16x16x32_bf16 v[68:71], v[170:173], v[216:219], v[68:71]
	v_mfma_f32_16x16x32_bf16 v[64:67], v[178:181], v[216:219], v[64:67]
	v_mfma_f32_16x16x32_bf16 v[112:115], v[174:177], v[196:199], v[112:115]
	v_mfma_f32_16x16x32_bf16 v[108:111], v[188:191], v[196:199], v[108:111]
	v_mfma_f32_16x16x32_bf16 v[100:103], v[174:177], v[204:207], v[100:103]
	v_mfma_f32_16x16x32_bf16 v[96:99], v[188:191], v[204:207], v[96:99]
	v_mfma_f32_16x16x32_bf16 v[84:87], v[174:177], v[212:215], v[84:87]
	v_mfma_f32_16x16x32_bf16 v[80:83], v[188:191], v[212:215], v[80:83]
	v_mfma_f32_16x16x32_bf16 v[68:71], v[174:177], v[220:223], v[68:71]
	v_mfma_f32_16x16x32_bf16 v[64:67], v[188:191], v[220:223], v[64:67]
	s_barrier
	s_add_i32 s24, s46, s28
	v_lshl_add_u64 v[224:225], v[224:225], 0, s[6:7]
	s_mov_b32 m0, s24
	ds_read_b128 v[192:195], v163 offset:49152
	ds_read_b128 v[196:199], v163 offset:50176
	ds_read_b128 v[200:203], v163 offset:51200
	ds_read_b128 v[204:207], v163 offset:52224
	ds_read_b128 v[208:211], v163 offset:53248
	ds_read_b128 v[212:215], v163 offset:54272
	ds_read_b128 v[216:219], v163 offset:55296
	ds_read_b128 v[220:223], v163 offset:56320
	global_load_lds_dwordx4 v[224:225], off
	s_add_i32 m0, s24, 0x2000
	s_add_u32 s22, s22, 0x40080
	v_lshl_add_u64 v[224:225], v[226:227], 0, s[6:7]
	s_addc_u32 s23, s23, 0
	s_add_i32 s24, s47, s28
	global_load_lds_dwordx4 v[224:225], off
	v_lshl_add_u64 v[224:225], s[22:23], 0, v[132:133]
	s_mov_b32 m0, s24
	s_nop 0
	global_load_lds_dwordx4 v[224:225], off
	v_lshl_add_u64 v[224:225], s[22:23], 0, v[128:129]
	s_add_i32 m0, s24, 0x2000
	s_nop 0
	global_load_lds_dwordx4 v[224:225], off
	v_lshl_add_u64 v[224:225], v[228:229], 0, s[6:7]
	s_mov_b32 m0, s37
	s_nop 0
	global_load_lds_dwordx4 v[224:225], off
	v_lshl_add_u64 v[224:225], v[230:231], 0, s[6:7]
	s_mov_b32 m0, s38
	s_nop 0
	global_load_lds_dwordx4 v[224:225], off
	s_waitcnt vmcnt(8)
	s_waitcnt lgkmcnt(0)
	s_barrier
	s_waitcnt lgkmcnt(0)
	v_mfma_f32_16x16x32_bf16 v[60:63], v[144:147], v[192:195], v[60:63]
	v_mfma_f32_16x16x32_bf16 v[56:59], v[152:155], v[192:195], v[56:59]
	v_mfma_f32_16x16x32_bf16 v[44:47], v[144:147], v[200:203], v[44:47]
	v_mfma_f32_16x16x32_bf16 v[40:43], v[152:155], v[200:203], v[40:43]
	v_mfma_f32_16x16x32_bf16 v[28:31], v[144:147], v[208:211], v[28:31]
	v_mfma_f32_16x16x32_bf16 v[24:27], v[152:155], v[208:211], v[24:27]
	v_mfma_f32_16x16x32_bf16 v[12:15], v[144:147], v[216:219], v[12:15]
	v_mfma_f32_16x16x32_bf16 v[8:11], v[152:155], v[216:219], v[8:11]
	v_mfma_f32_16x16x32_bf16 v[60:63], v[148:151], v[196:199], v[60:63]
	v_mfma_f32_16x16x32_bf16 v[56:59], v[166:169], v[196:199], v[56:59]
	v_mfma_f32_16x16x32_bf16 v[44:47], v[148:151], v[204:207], v[44:47]
	v_mfma_f32_16x16x32_bf16 v[40:43], v[166:169], v[204:207], v[40:43]
	v_mfma_f32_16x16x32_bf16 v[28:31], v[148:151], v[212:215], v[28:31]
	v_mfma_f32_16x16x32_bf16 v[24:27], v[166:169], v[212:215], v[24:27]
	v_mfma_f32_16x16x32_bf16 v[12:15], v[148:151], v[220:223], v[12:15]
	v_mfma_f32_16x16x32_bf16 v[8:11], v[166:169], v[220:223], v[8:11]
	v_mfma_f32_16x16x32_bf16 v[52:55], v[170:173], v[192:195], v[52:55]
	v_mfma_f32_16x16x32_bf16 v[48:51], v[178:181], v[192:195], v[48:51]
	v_mfma_f32_16x16x32_bf16 v[36:39], v[170:173], v[200:203], v[36:39]
	v_mfma_f32_16x16x32_bf16 v[32:35], v[178:181], v[200:203], v[32:35]
	v_mfma_f32_16x16x32_bf16 v[20:23], v[170:173], v[208:211], v[20:23]
	v_mfma_f32_16x16x32_bf16 v[16:19], v[178:181], v[208:211], v[16:19]
	v_mfma_f32_16x16x32_bf16 v[4:7], v[170:173], v[216:219], v[4:7]
	v_mfma_f32_16x16x32_bf16 v[0:3], v[178:181], v[216:219], v[0:3]
	v_mfma_f32_16x16x32_bf16 v[52:55], v[174:177], v[196:199], v[52:55]
	v_mfma_f32_16x16x32_bf16 v[48:51], v[188:191], v[196:199], v[48:51]
	v_mfma_f32_16x16x32_bf16 v[36:39], v[174:177], v[204:207], v[36:39]
	v_mfma_f32_16x16x32_bf16 v[32:35], v[188:191], v[204:207], v[32:35]
	v_mfma_f32_16x16x32_bf16 v[20:23], v[174:177], v[212:215], v[20:23]
	v_mfma_f32_16x16x32_bf16 v[16:19], v[188:191], v[212:215], v[16:19]
	v_mfma_f32_16x16x32_bf16 v[4:7], v[174:177], v[220:223], v[4:7]
	v_mfma_f32_16x16x32_bf16 v[0:3], v[188:191], v[220:223], v[0:3]
	s_barrier
	s_add_i32 s45, s45, 2
	s_add_u32 s0, s0, 0x100
	s_addc_u32 s1, s1, 0
	s_add_u32 s43, s43, 0x100
	s_addc_u32 s44, s44, 0
	s_cmp_gt_u32 s45, 13
	s_cbranch_scc0 .LBB0_1488
	s_branch .Lpeel_exit_7
.LBB0_1488:
	ds_read_b128 v[144:147], v159
	ds_read_b128 v[148:151], v159 offset:1024
	ds_read_b128 v[152:155], v159 offset:2048
	ds_read_b128 v[166:169], v159 offset:3072
	ds_read_b128 v[170:173], v162
	ds_read_b128 v[174:177], v162 offset:1024
	ds_read_b128 v[178:181], v162 offset:2048
	ds_read_b128 v[188:191], v162 offset:3072
	s_add_u32 s22, s0, 0xfffc0080
	s_addc_u32 s23, s1, -1
	s_cmp_eq_u32 s45, 12
	s_cselect_b32 s25, s15, s23
	s_cselect_b32 s24, s41, s22
	s_cselect_b32 s23, s13, s44
	s_cselect_b32 s22, s42, s43
	v_lshl_add_u64 v[224:225], s[0:1], 0, v[136:137]
	s_add_i32 m0, s21, 0xc000
	ds_read_b128 v[192:195], v163
	ds_read_b128 v[196:199], v163 offset:1024
	ds_read_b128 v[200:203], v163 offset:2048
	ds_read_b128 v[204:207], v163 offset:3072
	ds_read_b128 v[208:211], v163 offset:4096
	ds_read_b128 v[212:215], v163 offset:5120
	ds_read_b128 v[216:219], v163 offset:6144
	ds_read_b128 v[220:223], v163 offset:7168
	global_load_lds_dwordx4 v[224:225], off
	v_lshl_add_u64 v[224:225], s[0:1], 0, v[138:139]
	s_add_i32 m0, s21, 0xe000
	s_nop 0
	global_load_lds_dwordx4 v[224:225], off
	s_waitcnt vmcnt(8)
	s_waitcnt lgkmcnt(0)
	s_barrier
	s_waitcnt lgkmcnt(0)
	v_mfma_f32_16x16x32_bf16 v[124:127], v[144:147], v[192:195], v[124:127]
	v_mfma_f32_16x16x32_bf16 v[120:123], v[152:155], v[192:195], v[120:123]
	v_mfma_f32_16x16x32_bf16 v[116:119], v[144:147], v[200:203], v[116:119]
	v_mfma_f32_16x16x32_bf16 v[104:107], v[152:155], v[200:203], v[104:107]
	v_mfma_f32_16x16x32_bf16 v[92:95], v[144:147], v[208:211], v[92:95]
	v_mfma_f32_16x16x32_bf16 v[88:91], v[152:155], v[208:211], v[88:91]
	v_mfma_f32_16x16x32_bf16 v[76:79], v[144:147], v[216:219], v[76:79]
	v_mfma_f32_16x16x32_bf16 v[72:75], v[152:155], v[216:219], v[72:75]
	v_mfma_f32_16x16x32_bf16 v[124:127], v[148:151], v[196:199], v[124:127]
	v_mfma_f32_16x16x32_bf16 v[120:123], v[166:169], v[196:199], v[120:123]
	v_mfma_f32_16x16x32_bf16 v[116:119], v[148:151], v[204:207], v[116:119]
	v_mfma_f32_16x16x32_bf16 v[104:107], v[166:169], v[204:207], v[104:107]
	v_mfma_f32_16x16x32_bf16 v[92:95], v[148:151], v[212:215], v[92:95]
	v_mfma_f32_16x16x32_bf16 v[88:91], v[166:169], v[212:215], v[88:91]
	v_mfma_f32_16x16x32_bf16 v[76:79], v[148:151], v[220:223], v[76:79]
	v_mfma_f32_16x16x32_bf16 v[72:75], v[166:169], v[220:223], v[72:75]
	v_mfma_f32_16x16x32_bf16 v[112:115], v[170:173], v[192:195], v[112:115]
	v_mfma_f32_16x16x32_bf16 v[108:111], v[178:181], v[192:195], v[108:111]
	v_mfma_f32_16x16x32_bf16 v[100:103], v[170:173], v[200:203], v[100:103]
	v_mfma_f32_16x16x32_bf16 v[96:99], v[178:181], v[200:203], v[96:99]
	v_mfma_f32_16x16x32_bf16 v[84:87], v[170:173], v[208:211], v[84:87]
	v_mfma_f32_16x16x32_bf16 v[80:83], v[178:181], v[208:211], v[80:83]
	v_mfma_f32_16x16x32_bf16 v[68:71], v[170:173], v[216:219], v[68:71]
	v_mfma_f32_16x16x32_bf16 v[64:67], v[178:181], v[216:219], v[64:67]
	v_mfma_f32_16x16x32_bf16 v[112:115], v[174:177], v[196:199], v[112:115]
	v_mfma_f32_16x16x32_bf16 v[108:111], v[188:191], v[196:199], v[108:111]
	v_mfma_f32_16x16x32_bf16 v[100:103], v[174:177], v[204:207], v[100:103]
	v_mfma_f32_16x16x32_bf16 v[96:99], v[188:191], v[204:207], v[96:99]
	v_mfma_f32_16x16x32_bf16 v[84:87], v[174:177], v[212:215], v[84:87]
	v_mfma_f32_16x16x32_bf16 v[80:83], v[188:191], v[212:215], v[80:83]
	v_mfma_f32_16x16x32_bf16 v[68:71], v[174:177], v[220:223], v[68:71]
	v_mfma_f32_16x16x32_bf16 v[64:67], v[188:191], v[220:223], v[64:67]
	s_barrier
	s_add_i32 s46, s39, s28
	v_lshl_add_u64 v[224:225], s[22:23], 0, v[132:133]
	s_mov_b32 m0, s46
	ds_read_b128 v[192:195], v163 offset:16384
	ds_read_b128 v[196:199], v163 offset:17408
	ds_read_b128 v[200:203], v163 offset:18432
	ds_read_b128 v[204:207], v163 offset:19456
	ds_read_b128 v[208:211], v163 offset:20480
	ds_read_b128 v[212:215], v163 offset:21504
	ds_read_b128 v[216:219], v163 offset:22528
	ds_read_b128 v[220:223], v163 offset:23552
	global_load_lds_dwordx4 v[224:225], off
	s_add_i32 m0, s46, 0x2000
	s_add_u32 s46, s22, 0x40000
	v_lshl_add_u64 v[226:227], s[22:23], 0, v[128:129]
	s_addc_u32 s47, s23, 0
	s_add_i32 s48, s40, s28
	global_load_lds_dwordx4 v[226:227], off
	v_lshl_add_u64 v[228:229], s[46:47], 0, v[132:133]
	s_mov_b32 m0, s48
	v_lshl_add_u64 v[230:231], s[24:25], 0, v[130:131]
	global_load_lds_dwordx4 v[228:229], off
	v_lshl_add_u64 v[228:229], s[46:47], 0, v[128:129]
	s_add_i32 m0, s48, 0x2000
	s_nop 0
	global_load_lds_dwordx4 v[228:229], off
	v_lshl_add_u64 v[228:229], s[24:25], 0, v[134:135]
	s_mov_b32 m0, s21
	s_nop 0
	global_load_lds_dwordx4 v[228:229], off
	s_mov_b32 m0, s31
	s_nop 0
	global_load_lds_dwordx4 v[230:231], off
	s_waitcnt vmcnt(8)
	s_waitcnt lgkmcnt(0)
	s_barrier
	s_waitcnt lgkmcnt(0)
	v_mfma_f32_16x16x32_bf16 v[60:63], v[144:147], v[192:195], v[60:63]
	v_mfma_f32_16x16x32_bf16 v[56:59], v[152:155], v[192:195], v[56:59]
	v_mfma_f32_16x16x32_bf16 v[44:47], v[144:147], v[200:203], v[44:47]
	v_mfma_f32_16x16x32_bf16 v[40:43], v[152:155], v[200:203], v[40:43]
	v_mfma_f32_16x16x32_bf16 v[28:31], v[144:147], v[208:211], v[28:31]
	v_mfma_f32_16x16x32_bf16 v[24:27], v[152:155], v[208:211], v[24:27]
	v_mfma_f32_16x16x32_bf16 v[12:15], v[144:147], v[216:219], v[12:15]
	v_mfma_f32_16x16x32_bf16 v[8:11], v[152:155], v[216:219], v[8:11]
	v_mfma_f32_16x16x32_bf16 v[60:63], v[148:151], v[196:199], v[60:63]
	v_mfma_f32_16x16x32_bf16 v[56:59], v[166:169], v[196:199], v[56:59]
	v_mfma_f32_16x16x32_bf16 v[44:47], v[148:151], v[204:207], v[44:47]
	v_mfma_f32_16x16x32_bf16 v[40:43], v[166:169], v[204:207], v[40:43]
	v_mfma_f32_16x16x32_bf16 v[28:31], v[148:151], v[212:215], v[28:31]
	v_mfma_f32_16x16x32_bf16 v[24:27], v[166:169], v[212:215], v[24:27]
	v_mfma_f32_16x16x32_bf16 v[12:15], v[148:151], v[220:223], v[12:15]
	v_mfma_f32_16x16x32_bf16 v[8:11], v[166:169], v[220:223], v[8:11]
	v_mfma_f32_16x16x32_bf16 v[52:55], v[170:173], v[192:195], v[52:55]
	v_mfma_f32_16x16x32_bf16 v[48:51], v[178:181], v[192:195], v[48:51]
	v_mfma_f32_16x16x32_bf16 v[36:39], v[170:173], v[200:203], v[36:39]
	v_mfma_f32_16x16x32_bf16 v[32:35], v[178:181], v[200:203], v[32:35]
	v_mfma_f32_16x16x32_bf16 v[20:23], v[170:173], v[208:211], v[20:23]
	v_mfma_f32_16x16x32_bf16 v[16:19], v[178:181], v[208:211], v[16:19]
	v_mfma_f32_16x16x32_bf16 v[4:7], v[170:173], v[216:219], v[4:7]
	v_mfma_f32_16x16x32_bf16 v[0:3], v[178:181], v[216:219], v[0:3]
	v_mfma_f32_16x16x32_bf16 v[52:55], v[174:177], v[196:199], v[52:55]
	v_mfma_f32_16x16x32_bf16 v[48:51], v[188:191], v[196:199], v[48:51]
	v_mfma_f32_16x16x32_bf16 v[36:39], v[174:177], v[204:207], v[36:39]
	v_mfma_f32_16x16x32_bf16 v[32:35], v[188:191], v[204:207], v[32:35]
	v_mfma_f32_16x16x32_bf16 v[20:23], v[174:177], v[212:215], v[20:23]
	v_mfma_f32_16x16x32_bf16 v[16:19], v[188:191], v[212:215], v[16:19]
	v_mfma_f32_16x16x32_bf16 v[4:7], v[174:177], v[220:223], v[4:7]
	v_mfma_f32_16x16x32_bf16 v[0:3], v[188:191], v[220:223], v[0:3]
	s_barrier
	s_add_i32 s46, 0, 0x18000
	v_add_u32_e32 v165, s46, v157
	s_add_i32 s47, 0, 0x1c000
	ds_read_b128 v[144:147], v165
	ds_read_b128 v[148:151], v165 offset:1024
	ds_read_b128 v[152:155], v165 offset:2048
	ds_read_b128 v[166:169], v165 offset:3072
	v_add_u32_e32 v165, s47, v157
	ds_read_b128 v[170:173], v165
	ds_read_b128 v[174:177], v165 offset:1024
	ds_read_b128 v[178:181], v165 offset:2048
	ds_read_b128 v[188:191], v165 offset:3072
	s_add_u32 s24, s24, 0x40000
	s_addc_u32 s25, s25, 0
	s_mov_b32 m0, s34
	v_lshl_add_u64 v[232:233], s[24:25], 0, v[134:135]
	ds_read_b128 v[192:195], v163 offset:32768
	ds_read_b128 v[196:199], v163 offset:33792
	ds_read_b128 v[200:203], v163 offset:34816
	ds_read_b128 v[204:207], v163 offset:35840
	ds_read_b128 v[208:211], v163 offset:36864
	ds_read_b128 v[212:215], v163 offset:37888
	ds_read_b128 v[216:219], v163 offset:38912
	ds_read_b128 v[220:223], v163 offset:39936
	global_load_lds_dwordx4 v[232:233], off
	v_lshl_add_u64 v[232:233], s[24:25], 0, v[130:131]
	s_mov_b32 m0, s35
	s_nop 0
	global_load_lds_dwordx4 v[232:233], off
	s_waitcnt vmcnt(8)
	s_waitcnt lgkmcnt(0)
	s_barrier
	s_waitcnt lgkmcnt(0)
	v_mfma_f32_16x16x32_bf16 v[124:127], v[144:147], v[192:195], v[124:127]
	v_mfma_f32_16x16x32_bf16 v[120:123], v[152:155], v[192:195], v[120:123]
	v_mfma_f32_16x16x32_bf16 v[116:119], v[144:147], v[200:203], v[116:119]
	v_mfma_f32_16x16x32_bf16 v[104:107], v[152:155], v[200:203], v[104:107]
	v_mfma_f32_16x16x32_bf16 v[92:95], v[144:147], v[208:211], v[92:95]
	v_mfma_f32_16x16x32_bf16 v[88:91], v[152:155], v[208:211], v[88:91]
	v_mfma_f32_16x16x32_bf16 v[76:79], v[144:147], v[216:219], v[76:79]
	v_mfma_f32_16x16x32_bf16 v[72:75], v[152:155], v[216:219], v[72:75]
	v_mfma_f32_16x16x32_bf16 v[124:127], v[148:151], v[196:199], v[124:127]
	v_mfma_f32_16x16x32_bf16 v[120:123], v[166:169], v[196:199], v[120:123]
	v_mfma_f32_16x16x32_bf16 v[116:119], v[148:151], v[204:207], v[116:119]
	v_mfma_f32_16x16x32_bf16 v[104:107], v[166:169], v[204:207], v[104:107]
	v_mfma_f32_16x16x32_bf16 v[92:95], v[148:151], v[212:215], v[92:95]
	v_mfma_f32_16x16x32_bf16 v[88:91], v[166:169], v[212:215], v[88:91]
	v_mfma_f32_16x16x32_bf16 v[76:79], v[148:151], v[220:223], v[76:79]
	v_mfma_f32_16x16x32_bf16 v[72:75], v[166:169], v[220:223], v[72:75]
	v_mfma_f32_16x16x32_bf16 v[112:115], v[170:173], v[192:195], v[112:115]
	v_mfma_f32_16x16x32_bf16 v[108:111], v[178:181], v[192:195], v[108:111]
	v_mfma_f32_16x16x32_bf16 v[100:103], v[170:173], v[200:203], v[100:103]
	v_mfma_f32_16x16x32_bf16 v[96:99], v[178:181], v[200:203], v[96:99]
	v_mfma_f32_16x16x32_bf16 v[84:87], v[170:173], v[208:211], v[84:87]
	v_mfma_f32_16x16x32_bf16 v[80:83], v[178:181], v[208:211], v[80:83]
	v_mfma_f32_16x16x32_bf16 v[68:71], v[170:173], v[216:219], v[68:71]
	v_mfma_f32_16x16x32_bf16 v[64:67], v[178:181], v[216:219], v[64:67]
	v_mfma_f32_16x16x32_bf16 v[112:115], v[174:177], v[196:199], v[112:115]
	v_mfma_f32_16x16x32_bf16 v[108:111], v[188:191], v[196:199], v[108:111]
	v_mfma_f32_16x16x32_bf16 v[100:103], v[174:177], v[204:207], v[100:103]
	v_mfma_f32_16x16x32_bf16 v[96:99], v[188:191], v[204:207], v[96:99]
	v_mfma_f32_16x16x32_bf16 v[84:87], v[174:177], v[212:215], v[84:87]
	v_mfma_f32_16x16x32_bf16 v[80:83], v[188:191], v[212:215], v[80:83]
	v_mfma_f32_16x16x32_bf16 v[68:71], v[174:177], v[220:223], v[68:71]
	v_mfma_f32_16x16x32_bf16 v[64:67], v[188:191], v[220:223], v[64:67]
	s_barrier
	s_add_i32 s24, s46, s28
	v_lshl_add_u64 v[224:225], v[224:225], 0, s[6:7]
	s_mov_b32 m0, s24
	ds_read_b128 v[192:195], v163 offset:49152
	ds_read_b128 v[196:199], v163 offset:50176
	ds_read_b128 v[200:203], v163 offset:51200
	ds_read_b128 v[204:207], v163 offset:52224
	ds_read_b128 v[208:211], v163 offset:53248
	ds_read_b128 v[212:215], v163 offset:54272
	ds_read_b128 v[216:219], v163 offset:55296
	ds_read_b128 v[220:223], v163 offset:56320
	global_load_lds_dwordx4 v[224:225], off
	s_add_i32 m0, s24, 0x2000
	s_add_u32 s22, s22, 0x40080
	v_lshl_add_u64 v[224:225], v[226:227], 0, s[6:7]
	s_addc_u32 s23, s23, 0
	s_add_i32 s24, s47, s28
	global_load_lds_dwordx4 v[224:225], off
	v_lshl_add_u64 v[224:225], s[22:23], 0, v[132:133]
	s_mov_b32 m0, s24
	s_nop 0
	global_load_lds_dwordx4 v[224:225], off
	v_lshl_add_u64 v[224:225], s[22:23], 0, v[128:129]
	s_add_i32 m0, s24, 0x2000
	s_nop 0
	global_load_lds_dwordx4 v[224:225], off
	v_lshl_add_u64 v[224:225], v[228:229], 0, s[6:7]
	s_mov_b32 m0, s37
	s_nop 0
	global_load_lds_dwordx4 v[224:225], off
	v_lshl_add_u64 v[224:225], v[230:231], 0, s[6:7]
	s_mov_b32 m0, s38
	s_nop 0
	global_load_lds_dwordx4 v[224:225], off
	s_waitcnt vmcnt(8)
	s_waitcnt lgkmcnt(0)
	s_barrier
	s_waitcnt lgkmcnt(0)
	v_mfma_f32_16x16x32_bf16 v[60:63], v[144:147], v[192:195], v[60:63]
	v_mfma_f32_16x16x32_bf16 v[56:59], v[152:155], v[192:195], v[56:59]
	v_mfma_f32_16x16x32_bf16 v[44:47], v[144:147], v[200:203], v[44:47]
	v_mfma_f32_16x16x32_bf16 v[40:43], v[152:155], v[200:203], v[40:43]
	v_mfma_f32_16x16x32_bf16 v[28:31], v[144:147], v[208:211], v[28:31]
	v_mfma_f32_16x16x32_bf16 v[24:27], v[152:155], v[208:211], v[24:27]
	v_mfma_f32_16x16x32_bf16 v[12:15], v[144:147], v[216:219], v[12:15]
	v_mfma_f32_16x16x32_bf16 v[8:11], v[152:155], v[216:219], v[8:11]
	v_mfma_f32_16x16x32_bf16 v[60:63], v[148:151], v[196:199], v[60:63]
	v_mfma_f32_16x16x32_bf16 v[56:59], v[166:169], v[196:199], v[56:59]
	v_mfma_f32_16x16x32_bf16 v[44:47], v[148:151], v[204:207], v[44:47]
	v_mfma_f32_16x16x32_bf16 v[40:43], v[166:169], v[204:207], v[40:43]
	v_mfma_f32_16x16x32_bf16 v[28:31], v[148:151], v[212:215], v[28:31]
	v_mfma_f32_16x16x32_bf16 v[24:27], v[166:169], v[212:215], v[24:27]
	v_mfma_f32_16x16x32_bf16 v[12:15], v[148:151], v[220:223], v[12:15]
	v_mfma_f32_16x16x32_bf16 v[8:11], v[166:169], v[220:223], v[8:11]
	v_mfma_f32_16x16x32_bf16 v[52:55], v[170:173], v[192:195], v[52:55]
	v_mfma_f32_16x16x32_bf16 v[48:51], v[178:181], v[192:195], v[48:51]
	v_mfma_f32_16x16x32_bf16 v[36:39], v[170:173], v[200:203], v[36:39]
	v_mfma_f32_16x16x32_bf16 v[32:35], v[178:181], v[200:203], v[32:35]
	v_mfma_f32_16x16x32_bf16 v[20:23], v[170:173], v[208:211], v[20:23]
	v_mfma_f32_16x16x32_bf16 v[16:19], v[178:181], v[208:211], v[16:19]
	v_mfma_f32_16x16x32_bf16 v[4:7], v[170:173], v[216:219], v[4:7]
	v_mfma_f32_16x16x32_bf16 v[0:3], v[178:181], v[216:219], v[0:3]
	v_mfma_f32_16x16x32_bf16 v[52:55], v[174:177], v[196:199], v[52:55]
	v_mfma_f32_16x16x32_bf16 v[48:51], v[188:191], v[196:199], v[48:51]
	v_mfma_f32_16x16x32_bf16 v[36:39], v[174:177], v[204:207], v[36:39]
	v_mfma_f32_16x16x32_bf16 v[32:35], v[188:191], v[204:207], v[32:35]
	v_mfma_f32_16x16x32_bf16 v[20:23], v[174:177], v[212:215], v[20:23]
	v_mfma_f32_16x16x32_bf16 v[16:19], v[188:191], v[212:215], v[16:19]
	v_mfma_f32_16x16x32_bf16 v[4:7], v[174:177], v[220:223], v[4:7]
	v_mfma_f32_16x16x32_bf16 v[0:3], v[188:191], v[220:223], v[0:3]
	s_barrier
	s_add_i32 s45, s45, 2
	s_add_u32 s0, s0, 0x100
	s_addc_u32 s1, s1, 0
	s_add_u32 s43, s43, 0x100
	s_addc_u32 s44, s44, 0
	s_cmp_gt_u32 s45, 13
	s_cbranch_scc0 .LBB0_1488

.LBB0_1562:
	s_ashr_i32 s17, s16, 31
	s_lshl_b64 s[18:19], s[16:17], 21
	s_add_u32 s18, s68, s18
	s_addc_u32 s19, s69, s19
	s_and_b64 s[20:21], s[4:5], exec
	s_cselect_b32 s17, s19, s1
	s_cselect_b32 s33, s18, s0
	s_ashr_i32 s15, s14, 31
	s_lshl_b64 s[20:21], s[14:15], 21
	s_add_u32 s20, s30, s20
	s_addc_u32 s21, s31, s21
	s_and_b64 s[28:29], s[4:5], exec
	s_cselect_b32 s15, s21, s27
	s_cselect_b32 s49, s20, s26
	s_add_u32 s0, s0, 0x100080
	s_addc_u32 s1, s1, 0
	s_add_u32 s50, s26, 0x100
	s_addc_u32 s51, s27, 0
	s_mov_b32 s52, -2
	s_waitcnt lgkmcnt(0)
	ds_read_b128 v[128:131], v193
	ds_read_b128 v[132:135], v193 offset:1024
	ds_read_b128 v[136:139], v193 offset:2048
	ds_read_b128 v[140:143], v193 offset:3072
	ds_read_b128 v[144:147], v194
	ds_read_b128 v[148:151], v194 offset:1024
	ds_read_b128 v[152:155], v194 offset:2048
	ds_read_b128 v[156:159], v194 offset:3072
	s_add_u32 s26, s0, 0xfff00080
	s_addc_u32 s27, s1, -1
	s_cmp_eq_u32 s52, 60
	s_cselect_b32 s29, s17, s27
	s_cselect_b32 s28, s33, s26
	s_cselect_b32 s27, s15, s51
	s_cselect_b32 s26, s49, s50
	v_lshl_add_u64 v[224:225], s[0:1], 0, v[170:171]
	s_add_i32 m0, s23, 0xc000
	ds_read_b128 v[178:181], v195
	ds_read_b128 v[196:199], v195 offset:1024
	ds_read_b128 v[200:203], v195 offset:2048
	ds_read_b128 v[204:207], v195 offset:3072
	ds_read_b128 v[208:211], v195 offset:4096
	ds_read_b128 v[212:215], v195 offset:5120
	ds_read_b128 v[216:219], v195 offset:6144
	ds_read_b128 v[220:223], v195 offset:7168
	global_load_lds_dwordx4 v[224:225], off
	v_lshl_add_u64 v[224:225], s[0:1], 0, v[172:173]
	s_add_i32 m0, s23, 0xe000
	s_nop 0
	global_load_lds_dwordx4 v[224:225], off
	s_waitcnt vmcnt(8)
	s_waitcnt lgkmcnt(0)
	s_barrier
	s_waitcnt lgkmcnt(0)
	v_mfma_f32_16x16x32_bf16 v[124:127], v[128:131], v[178:181], 0
	v_mfma_f32_16x16x32_bf16 v[120:123], v[136:139], v[178:181], 0
	v_mfma_f32_16x16x32_bf16 v[108:111], v[128:131], v[200:203], 0
	v_mfma_f32_16x16x32_bf16 v[104:107], v[136:139], v[200:203], 0
	v_mfma_f32_16x16x32_bf16 v[92:95], v[128:131], v[208:211], 0
	v_mfma_f32_16x16x32_bf16 v[88:91], v[136:139], v[208:211], 0
	v_mfma_f32_16x16x32_bf16 v[76:79], v[128:131], v[216:219], 0
	v_mfma_f32_16x16x32_bf16 v[72:75], v[136:139], v[216:219], 0
	v_mfma_f32_16x16x32_bf16 v[124:127], v[132:135], v[196:199], v[124:127]
	v_mfma_f32_16x16x32_bf16 v[120:123], v[140:143], v[196:199], v[120:123]
	v_mfma_f32_16x16x32_bf16 v[108:111], v[132:135], v[204:207], v[108:111]
	v_mfma_f32_16x16x32_bf16 v[104:107], v[140:143], v[204:207], v[104:107]
	v_mfma_f32_16x16x32_bf16 v[92:95], v[132:135], v[212:215], v[92:95]
	v_mfma_f32_16x16x32_bf16 v[88:91], v[140:143], v[212:215], v[88:91]
	v_mfma_f32_16x16x32_bf16 v[76:79], v[132:135], v[220:223], v[76:79]
	v_mfma_f32_16x16x32_bf16 v[72:75], v[140:143], v[220:223], v[72:75]
	v_mfma_f32_16x16x32_bf16 v[116:119], v[144:147], v[178:181], 0
	v_mfma_f32_16x16x32_bf16 v[112:115], v[152:155], v[178:181], 0
	v_mfma_f32_16x16x32_bf16 v[100:103], v[144:147], v[200:203], 0
	v_mfma_f32_16x16x32_bf16 v[96:99], v[152:155], v[200:203], 0
	v_mfma_f32_16x16x32_bf16 v[84:87], v[144:147], v[208:211], 0
	v_mfma_f32_16x16x32_bf16 v[80:83], v[152:155], v[208:211], 0
	v_mfma_f32_16x16x32_bf16 v[68:71], v[144:147], v[216:219], 0
	v_mfma_f32_16x16x32_bf16 v[64:67], v[152:155], v[216:219], 0
	v_mfma_f32_16x16x32_bf16 v[116:119], v[148:151], v[196:199], v[116:119]
	v_mfma_f32_16x16x32_bf16 v[112:115], v[156:159], v[196:199], v[112:115]
	v_mfma_f32_16x16x32_bf16 v[100:103], v[148:151], v[204:207], v[100:103]
	v_mfma_f32_16x16x32_bf16 v[96:99], v[156:159], v[204:207], v[96:99]
	v_mfma_f32_16x16x32_bf16 v[84:87], v[148:151], v[212:215], v[84:87]
	v_mfma_f32_16x16x32_bf16 v[80:83], v[156:159], v[212:215], v[80:83]
	v_mfma_f32_16x16x32_bf16 v[68:71], v[148:151], v[220:223], v[68:71]
	v_mfma_f32_16x16x32_bf16 v[64:67], v[156:159], v[220:223], v[64:67]
	s_barrier
	s_add_i32 s53, s43, s34
	v_lshl_add_u64 v[224:225], s[26:27], 0, v[164:165]
	s_mov_b32 m0, s53
	ds_read_b128 v[178:181], v195 offset:16384
	ds_read_b128 v[196:199], v195 offset:17408
	ds_read_b128 v[200:203], v195 offset:18432
	ds_read_b128 v[204:207], v195 offset:19456
	ds_read_b128 v[208:211], v195 offset:20480
	ds_read_b128 v[212:215], v195 offset:21504
	ds_read_b128 v[216:219], v195 offset:22528
	ds_read_b128 v[220:223], v195 offset:23552
	global_load_lds_dwordx4 v[224:225], off
	s_add_i32 m0, s53, 0x2000
	s_add_u32 s54, s26, 0x100000
	v_lshl_add_u64 v[226:227], s[26:27], 0, v[168:169]
	s_addc_u32 s55, s27, 0
	s_add_i32 s53, s44, s34
	global_load_lds_dwordx4 v[226:227], off
	v_lshl_add_u64 v[228:229], s[54:55], 0, v[164:165]
	s_mov_b32 m0, s53
	v_lshl_add_u64 v[230:231], s[28:29], 0, v[166:167]
	global_load_lds_dwordx4 v[228:229], off
	v_lshl_add_u64 v[228:229], s[54:55], 0, v[168:169]
	s_add_i32 m0, s53, 0x2000
	s_nop 0
	global_load_lds_dwordx4 v[228:229], off
	v_lshl_add_u64 v[228:229], s[28:29], 0, v[162:163]
	s_mov_b32 m0, s23
	s_nop 0
	global_load_lds_dwordx4 v[228:229], off
	s_mov_b32 m0, s25
	s_nop 0
	global_load_lds_dwordx4 v[230:231], off
	s_waitcnt vmcnt(8)
	s_waitcnt lgkmcnt(0)
	s_barrier
	s_waitcnt lgkmcnt(0)
	v_mfma_f32_16x16x32_bf16 v[60:63], v[128:131], v[178:181], 0
	v_mfma_f32_16x16x32_bf16 v[56:59], v[136:139], v[178:181], 0
	v_mfma_f32_16x16x32_bf16 v[44:47], v[128:131], v[200:203], 0
	v_mfma_f32_16x16x32_bf16 v[40:43], v[136:139], v[200:203], 0
	v_mfma_f32_16x16x32_bf16 v[28:31], v[128:131], v[208:211], 0
	v_mfma_f32_16x16x32_bf16 v[24:27], v[136:139], v[208:211], 0
	v_mfma_f32_16x16x32_bf16 v[12:15], v[128:131], v[216:219], 0
	v_mfma_f32_16x16x32_bf16 v[8:11], v[136:139], v[216:219], 0
	v_mfma_f32_16x16x32_bf16 v[60:63], v[132:135], v[196:199], v[60:63]
	v_mfma_f32_16x16x32_bf16 v[56:59], v[140:143], v[196:199], v[56:59]
	v_mfma_f32_16x16x32_bf16 v[44:47], v[132:135], v[204:207], v[44:47]
	v_mfma_f32_16x16x32_bf16 v[40:43], v[140:143], v[204:207], v[40:43]
	v_mfma_f32_16x16x32_bf16 v[28:31], v[132:135], v[212:215], v[28:31]
	v_mfma_f32_16x16x32_bf16 v[24:27], v[140:143], v[212:215], v[24:27]
	v_mfma_f32_16x16x32_bf16 v[12:15], v[132:135], v[220:223], v[12:15]
	v_mfma_f32_16x16x32_bf16 v[8:11], v[140:143], v[220:223], v[8:11]
	v_mfma_f32_16x16x32_bf16 v[52:55], v[144:147], v[178:181], 0
	v_mfma_f32_16x16x32_bf16 v[48:51], v[152:155], v[178:181], 0
	v_mfma_f32_16x16x32_bf16 v[36:39], v[144:147], v[200:203], 0
	v_mfma_f32_16x16x32_bf16 v[32:35], v[152:155], v[200:203], 0
	v_mfma_f32_16x16x32_bf16 v[20:23], v[144:147], v[208:211], 0
	v_mfma_f32_16x16x32_bf16 v[16:19], v[152:155], v[208:211], 0
	v_mfma_f32_16x16x32_bf16 v[4:7], v[144:147], v[216:219], 0
	v_mfma_f32_16x16x32_bf16 v[0:3], v[152:155], v[216:219], 0
	v_mfma_f32_16x16x32_bf16 v[52:55], v[148:151], v[196:199], v[52:55]
	v_mfma_f32_16x16x32_bf16 v[48:51], v[156:159], v[196:199], v[48:51]
	v_mfma_f32_16x16x32_bf16 v[36:39], v[148:151], v[204:207], v[36:39]
	v_mfma_f32_16x16x32_bf16 v[32:35], v[156:159], v[204:207], v[32:35]
	v_mfma_f32_16x16x32_bf16 v[20:23], v[148:151], v[212:215], v[20:23]
	v_mfma_f32_16x16x32_bf16 v[16:19], v[156:159], v[212:215], v[16:19]
	v_mfma_f32_16x16x32_bf16 v[4:7], v[148:151], v[220:223], v[4:7]
	v_mfma_f32_16x16x32_bf16 v[0:3], v[156:159], v[220:223], v[0:3]
	s_barrier
	s_add_i32 s53, 0, 0x18000
	s_add_i32 s54, 0, 0x1c000
	v_add_u32_e32 v140, s53, v188
	v_add_u32_e32 v156, s54, v188
	ds_read_b128 v[128:131], v140
	ds_read_b128 v[132:135], v140 offset:1024
	ds_read_b128 v[136:139], v140 offset:2048
	ds_read_b128 v[140:143], v140 offset:3072
	ds_read_b128 v[144:147], v156
	ds_read_b128 v[148:151], v156 offset:1024
	ds_read_b128 v[152:155], v156 offset:2048
	ds_read_b128 v[156:159], v156 offset:3072
	s_add_u32 s28, s28, 0x100000
	s_addc_u32 s29, s29, 0
	s_mov_b32 m0, s35
	v_lshl_add_u64 v[232:233], s[28:29], 0, v[162:163]
	ds_read_b128 v[178:181], v195 offset:32768
	ds_read_b128 v[196:199], v195 offset:33792
	ds_read_b128 v[200:203], v195 offset:34816
	ds_read_b128 v[204:207], v195 offset:35840
	ds_read_b128 v[208:211], v195 offset:36864
	ds_read_b128 v[212:215], v195 offset:37888
	ds_read_b128 v[216:219], v195 offset:38912
	ds_read_b128 v[220:223], v195 offset:39936
	global_load_lds_dwordx4 v[232:233], off
	v_lshl_add_u64 v[232:233], s[28:29], 0, v[166:167]
	s_mov_b32 m0, s36
	s_nop 0
	global_load_lds_dwordx4 v[232:233], off
	s_waitcnt vmcnt(8)
	s_waitcnt lgkmcnt(0)
	s_barrier
	s_waitcnt lgkmcnt(0)
	v_mfma_f32_16x16x32_bf16 v[124:127], v[128:131], v[178:181], v[124:127]
	v_mfma_f32_16x16x32_bf16 v[120:123], v[136:139], v[178:181], v[120:123]
	v_mfma_f32_16x16x32_bf16 v[108:111], v[128:131], v[200:203], v[108:111]
	v_mfma_f32_16x16x32_bf16 v[104:107], v[136:139], v[200:203], v[104:107]
	v_mfma_f32_16x16x32_bf16 v[92:95], v[128:131], v[208:211], v[92:95]
	v_mfma_f32_16x16x32_bf16 v[88:91], v[136:139], v[208:211], v[88:91]
	v_mfma_f32_16x16x32_bf16 v[76:79], v[128:131], v[216:219], v[76:79]
	v_mfma_f32_16x16x32_bf16 v[72:75], v[136:139], v[216:219], v[72:75]
	v_mfma_f32_16x16x32_bf16 v[124:127], v[132:135], v[196:199], v[124:127]
	v_mfma_f32_16x16x32_bf16 v[120:123], v[140:143], v[196:199], v[120:123]
	v_mfma_f32_16x16x32_bf16 v[108:111], v[132:135], v[204:207], v[108:111]
	v_mfma_f32_16x16x32_bf16 v[104:107], v[140:143], v[204:207], v[104:107]
	v_mfma_f32_16x16x32_bf16 v[92:95], v[132:135], v[212:215], v[92:95]
	v_mfma_f32_16x16x32_bf16 v[88:91], v[140:143], v[212:215], v[88:91]
	v_mfma_f32_16x16x32_bf16 v[76:79], v[132:135], v[220:223], v[76:79]
	v_mfma_f32_16x16x32_bf16 v[72:75], v[140:143], v[220:223], v[72:75]
	v_mfma_f32_16x16x32_bf16 v[116:119], v[144:147], v[178:181], v[116:119]
	v_mfma_f32_16x16x32_bf16 v[112:115], v[152:155], v[178:181], v[112:115]
	v_mfma_f32_16x16x32_bf16 v[100:103], v[144:147], v[200:203], v[100:103]
	v_mfma_f32_16x16x32_bf16 v[96:99], v[152:155], v[200:203], v[96:99]
	v_mfma_f32_16x16x32_bf16 v[84:87], v[144:147], v[208:211], v[84:87]
	v_mfma_f32_16x16x32_bf16 v[80:83], v[152:155], v[208:211], v[80:83]
	v_mfma_f32_16x16x32_bf16 v[68:71], v[144:147], v[216:219], v[68:71]
	v_mfma_f32_16x16x32_bf16 v[64:67], v[152:155], v[216:219], v[64:67]
	v_mfma_f32_16x16x32_bf16 v[116:119], v[148:151], v[196:199], v[116:119]
	v_mfma_f32_16x16x32_bf16 v[112:115], v[156:159], v[196:199], v[112:115]
	v_mfma_f32_16x16x32_bf16 v[100:103], v[148:151], v[204:207], v[100:103]
	v_mfma_f32_16x16x32_bf16 v[96:99], v[156:159], v[204:207], v[96:99]
	v_mfma_f32_16x16x32_bf16 v[84:87], v[148:151], v[212:215], v[84:87]
	v_mfma_f32_16x16x32_bf16 v[80:83], v[156:159], v[212:215], v[80:83]
	v_mfma_f32_16x16x32_bf16 v[68:71], v[148:151], v[220:223], v[68:71]
	v_mfma_f32_16x16x32_bf16 v[64:67], v[156:159], v[220:223], v[64:67]
	s_barrier
	s_add_i32 s28, s53, s34
	v_lshl_add_u64 v[224:225], v[224:225], 0, s[10:11]
	s_mov_b32 m0, s28
	ds_read_b128 v[178:181], v195 offset:49152
	ds_read_b128 v[196:199], v195 offset:50176
	ds_read_b128 v[200:203], v195 offset:51200
	ds_read_b128 v[204:207], v195 offset:52224
	ds_read_b128 v[208:211], v195 offset:53248
	ds_read_b128 v[212:215], v195 offset:54272
	ds_read_b128 v[216:219], v195 offset:55296
	ds_read_b128 v[220:223], v195 offset:56320
	global_load_lds_dwordx4 v[224:225], off
	s_add_i32 m0, s28, 0x2000
	s_add_u32 s26, s26, 0x100080
	v_lshl_add_u64 v[224:225], v[226:227], 0, s[10:11]
	s_addc_u32 s27, s27, 0
	s_add_i32 s28, s54, s34
	global_load_lds_dwordx4 v[224:225], off
	v_lshl_add_u64 v[224:225], s[26:27], 0, v[164:165]
	s_mov_b32 m0, s28
	s_nop 0
	global_load_lds_dwordx4 v[224:225], off
	v_lshl_add_u64 v[224:225], s[26:27], 0, v[168:169]
	s_add_i32 m0, s28, 0x2000
	s_nop 0
	global_load_lds_dwordx4 v[224:225], off
	v_lshl_add_u64 v[224:225], v[228:229], 0, s[10:11]
	s_mov_b32 m0, s39
	s_nop 0
	global_load_lds_dwordx4 v[224:225], off
	v_lshl_add_u64 v[224:225], v[230:231], 0, s[10:11]
	s_mov_b32 m0, s40
	s_nop 0
	global_load_lds_dwordx4 v[224:225], off
	s_waitcnt vmcnt(8)
	s_waitcnt lgkmcnt(0)
	s_barrier
	s_waitcnt lgkmcnt(0)
	v_mfma_f32_16x16x32_bf16 v[60:63], v[128:131], v[178:181], v[60:63]
	v_mfma_f32_16x16x32_bf16 v[56:59], v[136:139], v[178:181], v[56:59]
	v_mfma_f32_16x16x32_bf16 v[44:47], v[128:131], v[200:203], v[44:47]
	v_mfma_f32_16x16x32_bf16 v[40:43], v[136:139], v[200:203], v[40:43]
	v_mfma_f32_16x16x32_bf16 v[28:31], v[128:131], v[208:211], v[28:31]
	v_mfma_f32_16x16x32_bf16 v[24:27], v[136:139], v[208:211], v[24:27]
	v_mfma_f32_16x16x32_bf16 v[12:15], v[128:131], v[216:219], v[12:15]
	v_mfma_f32_16x16x32_bf16 v[8:11], v[136:139], v[216:219], v[8:11]
	v_mfma_f32_16x16x32_bf16 v[60:63], v[132:135], v[196:199], v[60:63]
	v_mfma_f32_16x16x32_bf16 v[56:59], v[140:143], v[196:199], v[56:59]
	v_mfma_f32_16x16x32_bf16 v[44:47], v[132:135], v[204:207], v[44:47]
	v_mfma_f32_16x16x32_bf16 v[40:43], v[140:143], v[204:207], v[40:43]
	v_mfma_f32_16x16x32_bf16 v[28:31], v[132:135], v[212:215], v[28:31]
	v_mfma_f32_16x16x32_bf16 v[24:27], v[140:143], v[212:215], v[24:27]
	v_mfma_f32_16x16x32_bf16 v[12:15], v[132:135], v[220:223], v[12:15]
	v_mfma_f32_16x16x32_bf16 v[8:11], v[140:143], v[220:223], v[8:11]
	v_mfma_f32_16x16x32_bf16 v[52:55], v[144:147], v[178:181], v[52:55]
	v_mfma_f32_16x16x32_bf16 v[48:51], v[152:155], v[178:181], v[48:51]
	v_mfma_f32_16x16x32_bf16 v[36:39], v[144:147], v[200:203], v[36:39]
	v_mfma_f32_16x16x32_bf16 v[32:35], v[152:155], v[200:203], v[32:35]
	v_mfma_f32_16x16x32_bf16 v[20:23], v[144:147], v[208:211], v[20:23]
	v_mfma_f32_16x16x32_bf16 v[16:19], v[152:155], v[208:211], v[16:19]
	v_mfma_f32_16x16x32_bf16 v[4:7], v[144:147], v[216:219], v[4:7]
	v_mfma_f32_16x16x32_bf16 v[0:3], v[152:155], v[216:219], v[0:3]
	v_mfma_f32_16x16x32_bf16 v[52:55], v[148:151], v[196:199], v[52:55]
	v_mfma_f32_16x16x32_bf16 v[48:51], v[156:159], v[196:199], v[48:51]
	v_mfma_f32_16x16x32_bf16 v[36:39], v[148:151], v[204:207], v[36:39]
	v_mfma_f32_16x16x32_bf16 v[32:35], v[156:159], v[204:207], v[32:35]
	v_mfma_f32_16x16x32_bf16 v[20:23], v[148:151], v[212:215], v[20:23]
	v_mfma_f32_16x16x32_bf16 v[16:19], v[156:159], v[212:215], v[16:19]
	v_mfma_f32_16x16x32_bf16 v[4:7], v[148:151], v[220:223], v[4:7]
	v_mfma_f32_16x16x32_bf16 v[0:3], v[156:159], v[220:223], v[0:3]
	s_barrier
	s_add_i32 s52, s52, 2
	s_add_u32 s0, s0, 0x100
	s_addc_u32 s1, s1, 0
	s_add_u32 s50, s50, 0x100
	s_addc_u32 s51, s51, 0
	s_cmp_gt_u32 s52, 61
	s_cbranch_scc0 .LBB0_1563
	s_branch .Lpeel_exit_8
.LBB0_1563:
	ds_read_b128 v[128:131], v193
	ds_read_b128 v[132:135], v193 offset:1024
	ds_read_b128 v[136:139], v193 offset:2048
	ds_read_b128 v[140:143], v193 offset:3072
	ds_read_b128 v[144:147], v194
	ds_read_b128 v[148:151], v194 offset:1024
	ds_read_b128 v[152:155], v194 offset:2048
	ds_read_b128 v[156:159], v194 offset:3072
	s_add_u32 s26, s0, 0xfff00080
	s_addc_u32 s27, s1, -1
	s_cmp_eq_u32 s52, 60
	s_cselect_b32 s29, s17, s27
	s_cselect_b32 s28, s33, s26
	s_cselect_b32 s27, s15, s51
	s_cselect_b32 s26, s49, s50
	v_lshl_add_u64 v[224:225], s[0:1], 0, v[170:171]
	s_add_i32 m0, s23, 0xc000
	ds_read_b128 v[178:181], v195
	ds_read_b128 v[196:199], v195 offset:1024
	ds_read_b128 v[200:203], v195 offset:2048
	ds_read_b128 v[204:207], v195 offset:3072
	ds_read_b128 v[208:211], v195 offset:4096
	ds_read_b128 v[212:215], v195 offset:5120
	ds_read_b128 v[216:219], v195 offset:6144
	ds_read_b128 v[220:223], v195 offset:7168
	global_load_lds_dwordx4 v[224:225], off
	v_lshl_add_u64 v[224:225], s[0:1], 0, v[172:173]
	s_add_i32 m0, s23, 0xe000
	s_nop 0
	global_load_lds_dwordx4 v[224:225], off
	s_waitcnt vmcnt(8)
	s_waitcnt lgkmcnt(0)
	s_barrier
	s_waitcnt lgkmcnt(0)
	v_mfma_f32_16x16x32_bf16 v[124:127], v[128:131], v[178:181], v[124:127]
	v_mfma_f32_16x16x32_bf16 v[120:123], v[136:139], v[178:181], v[120:123]
	v_mfma_f32_16x16x32_bf16 v[108:111], v[128:131], v[200:203], v[108:111]
	v_mfma_f32_16x16x32_bf16 v[104:107], v[136:139], v[200:203], v[104:107]
	v_mfma_f32_16x16x32_bf16 v[92:95], v[128:131], v[208:211], v[92:95]
	v_mfma_f32_16x16x32_bf16 v[88:91], v[136:139], v[208:211], v[88:91]
	v_mfma_f32_16x16x32_bf16 v[76:79], v[128:131], v[216:219], v[76:79]
	v_mfma_f32_16x16x32_bf16 v[72:75], v[136:139], v[216:219], v[72:75]
	v_mfma_f32_16x16x32_bf16 v[124:127], v[132:135], v[196:199], v[124:127]
	v_mfma_f32_16x16x32_bf16 v[120:123], v[140:143], v[196:199], v[120:123]
	v_mfma_f32_16x16x32_bf16 v[108:111], v[132:135], v[204:207], v[108:111]
	v_mfma_f32_16x16x32_bf16 v[104:107], v[140:143], v[204:207], v[104:107]
	v_mfma_f32_16x16x32_bf16 v[92:95], v[132:135], v[212:215], v[92:95]
	v_mfma_f32_16x16x32_bf16 v[88:91], v[140:143], v[212:215], v[88:91]
	v_mfma_f32_16x16x32_bf16 v[76:79], v[132:135], v[220:223], v[76:79]
	v_mfma_f32_16x16x32_bf16 v[72:75], v[140:143], v[220:223], v[72:75]
	v_mfma_f32_16x16x32_bf16 v[116:119], v[144:147], v[178:181], v[116:119]
	v_mfma_f32_16x16x32_bf16 v[112:115], v[152:155], v[178:181], v[112:115]
	v_mfma_f32_16x16x32_bf16 v[100:103], v[144:147], v[200:203], v[100:103]
	v_mfma_f32_16x16x32_bf16 v[96:99], v[152:155], v[200:203], v[96:99]
	v_mfma_f32_16x16x32_bf16 v[84:87], v[144:147], v[208:211], v[84:87]
	v_mfma_f32_16x16x32_bf16 v[80:83], v[152:155], v[208:211], v[80:83]
	v_mfma_f32_16x16x32_bf16 v[68:71], v[144:147], v[216:219], v[68:71]
	v_mfma_f32_16x16x32_bf16 v[64:67], v[152:155], v[216:219], v[64:67]
	v_mfma_f32_16x16x32_bf16 v[116:119], v[148:151], v[196:199], v[116:119]
	v_mfma_f32_16x16x32_bf16 v[112:115], v[156:159], v[196:199], v[112:115]
	v_mfma_f32_16x16x32_bf16 v[100:103], v[148:151], v[204:207], v[100:103]
	v_mfma_f32_16x16x32_bf16 v[96:99], v[156:159], v[204:207], v[96:99]
	v_mfma_f32_16x16x32_bf16 v[84:87], v[148:151], v[212:215], v[84:87]
	v_mfma_f32_16x16x32_bf16 v[80:83], v[156:159], v[212:215], v[80:83]
	v_mfma_f32_16x16x32_bf16 v[68:71], v[148:151], v[220:223], v[68:71]
	v_mfma_f32_16x16x32_bf16 v[64:67], v[156:159], v[220:223], v[64:67]
	s_barrier
	s_add_i32 s53, s43, s34
	v_lshl_add_u64 v[224:225], s[26:27], 0, v[164:165]
	s_mov_b32 m0, s53
	ds_read_b128 v[178:181], v195 offset:16384
	ds_read_b128 v[196:199], v195 offset:17408
	ds_read_b128 v[200:203], v195 offset:18432
	ds_read_b128 v[204:207], v195 offset:19456
	ds_read_b128 v[208:211], v195 offset:20480
	ds_read_b128 v[212:215], v195 offset:21504
	ds_read_b128 v[216:219], v195 offset:22528
	ds_read_b128 v[220:223], v195 offset:23552
	global_load_lds_dwordx4 v[224:225], off
	s_add_i32 m0, s53, 0x2000
	s_add_u32 s54, s26, 0x100000
	v_lshl_add_u64 v[226:227], s[26:27], 0, v[168:169]
	s_addc_u32 s55, s27, 0
	s_add_i32 s53, s44, s34
	global_load_lds_dwordx4 v[226:227], off
	v_lshl_add_u64 v[228:229], s[54:55], 0, v[164:165]
	s_mov_b32 m0, s53
	v_lshl_add_u64 v[230:231], s[28:29], 0, v[166:167]
	global_load_lds_dwordx4 v[228:229], off
	v_lshl_add_u64 v[228:229], s[54:55], 0, v[168:169]
	s_add_i32 m0, s53, 0x2000
	s_nop 0
	global_load_lds_dwordx4 v[228:229], off
	v_lshl_add_u64 v[228:229], s[28:29], 0, v[162:163]
	s_mov_b32 m0, s23
	s_nop 0
	global_load_lds_dwordx4 v[228:229], off
	s_mov_b32 m0, s25
	s_nop 0
	global_load_lds_dwordx4 v[230:231], off
	s_waitcnt vmcnt(8)
	s_waitcnt lgkmcnt(0)
	s_barrier
	s_waitcnt lgkmcnt(0)
	v_mfma_f32_16x16x32_bf16 v[60:63], v[128:131], v[178:181], v[60:63]
	v_mfma_f32_16x16x32_bf16 v[56:59], v[136:139], v[178:181], v[56:59]
	v_mfma_f32_16x16x32_bf16 v[44:47], v[128:131], v[200:203], v[44:47]
	v_mfma_f32_16x16x32_bf16 v[40:43], v[136:139], v[200:203], v[40:43]
	v_mfma_f32_16x16x32_bf16 v[28:31], v[128:131], v[208:211], v[28:31]
	v_mfma_f32_16x16x32_bf16 v[24:27], v[136:139], v[208:211], v[24:27]
	v_mfma_f32_16x16x32_bf16 v[12:15], v[128:131], v[216:219], v[12:15]
	v_mfma_f32_16x16x32_bf16 v[8:11], v[136:139], v[216:219], v[8:11]
	v_mfma_f32_16x16x32_bf16 v[60:63], v[132:135], v[196:199], v[60:63]
	v_mfma_f32_16x16x32_bf16 v[56:59], v[140:143], v[196:199], v[56:59]
	v_mfma_f32_16x16x32_bf16 v[44:47], v[132:135], v[204:207], v[44:47]
	v_mfma_f32_16x16x32_bf16 v[40:43], v[140:143], v[204:207], v[40:43]
	v_mfma_f32_16x16x32_bf16 v[28:31], v[132:135], v[212:215], v[28:31]
	v_mfma_f32_16x16x32_bf16 v[24:27], v[140:143], v[212:215], v[24:27]
	v_mfma_f32_16x16x32_bf16 v[12:15], v[132:135], v[220:223], v[12:15]
	v_mfma_f32_16x16x32_bf16 v[8:11], v[140:143], v[220:223], v[8:11]
	v_mfma_f32_16x16x32_bf16 v[52:55], v[144:147], v[178:181], v[52:55]
	v_mfma_f32_16x16x32_bf16 v[48:51], v[152:155], v[178:181], v[48:51]
	v_mfma_f32_16x16x32_bf16 v[36:39], v[144:147], v[200:203], v[36:39]
	v_mfma_f32_16x16x32_bf16 v[32:35], v[152:155], v[200:203], v[32:35]
	v_mfma_f32_16x16x32_bf16 v[20:23], v[144:147], v[208:211], v[20:23]
	v_mfma_f32_16x16x32_bf16 v[16:19], v[152:155], v[208:211], v[16:19]
	v_mfma_f32_16x16x32_bf16 v[4:7], v[144:147], v[216:219], v[4:7]
	v_mfma_f32_16x16x32_bf16 v[0:3], v[152:155], v[216:219], v[0:3]
	v_mfma_f32_16x16x32_bf16 v[52:55], v[148:151], v[196:199], v[52:55]
	v_mfma_f32_16x16x32_bf16 v[48:51], v[156:159], v[196:199], v[48:51]
	v_mfma_f32_16x16x32_bf16 v[36:39], v[148:151], v[204:207], v[36:39]
	v_mfma_f32_16x16x32_bf16 v[32:35], v[156:159], v[204:207], v[32:35]
	v_mfma_f32_16x16x32_bf16 v[20:23], v[148:151], v[212:215], v[20:23]
	v_mfma_f32_16x16x32_bf16 v[16:19], v[156:159], v[212:215], v[16:19]
	v_mfma_f32_16x16x32_bf16 v[4:7], v[148:151], v[220:223], v[4:7]
	v_mfma_f32_16x16x32_bf16 v[0:3], v[156:159], v[220:223], v[0:3]
	s_barrier
	s_add_i32 s53, 0, 0x18000
	s_add_i32 s54, 0, 0x1c000
	v_add_u32_e32 v140, s53, v188
	v_add_u32_e32 v156, s54, v188
	ds_read_b128 v[128:131], v140
	ds_read_b128 v[132:135], v140 offset:1024
	ds_read_b128 v[136:139], v140 offset:2048
	ds_read_b128 v[140:143], v140 offset:3072
	ds_read_b128 v[144:147], v156
	ds_read_b128 v[148:151], v156 offset:1024
	ds_read_b128 v[152:155], v156 offset:2048
	ds_read_b128 v[156:159], v156 offset:3072
	s_add_u32 s28, s28, 0x100000
	s_addc_u32 s29, s29, 0
	s_mov_b32 m0, s35
	v_lshl_add_u64 v[232:233], s[28:29], 0, v[162:163]
	ds_read_b128 v[178:181], v195 offset:32768
	ds_read_b128 v[196:199], v195 offset:33792
	ds_read_b128 v[200:203], v195 offset:34816
	ds_read_b128 v[204:207], v195 offset:35840
	ds_read_b128 v[208:211], v195 offset:36864
	ds_read_b128 v[212:215], v195 offset:37888
	ds_read_b128 v[216:219], v195 offset:38912
	ds_read_b128 v[220:223], v195 offset:39936
	global_load_lds_dwordx4 v[232:233], off
	v_lshl_add_u64 v[232:233], s[28:29], 0, v[166:167]
	s_mov_b32 m0, s36
	s_nop 0
	global_load_lds_dwordx4 v[232:233], off
	s_waitcnt vmcnt(8)
	s_waitcnt lgkmcnt(0)
	s_barrier
	s_waitcnt lgkmcnt(0)
	v_mfma_f32_16x16x32_bf16 v[124:127], v[128:131], v[178:181], v[124:127]
	v_mfma_f32_16x16x32_bf16 v[120:123], v[136:139], v[178:181], v[120:123]
	v_mfma_f32_16x16x32_bf16 v[108:111], v[128:131], v[200:203], v[108:111]
	v_mfma_f32_16x16x32_bf16 v[104:107], v[136:139], v[200:203], v[104:107]
	v_mfma_f32_16x16x32_bf16 v[92:95], v[128:131], v[208:211], v[92:95]
	v_mfma_f32_16x16x32_bf16 v[88:91], v[136:139], v[208:211], v[88:91]
	v_mfma_f32_16x16x32_bf16 v[76:79], v[128:131], v[216:219], v[76:79]
	v_mfma_f32_16x16x32_bf16 v[72:75], v[136:139], v[216:219], v[72:75]
	v_mfma_f32_16x16x32_bf16 v[124:127], v[132:135], v[196:199], v[124:127]
	v_mfma_f32_16x16x32_bf16 v[120:123], v[140:143], v[196:199], v[120:123]
	v_mfma_f32_16x16x32_bf16 v[108:111], v[132:135], v[204:207], v[108:111]
	v_mfma_f32_16x16x32_bf16 v[104:107], v[140:143], v[204:207], v[104:107]
	v_mfma_f32_16x16x32_bf16 v[92:95], v[132:135], v[212:215], v[92:95]
	v_mfma_f32_16x16x32_bf16 v[88:91], v[140:143], v[212:215], v[88:91]
	v_mfma_f32_16x16x32_bf16 v[76:79], v[132:135], v[220:223], v[76:79]
	v_mfma_f32_16x16x32_bf16 v[72:75], v[140:143], v[220:223], v[72:75]
	v_mfma_f32_16x16x32_bf16 v[116:119], v[144:147], v[178:181], v[116:119]
	v_mfma_f32_16x16x32_bf16 v[112:115], v[152:155], v[178:181], v[112:115]
	v_mfma_f32_16x16x32_bf16 v[100:103], v[144:147], v[200:203], v[100:103]
	v_mfma_f32_16x16x32_bf16 v[96:99], v[152:155], v[200:203], v[96:99]
	v_mfma_f32_16x16x32_bf16 v[84:87], v[144:147], v[208:211], v[84:87]
	v_mfma_f32_16x16x32_bf16 v[80:83], v[152:155], v[208:211], v[80:83]
	v_mfma_f32_16x16x32_bf16 v[68:71], v[144:147], v[216:219], v[68:71]
	v_mfma_f32_16x16x32_bf16 v[64:67], v[152:155], v[216:219], v[64:67]
	v_mfma_f32_16x16x32_bf16 v[116:119], v[148:151], v[196:199], v[116:119]
	v_mfma_f32_16x16x32_bf16 v[112:115], v[156:159], v[196:199], v[112:115]
	v_mfma_f32_16x16x32_bf16 v[100:103], v[148:151], v[204:207], v[100:103]
	v_mfma_f32_16x16x32_bf16 v[96:99], v[156:159], v[204:207], v[96:99]
	v_mfma_f32_16x16x32_bf16 v[84:87], v[148:151], v[212:215], v[84:87]
	v_mfma_f32_16x16x32_bf16 v[80:83], v[156:159], v[212:215], v[80:83]
	v_mfma_f32_16x16x32_bf16 v[68:71], v[148:151], v[220:223], v[68:71]
	v_mfma_f32_16x16x32_bf16 v[64:67], v[156:159], v[220:223], v[64:67]
	s_barrier
	s_add_i32 s28, s53, s34
	v_lshl_add_u64 v[224:225], v[224:225], 0, s[10:11]
	s_mov_b32 m0, s28
	ds_read_b128 v[178:181], v195 offset:49152
	ds_read_b128 v[196:199], v195 offset:50176
	ds_read_b128 v[200:203], v195 offset:51200
	ds_read_b128 v[204:207], v195 offset:52224
	ds_read_b128 v[208:211], v195 offset:53248
	ds_read_b128 v[212:215], v195 offset:54272
	ds_read_b128 v[216:219], v195 offset:55296
	ds_read_b128 v[220:223], v195 offset:56320
	global_load_lds_dwordx4 v[224:225], off
	s_add_i32 m0, s28, 0x2000
	s_add_u32 s26, s26, 0x100080
	v_lshl_add_u64 v[224:225], v[226:227], 0, s[10:11]
	s_addc_u32 s27, s27, 0
	s_add_i32 s28, s54, s34
	global_load_lds_dwordx4 v[224:225], off
	v_lshl_add_u64 v[224:225], s[26:27], 0, v[164:165]
	s_mov_b32 m0, s28
	s_nop 0
	global_load_lds_dwordx4 v[224:225], off
	v_lshl_add_u64 v[224:225], s[26:27], 0, v[168:169]
	s_add_i32 m0, s28, 0x2000
	s_nop 0
	global_load_lds_dwordx4 v[224:225], off
	v_lshl_add_u64 v[224:225], v[228:229], 0, s[10:11]
	s_mov_b32 m0, s39
	s_nop 0
	global_load_lds_dwordx4 v[224:225], off
	v_lshl_add_u64 v[224:225], v[230:231], 0, s[10:11]
	s_mov_b32 m0, s40
	s_nop 0
	global_load_lds_dwordx4 v[224:225], off
	s_waitcnt vmcnt(8)
	s_waitcnt lgkmcnt(0)
	s_barrier
	s_waitcnt lgkmcnt(0)
	v_mfma_f32_16x16x32_bf16 v[60:63], v[128:131], v[178:181], v[60:63]
	v_mfma_f32_16x16x32_bf16 v[56:59], v[136:139], v[178:181], v[56:59]
	v_mfma_f32_16x16x32_bf16 v[44:47], v[128:131], v[200:203], v[44:47]
	v_mfma_f32_16x16x32_bf16 v[40:43], v[136:139], v[200:203], v[40:43]
	v_mfma_f32_16x16x32_bf16 v[28:31], v[128:131], v[208:211], v[28:31]
	v_mfma_f32_16x16x32_bf16 v[24:27], v[136:139], v[208:211], v[24:27]
	v_mfma_f32_16x16x32_bf16 v[12:15], v[128:131], v[216:219], v[12:15]
	v_mfma_f32_16x16x32_bf16 v[8:11], v[136:139], v[216:219], v[8:11]
	v_mfma_f32_16x16x32_bf16 v[60:63], v[132:135], v[196:199], v[60:63]
	v_mfma_f32_16x16x32_bf16 v[56:59], v[140:143], v[196:199], v[56:59]
	v_mfma_f32_16x16x32_bf16 v[44:47], v[132:135], v[204:207], v[44:47]
	v_mfma_f32_16x16x32_bf16 v[40:43], v[140:143], v[204:207], v[40:43]
	v_mfma_f32_16x16x32_bf16 v[28:31], v[132:135], v[212:215], v[28:31]
	v_mfma_f32_16x16x32_bf16 v[24:27], v[140:143], v[212:215], v[24:27]
	v_mfma_f32_16x16x32_bf16 v[12:15], v[132:135], v[220:223], v[12:15]
	v_mfma_f32_16x16x32_bf16 v[8:11], v[140:143], v[220:223], v[8:11]
	v_mfma_f32_16x16x32_bf16 v[52:55], v[144:147], v[178:181], v[52:55]
	v_mfma_f32_16x16x32_bf16 v[48:51], v[152:155], v[178:181], v[48:51]
	v_mfma_f32_16x16x32_bf16 v[36:39], v[144:147], v[200:203], v[36:39]
	v_mfma_f32_16x16x32_bf16 v[32:35], v[152:155], v[200:203], v[32:35]
	v_mfma_f32_16x16x32_bf16 v[20:23], v[144:147], v[208:211], v[20:23]
	v_mfma_f32_16x16x32_bf16 v[16:19], v[152:155], v[208:211], v[16:19]
	v_mfma_f32_16x16x32_bf16 v[4:7], v[144:147], v[216:219], v[4:7]
	v_mfma_f32_16x16x32_bf16 v[0:3], v[152:155], v[216:219], v[0:3]
	v_mfma_f32_16x16x32_bf16 v[52:55], v[148:151], v[196:199], v[52:55]
	v_mfma_f32_16x16x32_bf16 v[48:51], v[156:159], v[196:199], v[48:51]
	v_mfma_f32_16x16x32_bf16 v[36:39], v[148:151], v[204:207], v[36:39]
	v_mfma_f32_16x16x32_bf16 v[32:35], v[156:159], v[204:207], v[32:35]
	v_mfma_f32_16x16x32_bf16 v[20:23], v[148:151], v[212:215], v[20:23]
	v_mfma_f32_16x16x32_bf16 v[16:19], v[156:159], v[212:215], v[16:19]
	v_mfma_f32_16x16x32_bf16 v[4:7], v[148:151], v[220:223], v[4:7]
	v_mfma_f32_16x16x32_bf16 v[0:3], v[156:159], v[220:223], v[0:3]
	s_barrier
	s_add_i32 s52, s52, 2
	s_add_u32 s0, s0, 0x100
	s_addc_u32 s1, s1, 0
	s_add_u32 s50, s50, 0x100
	s_addc_u32 s51, s51, 0
	s_cmp_gt_u32 s52, 61
	s_cbranch_scc0 .LBB0_1563
